# GEMM main loops: dropped the per-phase s_setprio toggles (and duplicate lgkmcnt waits)
# speedup vs baseline: 1.0531x; 1.0110x over previous
; #define PG8_STAGE(bufoff, gbase, voff) do { _Pragma("unroll") for (int _i = 0; _i < 2; ++_i) \
;         __builtin_amdgcn_global_load_lds((const unsigned*)((const char*)(gbase) + (voff)[_i]), (LAS unsigned*)(lds + (bufoff) + ldsw + _i * 8192), 16, 0, 0); } while (0)
; #define PG8_LDA(dst, b, h) do { _Pragma("unroll") for (int m = 0; m < 4; ++m) _Pragma("unroll") for (int k = 0; k < 2; ++k) dst[m][k] = *(const LAS bf16x8*)(lds + PG8_SA(b, h) + aoff + m * 2048 + k * 1024); } while (0)
; #define PG8_LDB(dst, b, h) do { _Pragma("unroll") for (int n = 0; n < 2; ++n) _Pragma("unroll") for (int k = 0; k < 2; ++k) dst[n][k] = *(const LAS bf16x8*)(lds + PG8_SB(b, h) + boff + n * 2048 + k * 1024); } while (0)
; #define PG8_MMA(ai, bj, At, Bt) do { __builtin_amdgcn_s_setprio(1); _Pragma("unroll") for (int m = 0; m < 4; ++m) _Pragma("unroll") for (int n = 0; n < 2; ++n) _Pragma("unroll") for (int k = 0; k < 2; ++k) \
;         acc[ai][bj][m][n] = __builtin_amdgcn_mfma_f32_16x16x32_bf16(Bt[n][k], At[m][k], acc[ai][bj][m][n], 0, 0, 0); __builtin_amdgcn_s_setprio(0); } while (0)
; #define PG8_WAIT_L(n) asm volatile("s_waitcnt lgkmcnt(" #n ")" ::: "memory")
; #define PG8_BAR __builtin_amdgcn_s_barrier()
; #define PG8_SCHED __builtin_amdgcn_sched_barrier(0)
; template <class Epi>
; __device__ __forceinline__ void gemm_phase(LAS unsigned char* lds, const Gemm g, const StaticOrder& S, const Epi& E) {
;     ...
;         for (int t = 0; t < nt; t += 2) {
;             const bool last = (t == nt - 2);
;             const char* a1 = cA + (size_t)(t + 1) * kstep;
;             const char* a2 = last ? nA : cA + (size_t)(t + 2) * kstep; const char* b2 = last ? nB : cB + (size_t)(t + 2) * kstep;
;             const char* a3 = a2 + kstep; const char* b3 = b2 + kstep;
;             PG8_LDB(B0, 0, 0); PG8_SCHED; PG8_LDA(At, 0, 0); PG8_STAGE(PG8_SA(1, 1), a1 + hstep, voffA);
;             PG8_WAIT_L(8); PG8_BAR; PG8_WAIT_L(0); PG8_MMA(0, 0, At, B0); PG8_BAR; PG8_SCHED;
;             PG8_LDB(B1, 0, 1); PG8_STAGE(PG8_SB(0, 0), b2, voffB);
;             PG8_BAR; PG8_WAIT_L(0); PG8_MMA(0, 1, At, B1); PG8_BAR;
;             PG8_LDA(At, 0, 1); PG8_STAGE(PG8_SA(0, 0), a2, voffA);
;             PG8_BAR; PG8_WAIT_L(0); PG8_MMA(1, 0, At, B0); PG8_BAR; PG8_SCHED;
.LBB0_2079:
	s_add_u32 s0, s22, 0xfffc0080
	s_addc_u32 s1, s23, -1
	s_add_i32 s62, 0, 0x10000
	v_add_u32_e32 v142, s62, v161
	ds_read_b128 v[122:125], v142
	ds_read_b128 v[126:129], v142 offset:1024
	ds_read_b128 v[138:141], v142 offset:2048
	ds_read_b128 v[142:145], v142 offset:3072
	s_cmp_eq_u32 s61, 12
	s_cselect_b32 s27, s15, s1
	s_cselect_b32 s26, s57, s0
	s_cselect_b32 s25, s13, s60
	s_cselect_b32 s24, s58, s59
	v_lshl_add_u64 v[186:187], s[22:23], 0, v[152:153]
	s_add_i32 m0, s21, 0xc000
	ds_read_b128 v[166:169], v165
	ds_read_b128 v[170:173], v165 offset:1024
	ds_read_b128 v[174:177], v165 offset:2048
	ds_read_b128 v[190:193], v165 offset:3072
	ds_read_b128 v[194:197], v165 offset:4096
	ds_read_b128 v[198:201], v165 offset:5120
	ds_read_b128 v[202:205], v165 offset:6144
	ds_read_b128 v[206:209], v165 offset:7168
	global_load_lds_dwordx4 v[186:187], off
	v_lshl_add_u64 v[186:187], s[22:23], 0, v[154:155]
	s_add_i32 m0, s21, 0xe000
	s_nop 0
	global_load_lds_dwordx4 v[186:187], off
	s_waitcnt lgkmcnt(8)
	s_barrier
	s_waitcnt lgkmcnt(0)
	v_mfma_f32_16x16x32_bf16 v[134:137], v[122:125], v[166:169], v[134:137]
	v_mfma_f32_16x16x32_bf16 v[130:133], v[138:141], v[166:169], v[130:133]
	v_mfma_f32_16x16x32_bf16 v[118:121], v[122:125], v[174:177], v[118:121]
	v_mfma_f32_16x16x32_bf16 v[114:117], v[138:141], v[174:177], v[114:117]
	v_mfma_f32_16x16x32_bf16 v[110:113], v[122:125], v[194:197], v[110:113]
	v_mfma_f32_16x16x32_bf16 v[106:109], v[138:141], v[194:197], v[106:109]
	v_mfma_f32_16x16x32_bf16 v[102:105], v[122:125], v[202:205], v[102:105]
	v_mfma_f32_16x16x32_bf16 v[98:101], v[138:141], v[202:205], v[98:101]
	v_mfma_f32_16x16x32_bf16 v[134:137], v[126:129], v[170:173], v[134:137]
	v_mfma_f32_16x16x32_bf16 v[130:133], v[142:145], v[170:173], v[130:133]
	v_mfma_f32_16x16x32_bf16 v[118:121], v[126:129], v[190:193], v[118:121]
	v_mfma_f32_16x16x32_bf16 v[114:117], v[142:145], v[190:193], v[114:117]
	v_mfma_f32_16x16x32_bf16 v[110:113], v[126:129], v[198:201], v[110:113]
	v_mfma_f32_16x16x32_bf16 v[106:109], v[142:145], v[198:201], v[106:109]
	v_mfma_f32_16x16x32_bf16 v[102:105], v[126:129], v[206:209], v[102:105]
	v_mfma_f32_16x16x32_bf16 v[98:101], v[142:145], v[206:209], v[98:101]
	s_barrier
	s_add_i32 s0, 0, 0x14000
	s_add_i32 s1, s62, s36
	v_add_u32_e32 v158, s0, v161
	v_lshl_add_u64 v[186:187], s[24:25], 0, v[4:5]
	s_mov_b32 m0, s1
	ds_read_b128 v[210:213], v158
	ds_read_b128 v[214:217], v158 offset:1024
	ds_read_b128 v[218:221], v158 offset:2048
	ds_read_b128 v[222:225], v158 offset:3072
	global_load_lds_dwordx4 v[186:187], off
	v_lshl_add_u64 v[226:227], s[24:25], 0, v[146:147]
	s_add_i32 m0, s1, 0x2000
	s_nop 0
	global_load_lds_dwordx4 v[226:227], off
	s_barrier
	s_waitcnt lgkmcnt(0)
	v_mfma_f32_16x16x32_bf16 v[70:73], v[210:213], v[166:169], v[70:73]
	v_mfma_f32_16x16x32_bf16 v[66:69], v[218:221], v[166:169], v[66:69]
	v_mfma_f32_16x16x32_bf16 v[54:57], v[210:213], v[174:177], v[54:57]
	v_mfma_f32_16x16x32_bf16 v[50:53], v[218:221], v[174:177], v[50:53]
	v_mfma_f32_16x16x32_bf16 v[46:49], v[210:213], v[194:197], v[46:49]
	v_mfma_f32_16x16x32_bf16 v[42:45], v[218:221], v[194:197], v[42:45]
	v_mfma_f32_16x16x32_bf16 v[38:41], v[210:213], v[202:205], v[38:41]
	v_mfma_f32_16x16x32_bf16 v[34:37], v[218:221], v[202:205], v[34:37]
	v_mfma_f32_16x16x32_bf16 v[70:73], v[214:217], v[170:173], v[70:73]
	v_mfma_f32_16x16x32_bf16 v[66:69], v[222:225], v[170:173], v[66:69]
	v_mfma_f32_16x16x32_bf16 v[54:57], v[214:217], v[190:193], v[54:57]
	v_mfma_f32_16x16x32_bf16 v[50:53], v[222:225], v[190:193], v[50:53]
	v_mfma_f32_16x16x32_bf16 v[46:49], v[214:217], v[198:201], v[46:49]
	v_mfma_f32_16x16x32_bf16 v[42:45], v[222:225], v[198:201], v[42:45]
	v_mfma_f32_16x16x32_bf16 v[38:41], v[214:217], v[206:209], v[38:41]
	v_mfma_f32_16x16x32_bf16 v[34:37], v[222:225], v[206:209], v[34:37]
	s_mov_b32 m0, s21
	v_lshl_add_u64 v[242:243], s[26:27], 0, v[150:151]
	s_barrier
	ds_read_b128 v[166:169], v165 offset:16384
	ds_read_b128 v[170:173], v165 offset:17408
	ds_read_b128 v[174:177], v165 offset:18432
	ds_read_b128 v[190:193], v165 offset:19456
	ds_read_b128 v[194:197], v165 offset:20480
	ds_read_b128 v[198:201], v165 offset:21504
	ds_read_b128 v[202:205], v165 offset:22528
	ds_read_b128 v[206:209], v165 offset:23552
	global_load_lds_dwordx4 v[242:243], off
	v_lshl_add_u64 v[244:245], s[26:27], 0, v[148:149]
	s_mov_b32 m0, s42
	s_nop 0
	global_load_lds_dwordx4 v[244:245], off
	s_barrier
	s_waitcnt lgkmcnt(0)
	v_mfma_f32_16x16x32_bf16 v[94:97], v[122:125], v[166:169], v[94:97]
	v_mfma_f32_16x16x32_bf16 v[90:93], v[138:141], v[166:169], v[90:93]
	v_mfma_f32_16x16x32_bf16 v[86:89], v[122:125], v[174:177], v[86:89]
	v_mfma_f32_16x16x32_bf16 v[82:85], v[138:141], v[174:177], v[82:85]
	v_mfma_f32_16x16x32_bf16 v[78:81], v[122:125], v[194:197], v[78:81]
	v_mfma_f32_16x16x32_bf16 v[74:77], v[138:141], v[194:197], v[74:77]
	v_mfma_f32_16x16x32_bf16 v[62:65], v[122:125], v[202:205], v[62:65]
	v_mfma_f32_16x16x32_bf16 v[58:61], v[138:141], v[202:205], v[58:61]
	v_mfma_f32_16x16x32_bf16 v[94:97], v[126:129], v[170:173], v[94:97]
	v_mfma_f32_16x16x32_bf16 v[90:93], v[142:145], v[170:173], v[90:93]
	v_mfma_f32_16x16x32_bf16 v[86:89], v[126:129], v[190:193], v[86:89]
	v_mfma_f32_16x16x32_bf16 v[82:85], v[142:145], v[190:193], v[82:85]
	v_mfma_f32_16x16x32_bf16 v[78:81], v[126:129], v[198:201], v[78:81]
	v_mfma_f32_16x16x32_bf16 v[74:77], v[142:145], v[198:201], v[74:77]
	v_mfma_f32_16x16x32_bf16 v[62:65], v[126:129], v[206:209], v[62:65]
	v_mfma_f32_16x16x32_bf16 v[58:61], v[142:145], v[206:209], v[58:61]
	s_barrier
; #define PG8_STAGE(bufoff, gbase, voff) do { _Pragma("unroll") for (int _i = 0; _i < 2; ++_i) \
;         __builtin_amdgcn_global_load_lds((const unsigned*)((const char*)(gbase) + (voff)[_i]), (LAS unsigned*)(lds + (bufoff) + ldsw + _i * 8192), 16, 0, 0); } while (0)
; #define PG8_LDA(dst, b, h) do { _Pragma("unroll") for (int m = 0; m < 4; ++m) _Pragma("unroll") for (int k = 0; k < 2; ++k) dst[m][k] = *(const LAS bf16x8*)(lds + PG8_SA(b, h) + aoff + m * 2048 + k * 1024); } while (0)
; #define PG8_LDB(dst, b, h) do { _Pragma("unroll") for (int n = 0; n < 2; ++n) _Pragma("unroll") for (int k = 0; k < 2; ++k) dst[n][k] = *(const LAS bf16x8*)(lds + PG8_SB(b, h) + boff + n * 2048 + k * 1024); } while (0)
; #define PG8_MMA(ai, bj, At, Bt) do { __builtin_amdgcn_s_setprio(1); _Pragma("unroll") for (int m = 0; m < 4; ++m) _Pragma("unroll") for (int n = 0; n < 2; ++n) _Pragma("unroll") for (int k = 0; k < 2; ++k) \
;         acc[ai][bj][m][n] = __builtin_amdgcn_mfma_f32_16x16x32_bf16(Bt[n][k], At[m][k], acc[ai][bj][m][n], 0, 0, 0); __builtin_amdgcn_s_setprio(0); } while (0)
; #define PG8_WAIT_V(n) asm volatile("s_waitcnt vmcnt(" #n ")" ::: "memory")
; #define PG8_WAIT_L(n) asm volatile("s_waitcnt lgkmcnt(" #n ")" ::: "memory")
; #define PG8_BAR __builtin_amdgcn_s_barrier()
; #define PG8_SCHED __builtin_amdgcn_sched_barrier(0)
; template <class Epi>
; __device__ __forceinline__ void gemm_phase(LAS unsigned char* lds, const Gemm g, const StaticOrder& S, const Epi& E) {
;     ...
;             PG8_STAGE(PG8_SB(0, 1), b2 + hstep, voffB);
;             PG8_WAIT_V(6); PG8_BAR; PG8_MMA(1, 1, At, B1); PG8_BAR;
;             PG8_LDB(B0, 1, 0); PG8_SCHED; PG8_LDA(At, 1, 0); PG8_STAGE(PG8_SA(0, 1), a2 + hstep, voffA);
;             PG8_WAIT_L(8); PG8_BAR; PG8_WAIT_L(0); PG8_MMA(0, 0, At, B0); PG8_BAR; PG8_SCHED;
;             PG8_LDB(B1, 1, 1); PG8_STAGE(PG8_SB(1, 0), b3, voffB);
;             PG8_BAR; PG8_WAIT_L(0); PG8_MMA(0, 1, At, B1); PG8_BAR;
;             PG8_LDA(At, 1, 1); PG8_STAGE(PG8_SA(1, 0), a3, voffA);
	s_add_u32 s62, s24, 0x40000
	s_addc_u32 s63, s25, 0
	s_add_i32 s0, s0, s36
	v_lshl_add_u64 v[122:123], s[62:63], 0, v[4:5]
	s_mov_b32 m0, s0
	s_nop 0
	global_load_lds_dwordx4 v[122:123], off
	v_lshl_add_u64 v[122:123], s[62:63], 0, v[146:147]
	s_add_i32 m0, s0, 0x2000
	s_nop 0
	global_load_lds_dwordx4 v[122:123], off
	s_waitcnt vmcnt(6)
	s_barrier
	v_mfma_f32_16x16x32_bf16 v[30:33], v[210:213], v[166:169], v[30:33]
	v_mfma_f32_16x16x32_bf16 v[26:29], v[218:221], v[166:169], v[26:29]
	v_mfma_f32_16x16x32_bf16 v[22:25], v[210:213], v[174:177], v[22:25]
	v_mfma_f32_16x16x32_bf16 v[18:21], v[218:221], v[174:177], v[18:21]
	v_mfma_f32_16x16x32_bf16 v[14:17], v[210:213], v[194:197], v[14:17]
	v_mfma_f32_16x16x32_bf16 v[10:13], v[218:221], v[194:197], v[10:13]
	v_mfma_f32_16x16x32_bf16 v[6:9], v[210:213], v[202:205], v[6:9]
	v_mfma_f32_16x16x32_bf16 v[0:3], v[218:221], v[202:205], v[0:3]
	v_mfma_f32_16x16x32_bf16 v[30:33], v[214:217], v[170:173], v[30:33]
	v_mfma_f32_16x16x32_bf16 v[26:29], v[222:225], v[170:173], v[26:29]
	v_mfma_f32_16x16x32_bf16 v[22:25], v[214:217], v[190:193], v[22:25]
	v_mfma_f32_16x16x32_bf16 v[18:21], v[222:225], v[190:193], v[18:21]
	v_mfma_f32_16x16x32_bf16 v[14:17], v[214:217], v[198:201], v[14:17]
	v_mfma_f32_16x16x32_bf16 v[10:13], v[222:225], v[198:201], v[10:13]
	v_mfma_f32_16x16x32_bf16 v[6:9], v[214:217], v[206:209], v[6:9]
	v_mfma_f32_16x16x32_bf16 v[0:3], v[222:225], v[206:209], v[0:3]
	s_add_i32 s0, 0, 0x18000
	v_add_u32_e32 v142, s0, v161
	s_barrier
	ds_read_b128 v[122:125], v142
	ds_read_b128 v[126:129], v142 offset:1024
	ds_read_b128 v[138:141], v142 offset:2048
	ds_read_b128 v[142:145], v142 offset:3072
	s_add_u32 s26, s26, 0x40000
	s_addc_u32 s27, s27, 0
	s_mov_b32 m0, s43
	v_lshl_add_u64 v[210:211], s[26:27], 0, v[150:151]
	ds_read_b128 v[166:169], v165 offset:32768
	ds_read_b128 v[170:173], v165 offset:33792
	ds_read_b128 v[174:177], v165 offset:34816
	ds_read_b128 v[190:193], v165 offset:35840
	ds_read_b128 v[194:197], v165 offset:36864
	ds_read_b128 v[198:201], v165 offset:37888
	ds_read_b128 v[202:205], v165 offset:38912
	ds_read_b128 v[206:209], v165 offset:39936
	global_load_lds_dwordx4 v[210:211], off
	v_lshl_add_u64 v[210:211], s[26:27], 0, v[148:149]
	s_mov_b32 m0, s48
	s_nop 0
	global_load_lds_dwordx4 v[210:211], off
	s_waitcnt lgkmcnt(8)
	s_barrier
	s_waitcnt lgkmcnt(0)
	v_mfma_f32_16x16x32_bf16 v[134:137], v[122:125], v[166:169], v[134:137]
	v_mfma_f32_16x16x32_bf16 v[130:133], v[138:141], v[166:169], v[130:133]
	v_mfma_f32_16x16x32_bf16 v[118:121], v[122:125], v[174:177], v[118:121]
	v_mfma_f32_16x16x32_bf16 v[114:117], v[138:141], v[174:177], v[114:117]
	v_mfma_f32_16x16x32_bf16 v[110:113], v[122:125], v[194:197], v[110:113]
	v_mfma_f32_16x16x32_bf16 v[106:109], v[138:141], v[194:197], v[106:109]
	v_mfma_f32_16x16x32_bf16 v[102:105], v[122:125], v[202:205], v[102:105]
	v_mfma_f32_16x16x32_bf16 v[98:101], v[138:141], v[202:205], v[98:101]
	v_mfma_f32_16x16x32_bf16 v[134:137], v[126:129], v[170:173], v[134:137]
	v_mfma_f32_16x16x32_bf16 v[130:133], v[142:145], v[170:173], v[130:133]
	v_mfma_f32_16x16x32_bf16 v[118:121], v[126:129], v[190:193], v[118:121]
	v_mfma_f32_16x16x32_bf16 v[114:117], v[142:145], v[190:193], v[114:117]
	v_mfma_f32_16x16x32_bf16 v[110:113], v[126:129], v[198:201], v[110:113]
	v_mfma_f32_16x16x32_bf16 v[106:109], v[142:145], v[198:201], v[106:109]
	v_mfma_f32_16x16x32_bf16 v[102:105], v[126:129], v[206:209], v[102:105]
	v_mfma_f32_16x16x32_bf16 v[98:101], v[142:145], v[206:209], v[98:101]
	s_barrier
	s_add_i32 s1, 0, 0x1c000
	s_add_i32 s0, s0, s36
	v_add_u32_e32 v158, s1, v161
	v_lshl_add_u64 v[186:187], v[186:187], 0, s[86:87]
	s_mov_b32 m0, s0
	ds_read_b128 v[210:213], v158
	ds_read_b128 v[214:217], v158 offset:1024
	ds_read_b128 v[218:221], v158 offset:2048
	ds_read_b128 v[222:225], v158 offset:3072
	global_load_lds_dwordx4 v[186:187], off
	v_lshl_add_u64 v[186:187], v[226:227], 0, s[86:87]
	s_add_i32 m0, s0, 0x2000
	s_nop 0
	global_load_lds_dwordx4 v[186:187], off
	s_barrier
	s_waitcnt lgkmcnt(0)
	v_mfma_f32_16x16x32_bf16 v[70:73], v[210:213], v[166:169], v[70:73]
	v_mfma_f32_16x16x32_bf16 v[66:69], v[218:221], v[166:169], v[66:69]
	v_mfma_f32_16x16x32_bf16 v[54:57], v[210:213], v[174:177], v[54:57]
	v_mfma_f32_16x16x32_bf16 v[50:53], v[218:221], v[174:177], v[50:53]
	v_mfma_f32_16x16x32_bf16 v[46:49], v[210:213], v[194:197], v[46:49]
	v_mfma_f32_16x16x32_bf16 v[42:45], v[218:221], v[194:197], v[42:45]
	v_mfma_f32_16x16x32_bf16 v[38:41], v[210:213], v[202:205], v[38:41]
	v_mfma_f32_16x16x32_bf16 v[34:37], v[218:221], v[202:205], v[34:37]
	v_mfma_f32_16x16x32_bf16 v[70:73], v[214:217], v[170:173], v[70:73]
	v_mfma_f32_16x16x32_bf16 v[66:69], v[222:225], v[170:173], v[66:69]
	v_mfma_f32_16x16x32_bf16 v[54:57], v[214:217], v[190:193], v[54:57]
	v_mfma_f32_16x16x32_bf16 v[50:53], v[222:225], v[190:193], v[50:53]
	v_mfma_f32_16x16x32_bf16 v[46:49], v[214:217], v[198:201], v[46:49]
	v_mfma_f32_16x16x32_bf16 v[42:45], v[222:225], v[198:201], v[42:45]
	v_mfma_f32_16x16x32_bf16 v[38:41], v[214:217], v[206:209], v[38:41]
	v_mfma_f32_16x16x32_bf16 v[34:37], v[222:225], v[206:209], v[34:37]
	s_mov_b32 m0, s51
	v_lshl_add_u64 v[186:187], v[242:243], 0, s[86:87]
	s_barrier
	ds_read_b128 v[166:169], v165 offset:49152
	ds_read_b128 v[170:173], v165 offset:50176
	ds_read_b128 v[174:177], v165 offset:51200
	ds_read_b128 v[190:193], v165 offset:52224
	ds_read_b128 v[194:197], v165 offset:53248
	ds_read_b128 v[198:201], v165 offset:54272
	ds_read_b128 v[202:205], v165 offset:55296
	ds_read_b128 v[206:209], v165 offset:56320
	global_load_lds_dwordx4 v[186:187], off
	v_lshl_add_u64 v[186:187], v[244:245], 0, s[86:87]
	s_mov_b32 m0, s54
	s_nop 0
	global_load_lds_dwordx4 v[186:187], off
	s_barrier
; #define PG8_STAGE(bufoff, gbase, voff) do { _Pragma("unroll") for (int _i = 0; _i < 2; ++_i) \
;         __builtin_amdgcn_global_load_lds((const unsigned*)((const char*)(gbase) + (voff)[_i]), (LAS unsigned*)(lds + (bufoff) + ldsw + _i * 8192), 16, 0, 0); } while (0)
; #define PG8_MMA(ai, bj, At, Bt) do { __builtin_amdgcn_s_setprio(1); _Pragma("unroll") for (int m = 0; m < 4; ++m) _Pragma("unroll") for (int n = 0; n < 2; ++n) _Pragma("unroll") for (int k = 0; k < 2; ++k) \
;         acc[ai][bj][m][n] = __builtin_amdgcn_mfma_f32_16x16x32_bf16(Bt[n][k], At[m][k], acc[ai][bj][m][n], 0, 0, 0); __builtin_amdgcn_s_setprio(0); } while (0)
; #define PG8_WAIT_V(n) asm volatile("s_waitcnt vmcnt(" #n ")" ::: "memory")
; #define PG8_WAIT_L(n) asm volatile("s_waitcnt lgkmcnt(" #n ")" ::: "memory")
; #define PG8_BAR __builtin_amdgcn_s_barrier()
; #define PG8_SCHED __builtin_amdgcn_sched_barrier(0)
; template <class Epi>
; __device__ __forceinline__ void gemm_phase(LAS unsigned char* lds, const Gemm g, const StaticOrder& S, const Epi& E) {
;     ...
;             PG8_BAR; PG8_WAIT_L(0); PG8_MMA(1, 0, At, B0); PG8_BAR; PG8_SCHED;
;             PG8_STAGE(PG8_SB(1, 1), b3 + hstep, voffB);
;             PG8_WAIT_V(6); PG8_BAR; PG8_MMA(1, 1, At, B1); PG8_BAR;
;         }
;         E(acc, cur, wr, wc, fr, fq);
;     __device__ __forceinline__ void operator()(const f32x4 (&acc)[2][2][4][2], const Unit& u, int wr, int wc, int fr, int fq) const {
;         const int row0 = u.pm * 256 + wr * 64 + fr, col0 = u.pn * 256 + wc * 32 + 8 * fq;
;         f32x4 ra = (f32x4){1.f, 1.f, 1.f, 1.f}, rb = ra;
;         f32x4 swv[4] = {(f32x4){0.f, 0.f, 0.f, 0.f}, (f32x4){0.f, 0.f, 0.f, 0.f}, (f32x4){0.f, 0.f, 0.f, 0.f}, (f32x4){0.f, 0.f, 0.f, 0.f}};
;         if (ss) { load_rstd(ss, row0, ra, rb); const float* swp = sw + (size_t)(u.pm >> 3) * ldc + col0;
;             swv[0] = *(const f32x4*)(swp); swv[1] = *(const f32x4*)(swp + 4); swv[2] = *(const f32x4*)(swp + 128); swv[3] = *(const f32x4*)(swp + 132); }
	s_waitcnt lgkmcnt(0)
	v_mfma_f32_16x16x32_bf16 v[94:97], v[122:125], v[166:169], v[94:97]
	v_mfma_f32_16x16x32_bf16 v[90:93], v[138:141], v[166:169], v[90:93]
	v_mfma_f32_16x16x32_bf16 v[86:89], v[122:125], v[174:177], v[86:89]
	v_mfma_f32_16x16x32_bf16 v[82:85], v[138:141], v[174:177], v[82:85]
	v_mfma_f32_16x16x32_bf16 v[78:81], v[122:125], v[194:197], v[78:81]
	v_mfma_f32_16x16x32_bf16 v[74:77], v[138:141], v[194:197], v[74:77]
	v_mfma_f32_16x16x32_bf16 v[62:65], v[122:125], v[202:205], v[62:65]
	v_mfma_f32_16x16x32_bf16 v[58:61], v[138:141], v[202:205], v[58:61]
	v_mfma_f32_16x16x32_bf16 v[94:97], v[126:129], v[170:173], v[94:97]
	v_mfma_f32_16x16x32_bf16 v[90:93], v[142:145], v[170:173], v[90:93]
	v_mfma_f32_16x16x32_bf16 v[86:89], v[126:129], v[190:193], v[86:89]
	v_mfma_f32_16x16x32_bf16 v[82:85], v[142:145], v[190:193], v[82:85]
	v_mfma_f32_16x16x32_bf16 v[78:81], v[126:129], v[198:201], v[78:81]
	v_mfma_f32_16x16x32_bf16 v[74:77], v[142:145], v[198:201], v[74:77]
	v_mfma_f32_16x16x32_bf16 v[62:65], v[126:129], v[206:209], v[62:65]
	v_mfma_f32_16x16x32_bf16 v[58:61], v[142:145], v[206:209], v[58:61]
	s_barrier
	s_add_u32 s24, s24, 0x40080
	s_addc_u32 s25, s25, 0
	s_add_i32 s0, s1, s36
	v_lshl_add_u64 v[122:123], s[24:25], 0, v[4:5]
	s_mov_b32 m0, s0
	s_nop 0
	global_load_lds_dwordx4 v[122:123], off
	v_lshl_add_u64 v[122:123], s[24:25], 0, v[146:147]
	s_add_i32 m0, s0, 0x2000
	s_nop 0
	global_load_lds_dwordx4 v[122:123], off
	s_waitcnt vmcnt(6)
	s_barrier
	v_mfma_f32_16x16x32_bf16 v[30:33], v[210:213], v[166:169], v[30:33]
	v_mfma_f32_16x16x32_bf16 v[26:29], v[218:221], v[166:169], v[26:29]
	v_mfma_f32_16x16x32_bf16 v[22:25], v[210:213], v[174:177], v[22:25]
	v_mfma_f32_16x16x32_bf16 v[18:21], v[218:221], v[174:177], v[18:21]
	v_mfma_f32_16x16x32_bf16 v[14:17], v[210:213], v[194:197], v[14:17]
	v_mfma_f32_16x16x32_bf16 v[10:13], v[218:221], v[194:197], v[10:13]
	v_mfma_f32_16x16x32_bf16 v[6:9], v[210:213], v[202:205], v[6:9]
	v_mfma_f32_16x16x32_bf16 v[0:3], v[218:221], v[202:205], v[0:3]
	v_mfma_f32_16x16x32_bf16 v[30:33], v[214:217], v[170:173], v[30:33]
	v_mfma_f32_16x16x32_bf16 v[26:29], v[222:225], v[170:173], v[26:29]
	v_mfma_f32_16x16x32_bf16 v[22:25], v[214:217], v[190:193], v[22:25]
	v_mfma_f32_16x16x32_bf16 v[18:21], v[222:225], v[190:193], v[18:21]
	v_mfma_f32_16x16x32_bf16 v[14:17], v[214:217], v[198:201], v[14:17]
	v_mfma_f32_16x16x32_bf16 v[10:13], v[222:225], v[198:201], v[10:13]
	v_mfma_f32_16x16x32_bf16 v[6:9], v[214:217], v[206:209], v[6:9]
	v_mfma_f32_16x16x32_bf16 v[0:3], v[222:225], v[206:209], v[0:3]
	s_add_i32 s61, s61, 2
	s_add_u32 s22, s22, 0x100
	s_addc_u32 s23, s23, 0
	s_add_u32 s59, s59, 0x100
	s_addc_u32 s60, s60, 0
	s_cmp_gt_u32 s61, 13
	s_barrier
	s_cbranch_scc0 .LBB0_2079
	v_lshl_add_u32 v174, s20, 8, v159
	v_ashrrev_i32_e32 v175, 31, v174
	v_lshl_add_u64 v[122:123], v[174:175], 2, s[10:11]
	global_load_dword v190, v[122:123], off
	global_load_dword v191, v[122:123], off offset:64
	global_load_dword v192, v[122:123], off offset:128
	global_load_dword v193, v[122:123], off offset:192
	global_load_dword v194, v[122:123], off offset:512
	global_load_dword v195, v[122:123], off offset:576
	global_load_dword v196, v[122:123], off offset:640
	global_load_dword v197, v[122:123], off offset:704
	s_ashr_i32 s0, s20, 3
	s_mul_hi_i32 s23, s0, s52
	s_mul_i32 s22, s0, s52
	s_lshl_b64 s[22:23], s[22:23], 2
	v_lshl_or_b32 v176, s56, 8, v163
	s_add_u32 s22, s49, s22
	s_addc_u32 s23, s50, s23
	v_ashrrev_i32_e32 v177, 31, v176
	v_lshl_add_u64 v[200:201], v[176:177], 2, s[22:23]
	global_load_dwordx4 v[138:141], v[200:201], off offset:16
	global_load_dwordx4 v[142:145], v[200:201], off
	global_load_dwordx4 v[122:125], v[200:201], off offset:528
	global_load_dwordx4 v[126:129], v[200:201], off offset:512
	s_and_b64 vcc, exec, s[4:5]
	s_mov_b32 s56, s12
	s_mov_b32 s20, s14
	s_mov_b64 s[24:25], s[18:19]
	s_waitcnt vmcnt(4)
	v_fmamk_f32 v202, v190, 0x3a800000, v229
	v_rsq_f32_e32 v172, v202
	v_fmamk_f32 v202, v194, 0x3a800000, v229
	v_rsq_f32_e32 v164, v202
	v_fmamk_f32 v202, v191, 0x3a800000, v229
	v_rsq_f32_e32 v170, v202
	v_fmamk_f32 v202, v195, 0x3a800000, v229
	v_rsq_f32_e32 v162, v202
	v_fmamk_f32 v202, v192, 0x3a800000, v229
	v_rsq_f32_e32 v168, v202
	v_fmamk_f32 v202, v196, 0x3a800000, v229
	v_rsq_f32_e32 v160, v202
	v_fmamk_f32 v202, v193, 0x3a800000, v229
	v_fmamk_f32 v203, v197, 0x3a800000, v229
	v_rsq_f32_e32 v166, v202
	v_rsq_f32_e32 v158, v203
	s_waitcnt vmcnt(0)
; __device__ __forceinline__ unsigned cvt_pk_bf16(float lo, float hi) { unsigned r; asm volatile("s_nop 0\n\tv_cvt_pk_bf16_f32 %0, %1, %2" : "=v"(r) : "v"(lo), "v"(hi)); return r; }
;     __device__ __forceinline__ void operator()(const f32x4 (&acc)[2][2][4][2], const Unit& u, int wr, int wc, int fr, int fq) const {
;     ...
;         for (int bj = 0; bj < 2; ++bj) {
;             const f32x4 s0 = swv[2 * bj], s1 = swv[2 * bj + 1];
; #pragma unroll
;             for (int ai = 0; ai < 2; ++ai)
; #pragma unroll
;                 for (int m = 0; m < 4; ++m) { const int r = row0 + ai * 128 + m * 16;
;                     const float rstd = ai ? rb[m] : ra[m];
;                     const f32x4 v0 = acc[ai][bj][m][0] * rstd + s0, v1 = acc[ai][bj][m][1] * rstd + s1;
;                     uint4 st; st.x = cvt_pk_bf16(v0[0], v0[1]); st.y = cvt_pk_bf16(v0[2], v0[3]); st.z = cvt_pk_bf16(v1[0], v1[1]); st.w = cvt_pk_bf16(v1[2], v1[3]);
;                     *(uint4*)(O + (size_t)r * ldc + col0 + bj * 128) = st; }
	v_pk_fma_f32 v[130:131], v[130:131], v[172:173], v[138:139] op_sel_hi:[1,0,1]
	v_pk_fma_f32 v[136:137], v[136:137], v[172:173], v[144:145] op_sel_hi:[1,0,1]
	v_pk_fma_f32 v[134:135], v[134:135], v[172:173], v[142:143] op_sel_hi:[1,0,1]
	v_pk_fma_f32 v[132:133], v[132:133], v[172:173], v[140:141] op_sel_hi:[1,0,1]
	s_nop 0
	v_cvt_pk_bf16_f32 v134, v134, v135
	s_nop 0
	v_cvt_pk_bf16_f32 v135, v136, v137
	s_nop 0
	v_cvt_pk_bf16_f32 v136, v130, v131
	v_mad_i64_i32 v[130:131], s[22:23], v174, s52, 0
	s_nop 0
	v_cvt_pk_bf16_f32 v137, v132, v133
	v_lshl_add_u64 v[130:131], v[130:131], 1, s[8:9]
	v_lshlrev_b64 v[132:133], 1, v[176:177]
	v_lshl_add_u64 v[130:131], v[130:131], 0, v[132:133]
	global_store_dwordx4 v[130:131], v[134:137], off
	v_pk_fma_f32 v[118:119], v[118:119], v[170:171], v[142:143] op_sel_hi:[1,0,1]
	v_pk_fma_f32 v[114:115], v[114:115], v[170:171], v[138:139] op_sel_hi:[1,0,1]
	v_or_b32_e32 v136, 16, v174
	v_pk_fma_f32 v[120:121], v[120:121], v[170:171], v[144:145] op_sel_hi:[1,0,1]
	v_pk_fma_f32 v[134:135], v[116:117], v[170:171], v[140:141] op_sel_hi:[1,0,1]
	s_nop 0
	v_cvt_pk_bf16_f32 v116, v118, v119
	s_nop 0
	v_cvt_pk_bf16_f32 v117, v120, v121
	s_nop 0
	v_cvt_pk_bf16_f32 v118, v114, v115
	v_mad_i64_i32 v[114:115], s[22:23], v136, s52, 0
	v_lshl_add_u64 v[114:115], v[114:115], 1, s[8:9]
	v_lshl_add_u64 v[114:115], v[114:115], 0, v[132:133]
	s_nop 0
	v_cvt_pk_bf16_f32 v119, v134, v135
	global_store_dwordx4 v[114:115], v[116:119], off
	v_pk_fma_f32 v[110:111], v[110:111], v[168:169], v[142:143] op_sel_hi:[1,0,1]
	v_pk_fma_f32 v[106:107], v[106:107], v[168:169], v[138:139] op_sel_hi:[1,0,1]
	v_or_b32_e32 v118, 32, v174
	v_pk_fma_f32 v[112:113], v[112:113], v[168:169], v[144:145] op_sel_hi:[1,0,1]
	v_pk_fma_f32 v[116:117], v[108:109], v[168:169], v[140:141] op_sel_hi:[1,0,1]
	s_nop 0
	v_cvt_pk_bf16_f32 v108, v110, v111
	s_nop 0
	v_cvt_pk_bf16_f32 v109, v112, v113
	s_nop 0
	v_cvt_pk_bf16_f32 v110, v106, v107
	v_mad_i64_i32 v[106:107], s[22:23], v118, s52, 0
	v_lshl_add_u64 v[106:107], v[106:107], 1, s[8:9]
	v_lshl_add_u64 v[106:107], v[106:107], 0, v[132:133]
	s_nop 0
	v_cvt_pk_bf16_f32 v111, v116, v117
	global_store_dwordx4 v[106:107], v[108:111], off
	v_pk_fma_f32 v[102:103], v[102:103], v[166:167], v[142:143] op_sel_hi:[1,0,1]
	v_pk_fma_f32 v[104:105], v[104:105], v[166:167], v[144:145] op_sel_hi:[1,0,1]
	v_or_b32_e32 v110, 48, v174
	v_pk_fma_f32 v[108:109], v[100:101], v[166:167], v[140:141] op_sel_hi:[1,0,1]
	v_pk_fma_f32 v[100:101], v[98:99], v[166:167], v[138:139] op_sel_hi:[1,0,1]
	s_nop 0
	v_cvt_pk_bf16_f32 v98, v102, v103
	v_mad_i64_i32 v[102:103], s[22:23], v110, s52, 0
	v_lshl_add_u64 v[102:103], v[102:103], 1, s[8:9]
	s_nop 0
	v_cvt_pk_bf16_f32 v99, v104, v105
	s_nop 0
	v_cvt_pk_bf16_f32 v100, v100, v101
	v_lshl_add_u64 v[102:103], v[102:103], 0, v[132:133]
	s_nop 0
	v_cvt_pk_bf16_f32 v101, v108, v109
	global_store_dwordx4 v[102:103], v[98:101], off
	v_pk_fma_f32 v[94:95], v[94:95], v[164:165], v[142:143] op_sel_hi:[1,0,1]
	v_pk_fma_f32 v[96:97], v[96:97], v[164:165], v[144:145] op_sel_hi:[1,0,1]
	v_add_u32_e32 v100, 0x80, v174
	v_pk_fma_f32 v[98:99], v[92:93], v[164:165], v[140:141] op_sel_hi:[1,0,1]
	v_pk_fma_f32 v[92:93], v[90:91], v[164:165], v[138:139] op_sel_hi:[1,0,1]
	s_nop 0
	v_cvt_pk_bf16_f32 v90, v94, v95
	v_mad_i64_i32 v[94:95], s[22:23], v100, s52, 0
	v_lshl_add_u64 v[94:95], v[94:95], 1, s[8:9]
	s_nop 0
	v_cvt_pk_bf16_f32 v91, v96, v97
	s_nop 0
	v_cvt_pk_bf16_f32 v92, v92, v93
	v_lshl_add_u64 v[94:95], v[94:95], 0, v[132:133]
	s_nop 0
	v_cvt_pk_bf16_f32 v93, v98, v99
	global_store_dwordx4 v[94:95], v[90:93], off
	v_pk_fma_f32 v[86:87], v[86:87], v[162:163], v[142:143] op_sel_hi:[1,0,1]
	v_pk_fma_f32 v[88:89], v[88:89], v[162:163], v[144:145] op_sel_hi:[1,0,1]
	v_add_u32_e32 v92, 0x90, v174
	v_pk_fma_f32 v[90:91], v[84:85], v[162:163], v[140:141] op_sel_hi:[1,0,1]
	v_pk_fma_f32 v[84:85], v[82:83], v[162:163], v[138:139] op_sel_hi:[1,0,1]
	s_nop 0
	v_cvt_pk_bf16_f32 v82, v86, v87
	v_mad_i64_i32 v[86:87], s[22:23], v92, s52, 0
	v_lshl_add_u64 v[86:87], v[86:87], 1, s[8:9]
	s_nop 0
	v_cvt_pk_bf16_f32 v83, v88, v89
	s_nop 0
	v_cvt_pk_bf16_f32 v84, v84, v85
	v_lshl_add_u64 v[86:87], v[86:87], 0, v[132:133]
	s_nop 0
	v_cvt_pk_bf16_f32 v85, v90, v91
	global_store_dwordx4 v[86:87], v[82:85], off
	v_pk_fma_f32 v[78:79], v[78:79], v[160:161], v[142:143] op_sel_hi:[1,0,1]
	v_pk_fma_f32 v[80:81], v[80:81], v[160:161], v[144:145] op_sel_hi:[1,0,1]
	v_add_u32_e32 v84, 0xa0, v174
	v_pk_fma_f32 v[82:83], v[76:77], v[160:161], v[140:141] op_sel_hi:[1,0,1]
	v_pk_fma_f32 v[76:77], v[74:75], v[160:161], v[138:139] op_sel_hi:[1,0,1]
	s_nop 0
	v_cvt_pk_bf16_f32 v74, v78, v79
	v_mad_i64_i32 v[78:79], s[22:23], v84, s52, 0
	v_lshl_add_u64 v[78:79], v[78:79], 1, s[8:9]
	s_nop 0
	v_cvt_pk_bf16_f32 v75, v80, v81
	s_nop 0
	v_cvt_pk_bf16_f32 v76, v76, v77
	v_lshl_add_u64 v[78:79], v[78:79], 0, v[132:133]
	s_nop 0
	v_cvt_pk_bf16_f32 v77, v82, v83
	global_store_dwordx4 v[78:79], v[74:77], off
; __device__ __forceinline__ unsigned cvt_pk_bf16(float lo, float hi) { unsigned r; asm volatile("s_nop 0\n\tv_cvt_pk_bf16_f32 %0, %1, %2" : "=v"(r) : "v"(lo), "v"(hi)); return r; }
; #define PG8_WAIT_V(n) asm volatile("s_waitcnt vmcnt(" #n ")" ::: "memory")
; #define PG8_BAR __builtin_amdgcn_s_barrier()
; template <class Epi>
; __device__ __forceinline__ void gemm_phase(LAS unsigned char* lds, const Gemm g, const StaticOrder& S, const Epi& E) {
;     ...
;         if (!has_next) break;
; #pragma unroll
;         for (int a = 0; a < 2; ++a)
; #pragma unroll
;             for (int b = 0; b < 2; ++b)
; #pragma unroll
;                 for (int m = 0; m < 4; ++m)
; #pragma unroll
;                     for (int n = 0; n < 2; ++n) acc[a][b][m][n] = (f32x4){0.f, 0.f, 0.f, 0.f};
;         cur = nxt; cA = nA; cB = nB; ++ui;
;     }
;     PG8_WAIT_V(0);
;     if (wr == 0) PG8_BAR;
;     PG8_BAR;
;     __device__ __forceinline__ void operator()(const f32x4 (&acc)[2][2][4][2], const Unit& u, int wr, int wc, int fr, int fq) const {
;     ...
;         for (int bj = 0; bj < 2; ++bj) {
;             const f32x4 s0 = swv[2 * bj], s1 = swv[2 * bj + 1];
; #pragma unroll
;             for (int ai = 0; ai < 2; ++ai)
; #pragma unroll
;                 for (int m = 0; m < 4; ++m) { const int r = row0 + ai * 128 + m * 16;
;                     const float rstd = ai ? rb[m] : ra[m];
;                     const f32x4 v0 = acc[ai][bj][m][0] * rstd + s0, v1 = acc[ai][bj][m][1] * rstd + s1;
;                     uint4 st; st.x = cvt_pk_bf16(v0[0], v0[1]); st.y = cvt_pk_bf16(v0[2], v0[3]); st.z = cvt_pk_bf16(v1[0], v1[1]); st.w = cvt_pk_bf16(v1[2], v1[3]);
;                     *(uint4*)(O + (size_t)r * ldc + col0 + bj * 128) = st; }
	v_pk_fma_f32 v[62:63], v[62:63], v[158:159], v[142:143] op_sel_hi:[1,0,1]
	v_pk_fma_f32 v[64:65], v[64:65], v[158:159], v[144:145] op_sel_hi:[1,0,1]
	v_add_u32_e32 v76, 0xb0, v174
	v_pk_fma_f32 v[74:75], v[60:61], v[158:159], v[140:141] op_sel_hi:[1,0,1]
	v_pk_fma_f32 v[60:61], v[58:59], v[158:159], v[138:139] op_sel_hi:[1,0,1]
	s_nop 0
	v_cvt_pk_bf16_f32 v58, v62, v63
	v_mad_i64_i32 v[62:63], s[22:23], v76, s52, 0
	v_lshl_add_u64 v[62:63], v[62:63], 1, s[8:9]
	s_nop 0
	v_cvt_pk_bf16_f32 v59, v64, v65
	v_lshl_add_u64 v[62:63], v[62:63], 0, v[132:133]
	s_nop 0
	v_cvt_pk_bf16_f32 v60, v60, v61
	s_nop 0
	v_cvt_pk_bf16_f32 v61, v74, v75
	global_store_dwordx4 v[62:63], v[58:61], off
	v_pk_fma_f32 v[64:65], v[68:69], v[172:173], v[124:125] op_sel_hi:[1,0,1]
	v_pk_fma_f32 v[66:67], v[66:67], v[172:173], v[122:123] op_sel_hi:[1,0,1]
	v_pk_fma_f32 v[58:59], v[70:71], v[172:173], v[126:127] op_sel_hi:[1,0,1]
	v_pk_fma_f32 v[60:61], v[72:73], v[172:173], v[128:129] op_sel_hi:[1,0,1]
	s_nop 0
	v_cvt_pk_bf16_f32 v58, v58, v59
	v_pk_fma_f32 v[56:57], v[56:57], v[170:171], v[128:129] op_sel_hi:[1,0,1]
	s_nop 0
	v_cvt_pk_bf16_f32 v59, v60, v61
	s_nop 0
	v_cvt_pk_bf16_f32 v60, v66, v67
	s_nop 0
	v_cvt_pk_bf16_f32 v61, v64, v65
	global_store_dwordx4 v[130:131], v[58:61], off offset:256
	v_pk_fma_f32 v[54:55], v[54:55], v[170:171], v[126:127] op_sel_hi:[1,0,1]
	v_pk_fma_f32 v[48:49], v[48:49], v[168:169], v[128:129] op_sel_hi:[1,0,1]
	v_pk_fma_f32 v[58:59], v[52:53], v[170:171], v[124:125] op_sel_hi:[1,0,1]
	v_pk_fma_f32 v[52:53], v[50:51], v[170:171], v[122:123] op_sel_hi:[1,0,1]
	s_nop 0
	v_cvt_pk_bf16_f32 v50, v54, v55
	s_nop 0
	v_cvt_pk_bf16_f32 v51, v56, v57
	v_pk_fma_f32 v[46:47], v[46:47], v[168:169], v[126:127] op_sel_hi:[1,0,1]
	s_nop 0
	v_cvt_pk_bf16_f32 v52, v52, v53
	s_nop 0
	v_cvt_pk_bf16_f32 v53, v58, v59
	global_store_dwordx4 v[114:115], v[50:53], off offset:256
	v_pk_fma_f32 v[40:41], v[40:41], v[166:167], v[128:129] op_sel_hi:[1,0,1]
	v_pk_fma_f32 v[38:39], v[38:39], v[166:167], v[126:127] op_sel_hi:[1,0,1]
	v_pk_fma_f32 v[50:51], v[44:45], v[168:169], v[124:125] op_sel_hi:[1,0,1]
	v_pk_fma_f32 v[44:45], v[42:43], v[168:169], v[122:123] op_sel_hi:[1,0,1]
	s_nop 0
	v_cvt_pk_bf16_f32 v42, v46, v47
	s_nop 0
	v_cvt_pk_bf16_f32 v43, v48, v49
	v_pk_fma_f32 v[32:33], v[32:33], v[164:165], v[128:129] op_sel_hi:[1,0,1]
	s_nop 0
	v_cvt_pk_bf16_f32 v44, v44, v45
	s_nop 0
	v_cvt_pk_bf16_f32 v45, v50, v51
	global_store_dwordx4 v[106:107], v[42:45], off offset:256
	v_pk_fma_f32 v[30:31], v[30:31], v[164:165], v[126:127] op_sel_hi:[1,0,1]
	v_pk_fma_f32 v[24:25], v[24:25], v[162:163], v[128:129] op_sel_hi:[1,0,1]
	v_pk_fma_f32 v[42:43], v[36:37], v[166:167], v[124:125] op_sel_hi:[1,0,1]
	v_pk_fma_f32 v[36:37], v[34:35], v[166:167], v[122:123] op_sel_hi:[1,0,1]
	s_nop 0
	v_cvt_pk_bf16_f32 v34, v38, v39
	s_nop 0
	v_cvt_pk_bf16_f32 v35, v40, v41
	v_pk_fma_f32 v[22:23], v[22:23], v[162:163], v[126:127] op_sel_hi:[1,0,1]
	s_nop 0
	v_cvt_pk_bf16_f32 v36, v36, v37
	s_nop 0
	v_cvt_pk_bf16_f32 v37, v42, v43
	global_store_dwordx4 v[102:103], v[34:37], off offset:256
	v_pk_fma_f32 v[16:17], v[16:17], v[160:161], v[128:129] op_sel_hi:[1,0,1]
	v_pk_fma_f32 v[14:15], v[14:15], v[160:161], v[126:127] op_sel_hi:[1,0,1]
	v_pk_fma_f32 v[34:35], v[28:29], v[164:165], v[124:125] op_sel_hi:[1,0,1]
	v_pk_fma_f32 v[28:29], v[26:27], v[164:165], v[122:123] op_sel_hi:[1,0,1]
	s_nop 0
	v_cvt_pk_bf16_f32 v26, v30, v31
	s_nop 0
	v_cvt_pk_bf16_f32 v27, v32, v33
	s_mov_b64 s[22:23], s[16:17]
	s_nop 0
	v_cvt_pk_bf16_f32 v28, v28, v29
	s_nop 0
	v_cvt_pk_bf16_f32 v29, v34, v35
	global_store_dwordx4 v[94:95], v[26:29], off offset:256
	v_pk_fma_f32 v[8:9], v[8:9], v[158:159], v[128:129] op_sel_hi:[1,0,1]
	v_pk_fma_f32 v[6:7], v[6:7], v[158:159], v[126:127] op_sel_hi:[1,0,1]
	v_pk_fma_f32 v[26:27], v[20:21], v[162:163], v[124:125] op_sel_hi:[1,0,1]
	v_pk_fma_f32 v[20:21], v[18:19], v[162:163], v[122:123] op_sel_hi:[1,0,1]
	s_nop 0
	v_cvt_pk_bf16_f32 v18, v22, v23
	s_nop 0
	v_cvt_pk_bf16_f32 v19, v24, v25
	s_nop 0
	s_nop 0
	v_cvt_pk_bf16_f32 v20, v20, v21
	s_nop 0
	v_cvt_pk_bf16_f32 v21, v26, v27
	global_store_dwordx4 v[86:87], v[18:21], off offset:256
	s_nop 1
	v_pk_fma_f32 v[18:19], v[12:13], v[160:161], v[124:125] op_sel_hi:[1,0,1]
	v_pk_fma_f32 v[12:13], v[10:11], v[160:161], v[122:123] op_sel_hi:[1,0,1]
	s_nop 0
	v_cvt_pk_bf16_f32 v10, v14, v15
	s_nop 0
	v_cvt_pk_bf16_f32 v11, v16, v17
	s_nop 0
	s_nop 0
	v_cvt_pk_bf16_f32 v12, v12, v13
	s_nop 0
	v_cvt_pk_bf16_f32 v13, v18, v19
	global_store_dwordx4 v[78:79], v[10:13], off offset:256
	s_nop 1
	v_pk_fma_f32 v[10:11], v[2:3], v[158:159], v[124:125] op_sel_hi:[1,0,1]
	v_pk_fma_f32 v[2:3], v[0:1], v[158:159], v[122:123] op_sel_hi:[1,0,1]
	s_nop 0
	v_cvt_pk_bf16_f32 v0, v6, v7
	s_nop 0
	v_cvt_pk_bf16_f32 v1, v8, v9
	s_nop 0
	s_nop 0
	v_cvt_pk_bf16_f32 v2, v2, v3
	s_nop 0
	v_cvt_pk_bf16_f32 v3, v10, v11
	global_store_dwordx4 v[62:63], v[0:3], off offset:256
	s_cbranch_vccz .LBB0_2076
	s_waitcnt vmcnt(0)
	s_cmpk_gt_u32 s28, 0xff
	s_cbranch_scc1 .LBB0_2083
	s_barrier

; #define PG8_STAGE(bufoff, gbase, voff) do { _Pragma("unroll") for (int _i = 0; _i < 2; ++_i) \
;         __builtin_amdgcn_global_load_lds((const unsigned*)((const char*)(gbase) + (voff)[_i]), (LAS unsigned*)(lds + (bufoff) + ldsw + _i * 8192), 16, 0, 0); } while (0)
; #define PG8_LDA(dst, b, h) do { _Pragma("unroll") for (int m = 0; m < 4; ++m) _Pragma("unroll") for (int k = 0; k < 2; ++k) dst[m][k] = *(const LAS bf16x8*)(lds + PG8_SA(b, h) + aoff + m * 2048 + k * 1024); } while (0)
; #define PG8_LDB(dst, b, h) do { _Pragma("unroll") for (int n = 0; n < 2; ++n) _Pragma("unroll") for (int k = 0; k < 2; ++k) dst[n][k] = *(const LAS bf16x8*)(lds + PG8_SB(b, h) + boff + n * 2048 + k * 1024); } while (0)
; #define PG8_MMA(ai, bj, At, Bt) do { __builtin_amdgcn_s_setprio(1); _Pragma("unroll") for (int m = 0; m < 4; ++m) _Pragma("unroll") for (int n = 0; n < 2; ++n) _Pragma("unroll") for (int k = 0; k < 2; ++k) \
;         acc[ai][bj][m][n] = __builtin_amdgcn_mfma_f32_16x16x32_bf16(Bt[n][k], At[m][k], acc[ai][bj][m][n], 0, 0, 0); __builtin_amdgcn_s_setprio(0); } while (0)
; #define PG8_WAIT_L(n) asm volatile("s_waitcnt lgkmcnt(" #n ")" ::: "memory")
; #define PG8_BAR __builtin_amdgcn_s_barrier()
; #define PG8_SCHED __builtin_amdgcn_sched_barrier(0)
; template <class Epi>
; __device__ __forceinline__ void gemm_phase(LAS unsigned char* lds, const Gemm g, const StaticOrder& S, const Epi& E) {
;     ...
;         for (int t = 0; t < nt; t += 2) {
;             const bool last = (t == nt - 2);
;             const char* a1 = cA + (size_t)(t + 1) * kstep;
;             const char* a2 = last ? nA : cA + (size_t)(t + 2) * kstep; const char* b2 = last ? nB : cB + (size_t)(t + 2) * kstep;
;             const char* a3 = a2 + kstep; const char* b3 = b2 + kstep;
;             PG8_LDB(B0, 0, 0); PG8_SCHED; PG8_LDA(At, 0, 0); PG8_STAGE(PG8_SA(1, 1), a1 + hstep, voffA);
;             PG8_WAIT_L(8); PG8_BAR; PG8_WAIT_L(0); PG8_MMA(0, 0, At, B0); PG8_BAR; PG8_SCHED;
;             PG8_LDB(B1, 0, 1); PG8_STAGE(PG8_SB(0, 0), b2, voffB);
;             PG8_BAR; PG8_WAIT_L(0); PG8_MMA(0, 1, At, B1); PG8_BAR;
;             PG8_LDA(At, 0, 1); PG8_STAGE(PG8_SA(0, 0), a2, voffA);
;             PG8_BAR; PG8_WAIT_L(0); PG8_MMA(1, 0, At, B0); PG8_BAR; PG8_SCHED;
.LBB0_2403:
	s_add_u32 s14, s12, 0x100
	s_addc_u32 s15, s13, 0
	s_add_i32 s0, 0, 0x10000
	v_add_u32_e32 v156, s0, v141
	ds_read_b128 v[144:147], v156
	ds_read_b128 v[148:151], v156 offset:1024
	ds_read_b128 v[152:155], v156 offset:2048
	ds_read_b128 v[156:159], v156 offset:3072
	s_cmp_eq_u32 s41, 2
	s_cselect_b32 s19, s7, s15
	s_cselect_b32 s18, s6, s14
	s_cselect_b32 s17, s9, s40
	s_cselect_b32 s16, s8, s39
	v_lshl_add_u64 v[176:177], s[12:13], 0, v[136:137]
	s_add_i32 m0, s26, 0xc000
	ds_read_b128 v[160:163], v143
	ds_read_b128 v[164:167], v143 offset:1024
	ds_read_b128 v[168:171], v143 offset:2048
	ds_read_b128 v[172:175], v143 offset:3072
	ds_read_b128 v[190:193], v143 offset:4096
	ds_read_b128 v[194:197], v143 offset:5120
	ds_read_b128 v[198:201], v143 offset:6144
	ds_read_b128 v[202:205], v143 offset:7168
	global_load_lds_dwordx4 v[176:177], off
	v_lshl_add_u64 v[176:177], s[12:13], 0, v[138:139]
	s_add_i32 m0, s26, 0xe000
	s_nop 0
	global_load_lds_dwordx4 v[176:177], off
	s_waitcnt lgkmcnt(8)
	s_barrier
	s_waitcnt lgkmcnt(0)
	v_mfma_f32_16x16x32_bf16 v[126:129], v[144:147], v[160:163], v[126:129]
	v_mfma_f32_16x16x32_bf16 v[122:125], v[152:155], v[160:163], v[122:125]
	v_mfma_f32_16x16x32_bf16 v[118:121], v[144:147], v[168:171], v[118:121]
	v_mfma_f32_16x16x32_bf16 v[114:117], v[152:155], v[168:171], v[114:117]
	v_mfma_f32_16x16x32_bf16 v[110:113], v[144:147], v[190:193], v[110:113]
	v_mfma_f32_16x16x32_bf16 v[106:109], v[152:155], v[190:193], v[106:109]
	v_mfma_f32_16x16x32_bf16 v[102:105], v[144:147], v[198:201], v[102:105]
	v_mfma_f32_16x16x32_bf16 v[98:101], v[152:155], v[198:201], v[98:101]
	v_mfma_f32_16x16x32_bf16 v[126:129], v[148:151], v[164:167], v[126:129]
	v_mfma_f32_16x16x32_bf16 v[122:125], v[156:159], v[164:167], v[122:125]
	v_mfma_f32_16x16x32_bf16 v[118:121], v[148:151], v[172:175], v[118:121]
	v_mfma_f32_16x16x32_bf16 v[114:117], v[156:159], v[172:175], v[114:117]
	v_mfma_f32_16x16x32_bf16 v[110:113], v[148:151], v[194:197], v[110:113]
	v_mfma_f32_16x16x32_bf16 v[106:109], v[156:159], v[194:197], v[106:109]
	v_mfma_f32_16x16x32_bf16 v[102:105], v[148:151], v[202:205], v[102:105]
	v_mfma_f32_16x16x32_bf16 v[98:101], v[156:159], v[202:205], v[98:101]
	s_barrier
	s_add_i32 s1, 0, 0x14000
	v_add_u32_e32 v176, s1, v141
	s_add_i32 s0, s0, s25
	ds_read_b128 v[206:209], v176
	ds_read_b128 v[210:213], v176 offset:1024
	ds_read_b128 v[214:217], v176 offset:2048
	ds_read_b128 v[218:221], v176 offset:3072
	v_lshl_add_u64 v[176:177], s[16:17], 0, v[4:5]
	s_mov_b32 m0, s0
	v_lshl_add_u64 v[186:187], s[16:17], 0, v[130:131]
	global_load_lds_dwordx4 v[176:177], off
	s_add_i32 m0, s0, 0x2000
	s_nop 0
	global_load_lds_dwordx4 v[186:187], off
	s_barrier
	s_waitcnt lgkmcnt(0)
	v_mfma_f32_16x16x32_bf16 v[74:77], v[206:209], v[160:163], v[74:77]
	v_mfma_f32_16x16x32_bf16 v[66:69], v[214:217], v[160:163], v[66:69]
	v_mfma_f32_16x16x32_bf16 v[58:61], v[206:209], v[168:171], v[58:61]
	v_mfma_f32_16x16x32_bf16 v[50:53], v[214:217], v[168:171], v[50:53]
	v_mfma_f32_16x16x32_bf16 v[46:49], v[206:209], v[190:193], v[46:49]
	v_mfma_f32_16x16x32_bf16 v[42:45], v[214:217], v[190:193], v[42:45]
	v_mfma_f32_16x16x32_bf16 v[38:41], v[206:209], v[198:201], v[38:41]
	v_mfma_f32_16x16x32_bf16 v[34:37], v[214:217], v[198:201], v[34:37]
	v_mfma_f32_16x16x32_bf16 v[74:77], v[210:213], v[164:167], v[74:77]
	v_mfma_f32_16x16x32_bf16 v[66:69], v[218:221], v[164:167], v[66:69]
	v_mfma_f32_16x16x32_bf16 v[58:61], v[210:213], v[172:175], v[58:61]
	v_mfma_f32_16x16x32_bf16 v[50:53], v[218:221], v[172:175], v[50:53]
	v_mfma_f32_16x16x32_bf16 v[46:49], v[210:213], v[194:197], v[46:49]
	v_mfma_f32_16x16x32_bf16 v[42:45], v[218:221], v[194:197], v[42:45]
	v_mfma_f32_16x16x32_bf16 v[38:41], v[210:213], v[202:205], v[38:41]
	v_mfma_f32_16x16x32_bf16 v[34:37], v[218:221], v[202:205], v[34:37]
	s_mov_b32 m0, s26
	v_lshl_add_u64 v[222:223], s[18:19], 0, v[134:135]
	s_barrier
	ds_read_b128 v[160:163], v143 offset:16384
	ds_read_b128 v[164:167], v143 offset:17408
	ds_read_b128 v[168:171], v143 offset:18432
	ds_read_b128 v[172:175], v143 offset:19456
	ds_read_b128 v[190:193], v143 offset:20480
	ds_read_b128 v[194:197], v143 offset:21504
	ds_read_b128 v[198:201], v143 offset:22528
	ds_read_b128 v[202:205], v143 offset:23552
	global_load_lds_dwordx4 v[222:223], off
	v_lshl_add_u64 v[224:225], s[18:19], 0, v[132:133]
	s_mov_b32 m0, s27
	s_nop 0
	global_load_lds_dwordx4 v[224:225], off
	s_barrier
	s_waitcnt lgkmcnt(0)
	v_mfma_f32_16x16x32_bf16 v[94:97], v[144:147], v[160:163], v[94:97]
	v_mfma_f32_16x16x32_bf16 v[90:93], v[152:155], v[160:163], v[90:93]
	v_mfma_f32_16x16x32_bf16 v[86:89], v[144:147], v[168:171], v[86:89]
	v_mfma_f32_16x16x32_bf16 v[82:85], v[152:155], v[168:171], v[82:85]
	v_mfma_f32_16x16x32_bf16 v[78:81], v[144:147], v[190:193], v[78:81]
	v_mfma_f32_16x16x32_bf16 v[70:73], v[152:155], v[190:193], v[70:73]
	v_mfma_f32_16x16x32_bf16 v[62:65], v[144:147], v[198:201], v[62:65]
	v_mfma_f32_16x16x32_bf16 v[54:57], v[152:155], v[198:201], v[54:57]
	v_mfma_f32_16x16x32_bf16 v[94:97], v[148:151], v[164:167], v[94:97]
	v_mfma_f32_16x16x32_bf16 v[90:93], v[156:159], v[164:167], v[90:93]
	v_mfma_f32_16x16x32_bf16 v[86:89], v[148:151], v[172:175], v[86:89]
	v_mfma_f32_16x16x32_bf16 v[82:85], v[156:159], v[172:175], v[82:85]
	v_mfma_f32_16x16x32_bf16 v[78:81], v[148:151], v[194:197], v[78:81]
	v_mfma_f32_16x16x32_bf16 v[70:73], v[156:159], v[194:197], v[70:73]
	v_mfma_f32_16x16x32_bf16 v[62:65], v[148:151], v[202:205], v[62:65]
	v_mfma_f32_16x16x32_bf16 v[54:57], v[156:159], v[202:205], v[54:57]
	s_barrier
; #define PG8_STAGE(bufoff, gbase, voff) do { _Pragma("unroll") for (int _i = 0; _i < 2; ++_i) \
;         __builtin_amdgcn_global_load_lds((const unsigned*)((const char*)(gbase) + (voff)[_i]), (LAS unsigned*)(lds + (bufoff) + ldsw + _i * 8192), 16, 0, 0); } while (0)
; #define PG8_LDA(dst, b, h) do { _Pragma("unroll") for (int m = 0; m < 4; ++m) _Pragma("unroll") for (int k = 0; k < 2; ++k) dst[m][k] = *(const LAS bf16x8*)(lds + PG8_SA(b, h) + aoff + m * 2048 + k * 1024); } while (0)
; #define PG8_LDB(dst, b, h) do { _Pragma("unroll") for (int n = 0; n < 2; ++n) _Pragma("unroll") for (int k = 0; k < 2; ++k) dst[n][k] = *(const LAS bf16x8*)(lds + PG8_SB(b, h) + boff + n * 2048 + k * 1024); } while (0)
; #define PG8_MMA(ai, bj, At, Bt) do { __builtin_amdgcn_s_setprio(1); _Pragma("unroll") for (int m = 0; m < 4; ++m) _Pragma("unroll") for (int n = 0; n < 2; ++n) _Pragma("unroll") for (int k = 0; k < 2; ++k) \
;         acc[ai][bj][m][n] = __builtin_amdgcn_mfma_f32_16x16x32_bf16(Bt[n][k], At[m][k], acc[ai][bj][m][n], 0, 0, 0); __builtin_amdgcn_s_setprio(0); } while (0)
; #define PG8_WAIT_V(n) asm volatile("s_waitcnt vmcnt(" #n ")" ::: "memory")
; #define PG8_WAIT_L(n) asm volatile("s_waitcnt lgkmcnt(" #n ")" ::: "memory")
; #define PG8_BAR __builtin_amdgcn_s_barrier()
; #define PG8_SCHED __builtin_amdgcn_sched_barrier(0)
; template <class Epi>
; __device__ __forceinline__ void gemm_phase(LAS unsigned char* lds, const Gemm g, const StaticOrder& S, const Epi& E) {
;     ...
;             PG8_STAGE(PG8_SB(0, 1), b2 + hstep, voffB);
;             PG8_WAIT_V(6); PG8_BAR; PG8_MMA(1, 1, At, B1); PG8_BAR;
;             PG8_LDB(B0, 1, 0); PG8_SCHED; PG8_LDA(At, 1, 0); PG8_STAGE(PG8_SA(0, 1), a2 + hstep, voffA);
;             PG8_WAIT_L(8); PG8_BAR; PG8_WAIT_L(0); PG8_MMA(0, 0, At, B0); PG8_BAR; PG8_SCHED;
;             PG8_LDB(B1, 1, 1); PG8_STAGE(PG8_SB(1, 0), b3, voffB);
;             PG8_BAR; PG8_WAIT_L(0); PG8_MMA(0, 1, At, B1); PG8_BAR;
;             PG8_LDA(At, 1, 1); PG8_STAGE(PG8_SA(1, 0), a3, voffA);
	s_add_u32 s12, s16, 0x18000
	s_addc_u32 s13, s17, 0
	s_add_i32 s0, s1, s25
	v_lshl_add_u64 v[144:145], s[12:13], 0, v[4:5]
	s_mov_b32 m0, s0
	s_nop 0
	global_load_lds_dwordx4 v[144:145], off
	v_lshl_add_u64 v[144:145], s[12:13], 0, v[130:131]
	s_add_i32 m0, s0, 0x2000
	s_nop 0
	global_load_lds_dwordx4 v[144:145], off
	s_waitcnt vmcnt(6)
	s_barrier
	v_mfma_f32_16x16x32_bf16 v[30:33], v[206:209], v[160:163], v[30:33]
	v_mfma_f32_16x16x32_bf16 v[26:29], v[214:217], v[160:163], v[26:29]
	v_mfma_f32_16x16x32_bf16 v[22:25], v[206:209], v[168:171], v[22:25]
	v_mfma_f32_16x16x32_bf16 v[18:21], v[214:217], v[168:171], v[18:21]
	v_mfma_f32_16x16x32_bf16 v[14:17], v[206:209], v[190:193], v[14:17]
	v_mfma_f32_16x16x32_bf16 v[10:13], v[214:217], v[190:193], v[10:13]
	v_mfma_f32_16x16x32_bf16 v[6:9], v[206:209], v[198:201], v[6:9]
	v_mfma_f32_16x16x32_bf16 v[0:3], v[214:217], v[198:201], v[0:3]
	v_mfma_f32_16x16x32_bf16 v[30:33], v[210:213], v[164:167], v[30:33]
	v_mfma_f32_16x16x32_bf16 v[26:29], v[218:221], v[164:167], v[26:29]
	v_mfma_f32_16x16x32_bf16 v[22:25], v[210:213], v[172:175], v[22:25]
	v_mfma_f32_16x16x32_bf16 v[18:21], v[218:221], v[172:175], v[18:21]
	v_mfma_f32_16x16x32_bf16 v[14:17], v[210:213], v[194:197], v[14:17]
	v_mfma_f32_16x16x32_bf16 v[10:13], v[218:221], v[194:197], v[10:13]
	v_mfma_f32_16x16x32_bf16 v[6:9], v[210:213], v[202:205], v[6:9]
	v_mfma_f32_16x16x32_bf16 v[0:3], v[218:221], v[202:205], v[0:3]
	s_add_i32 s0, 0, 0x18000
	v_add_u32_e32 v156, s0, v141
	s_barrier
	ds_read_b128 v[144:147], v156
	ds_read_b128 v[148:151], v156 offset:1024
	ds_read_b128 v[152:155], v156 offset:2048
	ds_read_b128 v[156:159], v156 offset:3072
	s_add_u32 s12, s18, 0x18000
	s_addc_u32 s13, s19, 0
	s_mov_b32 m0, s28
	v_lshl_add_u64 v[206:207], s[12:13], 0, v[134:135]
	ds_read_b128 v[160:163], v143 offset:32768
	ds_read_b128 v[164:167], v143 offset:33792
	ds_read_b128 v[168:171], v143 offset:34816
	ds_read_b128 v[172:175], v143 offset:35840
	ds_read_b128 v[190:193], v143 offset:36864
	ds_read_b128 v[194:197], v143 offset:37888
	ds_read_b128 v[198:201], v143 offset:38912
	ds_read_b128 v[202:205], v143 offset:39936
	global_load_lds_dwordx4 v[206:207], off
	v_lshl_add_u64 v[206:207], s[12:13], 0, v[132:133]
	s_mov_b32 m0, s29
	s_nop 0
	global_load_lds_dwordx4 v[206:207], off
	s_waitcnt lgkmcnt(8)
	s_barrier
	s_waitcnt lgkmcnt(0)
	v_mfma_f32_16x16x32_bf16 v[126:129], v[144:147], v[160:163], v[126:129]
	v_mfma_f32_16x16x32_bf16 v[122:125], v[152:155], v[160:163], v[122:125]
	v_mfma_f32_16x16x32_bf16 v[118:121], v[144:147], v[168:171], v[118:121]
	v_mfma_f32_16x16x32_bf16 v[114:117], v[152:155], v[168:171], v[114:117]
	v_mfma_f32_16x16x32_bf16 v[110:113], v[144:147], v[190:193], v[110:113]
	v_mfma_f32_16x16x32_bf16 v[106:109], v[152:155], v[190:193], v[106:109]
	v_mfma_f32_16x16x32_bf16 v[102:105], v[144:147], v[198:201], v[102:105]
	v_mfma_f32_16x16x32_bf16 v[98:101], v[152:155], v[198:201], v[98:101]
	v_mfma_f32_16x16x32_bf16 v[126:129], v[148:151], v[164:167], v[126:129]
	v_mfma_f32_16x16x32_bf16 v[122:125], v[156:159], v[164:167], v[122:125]
	v_mfma_f32_16x16x32_bf16 v[118:121], v[148:151], v[172:175], v[118:121]
	v_mfma_f32_16x16x32_bf16 v[114:117], v[156:159], v[172:175], v[114:117]
	v_mfma_f32_16x16x32_bf16 v[110:113], v[148:151], v[194:197], v[110:113]
	v_mfma_f32_16x16x32_bf16 v[106:109], v[156:159], v[194:197], v[106:109]
	v_mfma_f32_16x16x32_bf16 v[102:105], v[148:151], v[202:205], v[102:105]
	v_mfma_f32_16x16x32_bf16 v[98:101], v[156:159], v[202:205], v[98:101]
	s_barrier
	s_add_i32 s1, 0, 0x1c000
	s_add_i32 s0, s0, s25
	v_add_u32_e32 v218, s1, v141
	v_lshl_add_u64 v[176:177], v[176:177], 0, s[86:87]
	s_mov_b32 m0, s0
	ds_read_b128 v[206:209], v218
	ds_read_b128 v[210:213], v218 offset:1024
	ds_read_b128 v[214:217], v218 offset:2048
	ds_read_b128 v[218:221], v218 offset:3072
	global_load_lds_dwordx4 v[176:177], off
	v_lshl_add_u64 v[176:177], v[186:187], 0, s[86:87]
	s_add_i32 m0, s0, 0x2000
	s_nop 0
	global_load_lds_dwordx4 v[176:177], off
	s_barrier
	s_waitcnt lgkmcnt(0)
	v_mfma_f32_16x16x32_bf16 v[74:77], v[206:209], v[160:163], v[74:77]
	v_mfma_f32_16x16x32_bf16 v[66:69], v[214:217], v[160:163], v[66:69]
	v_mfma_f32_16x16x32_bf16 v[58:61], v[206:209], v[168:171], v[58:61]
	v_mfma_f32_16x16x32_bf16 v[50:53], v[214:217], v[168:171], v[50:53]
	v_mfma_f32_16x16x32_bf16 v[46:49], v[206:209], v[190:193], v[46:49]
	v_mfma_f32_16x16x32_bf16 v[42:45], v[214:217], v[190:193], v[42:45]
	v_mfma_f32_16x16x32_bf16 v[38:41], v[206:209], v[198:201], v[38:41]
	v_mfma_f32_16x16x32_bf16 v[34:37], v[214:217], v[198:201], v[34:37]
	v_mfma_f32_16x16x32_bf16 v[74:77], v[210:213], v[164:167], v[74:77]
	v_mfma_f32_16x16x32_bf16 v[66:69], v[218:221], v[164:167], v[66:69]
	v_mfma_f32_16x16x32_bf16 v[58:61], v[210:213], v[172:175], v[58:61]
	v_mfma_f32_16x16x32_bf16 v[50:53], v[218:221], v[172:175], v[50:53]
	v_mfma_f32_16x16x32_bf16 v[46:49], v[210:213], v[194:197], v[46:49]
	v_mfma_f32_16x16x32_bf16 v[42:45], v[218:221], v[194:197], v[42:45]
	v_mfma_f32_16x16x32_bf16 v[38:41], v[210:213], v[202:205], v[38:41]
	v_mfma_f32_16x16x32_bf16 v[34:37], v[218:221], v[202:205], v[34:37]
	s_mov_b32 m0, s30
	v_lshl_add_u64 v[176:177], v[222:223], 0, s[86:87]
	s_barrier
	ds_read_b128 v[160:163], v143 offset:49152
	ds_read_b128 v[164:167], v143 offset:50176
	ds_read_b128 v[168:171], v143 offset:51200
	ds_read_b128 v[172:175], v143 offset:52224
	ds_read_b128 v[190:193], v143 offset:53248
	ds_read_b128 v[194:197], v143 offset:54272
	ds_read_b128 v[198:201], v143 offset:55296
	ds_read_b128 v[202:205], v143 offset:56320
	global_load_lds_dwordx4 v[176:177], off
	v_lshl_add_u64 v[176:177], v[224:225], 0, s[86:87]
	s_mov_b32 m0, s31
	s_nop 0
	global_load_lds_dwordx4 v[176:177], off
	s_barrier
; __device__ __forceinline__ unsigned cvt_pk_bf16(float lo, float hi) { unsigned r; asm volatile("s_nop 0\n\tv_cvt_pk_bf16_f32 %0, %1, %2" : "=v"(r) : "v"(lo), "v"(hi)); return r; }
; #define PG8_STAGE(bufoff, gbase, voff) do { _Pragma("unroll") for (int _i = 0; _i < 2; ++_i) \
;         __builtin_amdgcn_global_load_lds((const unsigned*)((const char*)(gbase) + (voff)[_i]), (LAS unsigned*)(lds + (bufoff) + ldsw + _i * 8192), 16, 0, 0); } while (0)
; #define PG8_MMA(ai, bj, At, Bt) do { __builtin_amdgcn_s_setprio(1); _Pragma("unroll") for (int m = 0; m < 4; ++m) _Pragma("unroll") for (int n = 0; n < 2; ++n) _Pragma("unroll") for (int k = 0; k < 2; ++k) \
;         acc[ai][bj][m][n] = __builtin_amdgcn_mfma_f32_16x16x32_bf16(Bt[n][k], At[m][k], acc[ai][bj][m][n], 0, 0, 0); __builtin_amdgcn_s_setprio(0); } while (0)
; #define PG8_WAIT_V(n) asm volatile("s_waitcnt vmcnt(" #n ")" ::: "memory")
; #define PG8_WAIT_L(n) asm volatile("s_waitcnt lgkmcnt(" #n ")" ::: "memory")
; #define PG8_BAR __builtin_amdgcn_s_barrier()
; #define PG8_SCHED __builtin_amdgcn_sched_barrier(0)
; template <class Epi>
; __device__ __forceinline__ void gemm_phase(LAS unsigned char* lds, const Gemm g, const StaticOrder& S, const Epi& E) {
;     ...
;             PG8_BAR; PG8_WAIT_L(0); PG8_MMA(1, 0, At, B0); PG8_BAR; PG8_SCHED;
;             PG8_STAGE(PG8_SB(1, 1), b3 + hstep, voffB);
;             PG8_WAIT_V(6); PG8_BAR; PG8_MMA(1, 1, At, B1); PG8_BAR;
;         }
;         E(acc, cur, wr, wc, fr, fq);
;     __device__ __forceinline__ void operator()(const f32x4 (&acc)[2][2][4][2], const Unit& u, int wr, int wc, int fr, int fq) const {
;     ...
;         for (int bj = 0; bj < 2; ++bj) {
;             const f32x4 s0 = swv[2 * bj], s1 = swv[2 * bj + 1];
; #pragma unroll
;             for (int ai = 0; ai < 2; ++ai)
; #pragma unroll
;                 for (int m = 0; m < 4; ++m) { const int r = row0 + ai * 128 + m * 16;
;                     const float rstd = ai ? rb[m] : ra[m];
;                     const f32x4 v0 = acc[ai][bj][m][0] * rstd + s0, v1 = acc[ai][bj][m][1] * rstd + s1;
;                     uint4 st; st.x = cvt_pk_bf16(v0[0], v0[1]); st.y = cvt_pk_bf16(v0[2], v0[3]); st.z = cvt_pk_bf16(v1[0], v1[1]); st.w = cvt_pk_bf16(v1[2], v1[3]);
;                     *(uint4*)(O + (size_t)r * ldc + col0 + bj * 128) = st; }
	s_waitcnt lgkmcnt(0)
	v_mfma_f32_16x16x32_bf16 v[94:97], v[144:147], v[160:163], v[94:97]
	v_mfma_f32_16x16x32_bf16 v[90:93], v[152:155], v[160:163], v[90:93]
	v_mfma_f32_16x16x32_bf16 v[86:89], v[144:147], v[168:171], v[86:89]
	v_mfma_f32_16x16x32_bf16 v[82:85], v[152:155], v[168:171], v[82:85]
	v_mfma_f32_16x16x32_bf16 v[78:81], v[144:147], v[190:193], v[78:81]
	v_mfma_f32_16x16x32_bf16 v[70:73], v[152:155], v[190:193], v[70:73]
	v_mfma_f32_16x16x32_bf16 v[62:65], v[144:147], v[198:201], v[62:65]
	v_mfma_f32_16x16x32_bf16 v[54:57], v[152:155], v[198:201], v[54:57]
	v_mfma_f32_16x16x32_bf16 v[94:97], v[148:151], v[164:167], v[94:97]
	v_mfma_f32_16x16x32_bf16 v[90:93], v[156:159], v[164:167], v[90:93]
	v_mfma_f32_16x16x32_bf16 v[86:89], v[148:151], v[172:175], v[86:89]
	v_mfma_f32_16x16x32_bf16 v[82:85], v[156:159], v[172:175], v[82:85]
	v_mfma_f32_16x16x32_bf16 v[78:81], v[148:151], v[194:197], v[78:81]
	v_mfma_f32_16x16x32_bf16 v[70:73], v[156:159], v[194:197], v[70:73]
	v_mfma_f32_16x16x32_bf16 v[62:65], v[148:151], v[202:205], v[62:65]
	v_mfma_f32_16x16x32_bf16 v[54:57], v[156:159], v[202:205], v[54:57]
	s_barrier
	s_add_u32 s12, s16, 0x18080
	s_addc_u32 s13, s17, 0
	s_add_i32 s0, s1, s25
	v_lshl_add_u64 v[144:145], s[12:13], 0, v[4:5]
	s_mov_b32 m0, s0
	s_nop 0
	global_load_lds_dwordx4 v[144:145], off
	v_lshl_add_u64 v[144:145], s[12:13], 0, v[130:131]
	s_add_i32 m0, s0, 0x2000
	s_nop 0
	global_load_lds_dwordx4 v[144:145], off
	s_waitcnt vmcnt(6)
	s_barrier
	v_mfma_f32_16x16x32_bf16 v[30:33], v[206:209], v[160:163], v[30:33]
	v_mfma_f32_16x16x32_bf16 v[26:29], v[214:217], v[160:163], v[26:29]
	v_mfma_f32_16x16x32_bf16 v[22:25], v[206:209], v[168:171], v[22:25]
	v_mfma_f32_16x16x32_bf16 v[18:21], v[214:217], v[168:171], v[18:21]
	v_mfma_f32_16x16x32_bf16 v[14:17], v[206:209], v[190:193], v[14:17]
	v_mfma_f32_16x16x32_bf16 v[10:13], v[214:217], v[190:193], v[10:13]
	v_mfma_f32_16x16x32_bf16 v[6:9], v[206:209], v[198:201], v[6:9]
	v_mfma_f32_16x16x32_bf16 v[0:3], v[214:217], v[198:201], v[0:3]
	v_mfma_f32_16x16x32_bf16 v[30:33], v[210:213], v[164:167], v[30:33]
	v_mfma_f32_16x16x32_bf16 v[26:29], v[218:221], v[164:167], v[26:29]
	v_mfma_f32_16x16x32_bf16 v[22:25], v[210:213], v[172:175], v[22:25]
	v_mfma_f32_16x16x32_bf16 v[18:21], v[218:221], v[172:175], v[18:21]
	v_mfma_f32_16x16x32_bf16 v[14:17], v[210:213], v[194:197], v[14:17]
	v_mfma_f32_16x16x32_bf16 v[10:13], v[218:221], v[194:197], v[10:13]
	v_mfma_f32_16x16x32_bf16 v[6:9], v[210:213], v[202:205], v[6:9]
	v_mfma_f32_16x16x32_bf16 v[0:3], v[218:221], v[202:205], v[0:3]
	s_add_i32 s41, s41, 2
	s_add_u32 s39, s39, 0x100
	s_addc_u32 s40, s40, 0
	s_cmp_gt_u32 s41, 3
	s_mov_b64 s[12:13], s[14:15]
	s_barrier
	s_cbranch_scc0 .LBB0_2403
	v_lshl_or_b32 v144, s37, 8, v142
	v_pk_add_f32 v[126:127], v[126:127], 0 op_sel_hi:[1,0]
	v_lshl_add_u32 v148, s38, 8, v140
	v_ashrrev_i32_e32 v145, 31, v144
	v_pk_add_f32 v[128:129], v[128:129], 0 op_sel_hi:[1,0]
	v_pk_add_f32 v[146:147], v[124:125], 0 op_sel_hi:[1,0]
	v_pk_add_f32 v[124:125], v[122:123], 0 op_sel_hi:[1,0]
	s_nop 0
	v_cvt_pk_bf16_f32 v122, v126, v127
	v_mov_b64_e32 v[126:127], s[10:11]
	s_nop 0
	v_cvt_pk_bf16_f32 v123, v128, v129
	v_mad_i64_i32 v[128:129], s[12:13], v148, s83, v[126:127]
	v_lshlrev_b64 v[144:145], 1, v[144:145]
	s_nop 0
	v_cvt_pk_bf16_f32 v124, v124, v125
	v_lshl_add_u64 v[128:129], v[128:129], 0, v[144:145]
	s_nop 0
	v_cvt_pk_bf16_f32 v125, v146, v147
	global_store_dwordx4 v[128:129], v[122:125], off
	v_pk_add_f32 v[118:119], v[118:119], 0 op_sel_hi:[1,0]
	v_pk_add_f32 v[120:121], v[120:121], 0 op_sel_hi:[1,0]
	v_or_b32_e32 v124, 16, v148
	v_pk_add_f32 v[122:123], v[116:117], 0 op_sel_hi:[1,0]
	v_pk_add_f32 v[116:117], v[114:115], 0 op_sel_hi:[1,0]
	s_nop 0
	v_cvt_pk_bf16_f32 v114, v118, v119
	v_mad_i64_i32 v[118:119], s[12:13], v124, s83, v[126:127]
	s_nop 0
	v_cvt_pk_bf16_f32 v115, v120, v121
	s_nop 0
	v_cvt_pk_bf16_f32 v116, v116, v117
	v_lshl_add_u64 v[118:119], v[118:119], 0, v[144:145]
	s_nop 0
	v_cvt_pk_bf16_f32 v117, v122, v123
	global_store_dwordx4 v[118:119], v[114:117], off
	v_pk_add_f32 v[110:111], v[110:111], 0 op_sel_hi:[1,0]
	v_pk_add_f32 v[112:113], v[112:113], 0 op_sel_hi:[1,0]
	v_or_b32_e32 v116, 32, v148
	v_pk_add_f32 v[114:115], v[108:109], 0 op_sel_hi:[1,0]
	v_pk_add_f32 v[108:109], v[106:107], 0 op_sel_hi:[1,0]
	s_nop 0
	v_cvt_pk_bf16_f32 v106, v110, v111
	v_mad_i64_i32 v[110:111], s[12:13], v116, s83, v[126:127]
	s_nop 0
	v_cvt_pk_bf16_f32 v107, v112, v113
	s_nop 0
	v_cvt_pk_bf16_f32 v108, v108, v109
	v_lshl_add_u64 v[110:111], v[110:111], 0, v[144:145]
	s_nop 0
	v_cvt_pk_bf16_f32 v109, v114, v115
	global_store_dwordx4 v[110:111], v[106:109], off
	v_pk_add_f32 v[102:103], v[102:103], 0 op_sel_hi:[1,0]
	v_pk_add_f32 v[104:105], v[104:105], 0 op_sel_hi:[1,0]
	v_or_b32_e32 v108, 48, v148
	v_pk_add_f32 v[106:107], v[100:101], 0 op_sel_hi:[1,0]
	v_pk_add_f32 v[100:101], v[98:99], 0 op_sel_hi:[1,0]
	s_nop 0
	v_cvt_pk_bf16_f32 v98, v102, v103
	v_mad_i64_i32 v[102:103], s[12:13], v108, s83, v[126:127]
	s_nop 0
	v_cvt_pk_bf16_f32 v99, v104, v105
	s_nop 0
	v_cvt_pk_bf16_f32 v100, v100, v101
	v_lshl_add_u64 v[102:103], v[102:103], 0, v[144:145]
	s_nop 0
	v_cvt_pk_bf16_f32 v101, v106, v107
	global_store_dwordx4 v[102:103], v[98:101], off
	v_pk_add_f32 v[94:95], v[94:95], 0 op_sel_hi:[1,0]
	v_pk_add_f32 v[96:97], v[96:97], 0 op_sel_hi:[1,0]
	v_add_u32_e32 v100, 0x80, v148
	v_pk_add_f32 v[98:99], v[92:93], 0 op_sel_hi:[1,0]
	v_pk_add_f32 v[92:93], v[90:91], 0 op_sel_hi:[1,0]
	s_nop 0
	v_cvt_pk_bf16_f32 v90, v94, v95
	v_mad_i64_i32 v[94:95], s[12:13], v100, s83, v[126:127]
; __device__ __forceinline__ unsigned cvt_pk_bf16(float lo, float hi) { unsigned r; asm volatile("s_nop 0\n\tv_cvt_pk_bf16_f32 %0, %1, %2" : "=v"(r) : "v"(lo), "v"(hi)); return r; }
; #define PG8_WAIT_V(n) asm volatile("s_waitcnt vmcnt(" #n ")" ::: "memory")
; #define PG8_BAR __builtin_amdgcn_s_barrier()
; template <class Epi>
; __device__ __forceinline__ void gemm_phase(LAS unsigned char* lds, const Gemm g, const StaticOrder& S, const Epi& E) {
;     ...
;         if (!has_next) break;
; #pragma unroll
;         for (int a = 0; a < 2; ++a)
; #pragma unroll
;             for (int b = 0; b < 2; ++b)
; #pragma unroll
;                 for (int m = 0; m < 4; ++m)
; #pragma unroll
;                     for (int n = 0; n < 2; ++n) acc[a][b][m][n] = (f32x4){0.f, 0.f, 0.f, 0.f};
;         cur = nxt; cA = nA; cB = nB; ++ui;
;     }
;     PG8_WAIT_V(0);
;     if (wr == 0) PG8_BAR;
;     __device__ __forceinline__ void operator()(const f32x4 (&acc)[2][2][4][2], const Unit& u, int wr, int wc, int fr, int fq) const {
;     ...
;         for (int bj = 0; bj < 2; ++bj) {
;             const f32x4 s0 = swv[2 * bj], s1 = swv[2 * bj + 1];
; #pragma unroll
;             for (int ai = 0; ai < 2; ++ai)
; #pragma unroll
;                 for (int m = 0; m < 4; ++m) { const int r = row0 + ai * 128 + m * 16;
;                     const float rstd = ai ? rb[m] : ra[m];
;                     const f32x4 v0 = acc[ai][bj][m][0] * rstd + s0, v1 = acc[ai][bj][m][1] * rstd + s1;
;                     uint4 st; st.x = cvt_pk_bf16(v0[0], v0[1]); st.y = cvt_pk_bf16(v0[2], v0[3]); st.z = cvt_pk_bf16(v1[0], v1[1]); st.w = cvt_pk_bf16(v1[2], v1[3]);
;                     *(uint4*)(O + (size_t)r * ldc + col0 + bj * 128) = st; }
	s_nop 0
	v_cvt_pk_bf16_f32 v91, v96, v97
	s_nop 0
	v_cvt_pk_bf16_f32 v92, v92, v93
	v_lshl_add_u64 v[94:95], v[94:95], 0, v[144:145]
	s_nop 0
	v_cvt_pk_bf16_f32 v93, v98, v99
	global_store_dwordx4 v[94:95], v[90:93], off
	v_pk_add_f32 v[86:87], v[86:87], 0 op_sel_hi:[1,0]
	v_pk_add_f32 v[88:89], v[88:89], 0 op_sel_hi:[1,0]
	v_add_u32_e32 v92, 0x90, v148
	v_pk_add_f32 v[90:91], v[84:85], 0 op_sel_hi:[1,0]
	v_pk_add_f32 v[84:85], v[82:83], 0 op_sel_hi:[1,0]
	s_nop 0
	v_cvt_pk_bf16_f32 v82, v86, v87
	v_mad_i64_i32 v[86:87], s[12:13], v92, s83, v[126:127]
	s_nop 0
	v_cvt_pk_bf16_f32 v83, v88, v89
	s_nop 0
	v_cvt_pk_bf16_f32 v84, v84, v85
	v_lshl_add_u64 v[86:87], v[86:87], 0, v[144:145]
	s_nop 0
	v_cvt_pk_bf16_f32 v85, v90, v91
	global_store_dwordx4 v[86:87], v[82:85], off
	v_pk_add_f32 v[78:79], v[78:79], 0 op_sel_hi:[1,0]
	v_pk_add_f32 v[80:81], v[80:81], 0 op_sel_hi:[1,0]
	v_add_u32_e32 v84, 0xa0, v148
	v_pk_add_f32 v[82:83], v[72:73], 0 op_sel_hi:[1,0]
	v_pk_add_f32 v[72:73], v[70:71], 0 op_sel_hi:[1,0]
	s_nop 0
	v_cvt_pk_bf16_f32 v70, v78, v79
	v_mad_i64_i32 v[78:79], s[12:13], v84, s83, v[126:127]
	s_nop 0
	v_cvt_pk_bf16_f32 v71, v80, v81
	s_nop 0
	v_cvt_pk_bf16_f32 v72, v72, v73
	v_lshl_add_u64 v[78:79], v[78:79], 0, v[144:145]
	s_nop 0
	v_cvt_pk_bf16_f32 v73, v82, v83
	global_store_dwordx4 v[78:79], v[70:73], off
	v_pk_add_f32 v[62:63], v[62:63], 0 op_sel_hi:[1,0]
	v_pk_add_f32 v[64:65], v[64:65], 0 op_sel_hi:[1,0]
	v_add_u32_e32 v72, 0xb0, v148
	v_pk_add_f32 v[70:71], v[56:57], 0 op_sel_hi:[1,0]
	v_pk_add_f32 v[56:57], v[54:55], 0 op_sel_hi:[1,0]
	s_nop 0
	v_cvt_pk_bf16_f32 v54, v62, v63
	v_mad_i64_i32 v[62:63], s[12:13], v72, s83, v[126:127]
	s_nop 0
	v_cvt_pk_bf16_f32 v55, v64, v65
	s_nop 0
	v_cvt_pk_bf16_f32 v56, v56, v57
	s_nop 0
	v_cvt_pk_bf16_f32 v57, v70, v71
	v_lshl_add_u64 v[62:63], v[62:63], 0, v[144:145]
	global_store_dwordx4 v[62:63], v[54:57], off
	v_pk_add_f32 v[64:65], v[68:69], 0 op_sel_hi:[1,0]
	v_pk_add_f32 v[66:67], v[66:67], 0 op_sel_hi:[1,0]
	v_pk_add_f32 v[56:57], v[76:77], 0 op_sel_hi:[1,0]
	v_pk_add_f32 v[54:55], v[74:75], 0 op_sel_hi:[1,0]
	v_pk_add_f32 v[48:49], v[48:49], 0 op_sel_hi:[1,0]
	s_nop 0
	v_cvt_pk_bf16_f32 v54, v54, v55
	s_nop 0
	v_cvt_pk_bf16_f32 v55, v56, v57
	s_nop 0
	v_cvt_pk_bf16_f32 v56, v66, v67
	s_nop 0
	v_cvt_pk_bf16_f32 v57, v64, v65
	global_store_dwordx4 v[128:129], v[54:57], off offset:256
	v_pk_add_f32 v[46:47], v[46:47], 0 op_sel_hi:[1,0]
	v_pk_add_f32 v[40:41], v[40:41], 0 op_sel_hi:[1,0]
	v_pk_add_f32 v[54:55], v[60:61], 0 op_sel_hi:[1,0]
	v_pk_add_f32 v[56:57], v[58:59], 0 op_sel_hi:[1,0]
	v_pk_add_f32 v[58:59], v[52:53], 0 op_sel_hi:[1,0]
	v_pk_add_f32 v[52:53], v[50:51], 0 op_sel_hi:[1,0]
	s_nop 0
	v_cvt_pk_bf16_f32 v50, v56, v57
	s_nop 0
	v_cvt_pk_bf16_f32 v51, v54, v55
	v_pk_add_f32 v[38:39], v[38:39], 0 op_sel_hi:[1,0]
	s_nop 0
	v_cvt_pk_bf16_f32 v52, v52, v53
	s_nop 0
	v_cvt_pk_bf16_f32 v53, v58, v59
	global_store_dwordx4 v[118:119], v[50:53], off offset:256
	v_pk_add_f32 v[32:33], v[32:33], 0 op_sel_hi:[1,0]
	v_pk_add_f32 v[30:31], v[30:31], 0 op_sel_hi:[1,0]
	v_pk_add_f32 v[50:51], v[44:45], 0 op_sel_hi:[1,0]
	v_pk_add_f32 v[44:45], v[42:43], 0 op_sel_hi:[1,0]
	s_nop 0
	v_cvt_pk_bf16_f32 v42, v46, v47
	s_nop 0
	v_cvt_pk_bf16_f32 v43, v48, v49
	v_pk_add_f32 v[24:25], v[24:25], 0 op_sel_hi:[1,0]
	s_nop 0
	v_cvt_pk_bf16_f32 v44, v44, v45
	s_nop 0
	v_cvt_pk_bf16_f32 v45, v50, v51
	global_store_dwordx4 v[110:111], v[42:45], off offset:256
	v_pk_add_f32 v[22:23], v[22:23], 0 op_sel_hi:[1,0]
	v_pk_add_f32 v[16:17], v[16:17], 0 op_sel_hi:[1,0]
	v_pk_add_f32 v[42:43], v[36:37], 0 op_sel_hi:[1,0]
	v_pk_add_f32 v[36:37], v[34:35], 0 op_sel_hi:[1,0]
	s_nop 0
	v_cvt_pk_bf16_f32 v34, v38, v39
	s_nop 0
	v_cvt_pk_bf16_f32 v35, v40, v41
	v_pk_add_f32 v[14:15], v[14:15], 0 op_sel_hi:[1,0]
	s_nop 0
	v_cvt_pk_bf16_f32 v36, v36, v37
	s_nop 0
	v_cvt_pk_bf16_f32 v37, v42, v43
	global_store_dwordx4 v[102:103], v[34:37], off offset:256
	s_and_b64 vcc, exec, s[4:5]
	s_mov_b32 s37, s35
	v_pk_add_f32 v[34:35], v[28:29], 0 op_sel_hi:[1,0]
	v_pk_add_f32 v[28:29], v[26:27], 0 op_sel_hi:[1,0]
	s_nop 0
	v_cvt_pk_bf16_f32 v26, v30, v31
	s_nop 0
	v_cvt_pk_bf16_f32 v27, v32, v33
	s_mov_b32 s38, s36
	s_nop 0
	v_cvt_pk_bf16_f32 v28, v28, v29
	s_nop 0
	v_cvt_pk_bf16_f32 v29, v34, v35
	global_store_dwordx4 v[94:95], v[26:29], off offset:256
	s_mov_b64 s[14:15], s[8:9]
	s_mov_b64 s[12:13], s[6:7]
	v_pk_add_f32 v[26:27], v[20:21], 0 op_sel_hi:[1,0]
	v_pk_add_f32 v[20:21], v[18:19], 0 op_sel_hi:[1,0]
	s_nop 0
	v_cvt_pk_bf16_f32 v18, v22, v23
	s_nop 0
	v_cvt_pk_bf16_f32 v19, v24, v25
	v_pk_add_f32 v[8:9], v[8:9], 0 op_sel_hi:[1,0]
	s_nop 0
	v_cvt_pk_bf16_f32 v20, v20, v21
	s_nop 0
	v_cvt_pk_bf16_f32 v21, v26, v27
	global_store_dwordx4 v[86:87], v[18:21], off offset:256
	v_pk_add_f32 v[6:7], v[6:7], 0 op_sel_hi:[1,0]
	s_nop 0
	v_pk_add_f32 v[18:19], v[12:13], 0 op_sel_hi:[1,0]
	v_pk_add_f32 v[12:13], v[10:11], 0 op_sel_hi:[1,0]
	s_nop 0
	v_cvt_pk_bf16_f32 v10, v14, v15
	s_nop 0
	v_cvt_pk_bf16_f32 v11, v16, v17
	s_nop 0
	s_nop 0
	v_cvt_pk_bf16_f32 v12, v12, v13
	s_nop 0
	v_cvt_pk_bf16_f32 v13, v18, v19
	global_store_dwordx4 v[78:79], v[10:13], off offset:256
	s_nop 1
	v_pk_add_f32 v[10:11], v[2:3], 0 op_sel_hi:[1,0]
	v_pk_add_f32 v[2:3], v[0:1], 0 op_sel_hi:[1,0]
	s_nop 0
	v_cvt_pk_bf16_f32 v0, v6, v7
	s_nop 0
	v_cvt_pk_bf16_f32 v1, v8, v9
	s_nop 0
	s_nop 0
	v_cvt_pk_bf16_f32 v2, v2, v3
	s_nop 0
	v_cvt_pk_bf16_f32 v3, v10, v11
	global_store_dwordx4 v[62:63], v[0:3], off offset:256
	s_cbranch_vccz .LBB0_2396
	s_waitcnt vmcnt(0)
	s_cmpk_gt_u32 s20, 0xff
	s_cbranch_scc1 .LBB0_2407
	s_barrier

; #define PG8_STAGE(bufoff, gbase, voff) do { _Pragma("unroll") for (int _i = 0; _i < 2; ++_i) \
;         __builtin_amdgcn_global_load_lds((const unsigned*)((const char*)(gbase) + (voff)[_i]), (LAS unsigned*)(lds + (bufoff) + ldsw + _i * 8192), 16, 0, 0); } while (0)
; #define PG8_LDA(dst, b, h) do { _Pragma("unroll") for (int m = 0; m < 4; ++m) _Pragma("unroll") for (int k = 0; k < 2; ++k) dst[m][k] = *(const LAS bf16x8*)(lds + PG8_SA(b, h) + aoff + m * 2048 + k * 1024); } while (0)
; #define PG8_LDB(dst, b, h) do { _Pragma("unroll") for (int n = 0; n < 2; ++n) _Pragma("unroll") for (int k = 0; k < 2; ++k) dst[n][k] = *(const LAS bf16x8*)(lds + PG8_SB(b, h) + boff + n * 2048 + k * 1024); } while (0)
; #define PG8_MMA(ai, bj, At, Bt) do { __builtin_amdgcn_s_setprio(1); _Pragma("unroll") for (int m = 0; m < 4; ++m) _Pragma("unroll") for (int n = 0; n < 2; ++n) _Pragma("unroll") for (int k = 0; k < 2; ++k) \
;         acc[ai][bj][m][n] = __builtin_amdgcn_mfma_f32_16x16x32_bf16(Bt[n][k], At[m][k], acc[ai][bj][m][n], 0, 0, 0); __builtin_amdgcn_s_setprio(0); } while (0)
; #define PG8_WAIT_L(n) asm volatile("s_waitcnt lgkmcnt(" #n ")" ::: "memory")
; #define PG8_BAR __builtin_amdgcn_s_barrier()
; #define PG8_SCHED __builtin_amdgcn_sched_barrier(0)
; template <class Epi>
; __device__ __forceinline__ void gemm_phase(LAS unsigned char* lds, const Gemm g, const StaticOrder& S, const Epi& E) {
;     ...
;         for (int t = 0; t < nt; t += 2) {
;             const bool last = (t == nt - 2);
;             const char* a1 = cA + (size_t)(t + 1) * kstep;
;             const char* a2 = last ? nA : cA + (size_t)(t + 2) * kstep; const char* b2 = last ? nB : cB + (size_t)(t + 2) * kstep;
;             const char* a3 = a2 + kstep; const char* b3 = b2 + kstep;
;             PG8_LDB(B0, 0, 0); PG8_SCHED; PG8_LDA(At, 0, 0); PG8_STAGE(PG8_SA(1, 1), a1 + hstep, voffA);
;             PG8_WAIT_L(8); PG8_BAR; PG8_WAIT_L(0); PG8_MMA(0, 0, At, B0); PG8_BAR; PG8_SCHED;
;             PG8_LDB(B1, 0, 1); PG8_STAGE(PG8_SB(0, 0), b2, voffB);
;             PG8_BAR; PG8_WAIT_L(0); PG8_MMA(0, 1, At, B1); PG8_BAR;
;             PG8_LDA(At, 0, 1); PG8_STAGE(PG8_SA(0, 0), a2, voffA);
;             PG8_BAR; PG8_WAIT_L(0); PG8_MMA(1, 0, At, B0); PG8_BAR; PG8_SCHED;
.LBB0_2732:
	s_add_u32 s0, s16, 0xfffe0080
	s_addc_u32 s1, s17, -1
	s_add_i32 s48, 0, 0x10000
	v_add_u32_e32 v156, s48, v141
	ds_read_b128 v[144:147], v156
	ds_read_b128 v[148:151], v156 offset:1024
	ds_read_b128 v[152:155], v156 offset:2048
	ds_read_b128 v[156:159], v156 offset:3072
	s_cmp_eq_u32 s43, 4
	s_cselect_b32 s21, s11, s1
	s_cselect_b32 s20, s39, s0
	s_cselect_b32 s19, s9, s42
	s_cselect_b32 s18, s40, s41
	v_lshl_add_u64 v[176:177], s[16:17], 0, v[136:137]
	s_add_i32 m0, s28, 0xc000
	ds_read_b128 v[160:163], v143
	ds_read_b128 v[164:167], v143 offset:1024
	ds_read_b128 v[168:171], v143 offset:2048
	ds_read_b128 v[172:175], v143 offset:3072
	ds_read_b128 v[190:193], v143 offset:4096
	ds_read_b128 v[194:197], v143 offset:5120
	ds_read_b128 v[198:201], v143 offset:6144
	ds_read_b128 v[202:205], v143 offset:7168
	global_load_lds_dwordx4 v[176:177], off
	v_lshl_add_u64 v[176:177], s[16:17], 0, v[138:139]
	s_add_i32 m0, s28, 0xe000
	s_nop 0
	global_load_lds_dwordx4 v[176:177], off
	s_waitcnt lgkmcnt(8)
	s_barrier
	s_waitcnt lgkmcnt(0)
	v_mfma_f32_16x16x32_bf16 v[126:129], v[144:147], v[160:163], v[126:129]
	v_mfma_f32_16x16x32_bf16 v[122:125], v[152:155], v[160:163], v[122:125]
	v_mfma_f32_16x16x32_bf16 v[118:121], v[144:147], v[168:171], v[118:121]
	v_mfma_f32_16x16x32_bf16 v[114:117], v[152:155], v[168:171], v[114:117]
	v_mfma_f32_16x16x32_bf16 v[110:113], v[144:147], v[190:193], v[110:113]
	v_mfma_f32_16x16x32_bf16 v[106:109], v[152:155], v[190:193], v[106:109]
	v_mfma_f32_16x16x32_bf16 v[102:105], v[144:147], v[198:201], v[102:105]
	v_mfma_f32_16x16x32_bf16 v[98:101], v[152:155], v[198:201], v[98:101]
	v_mfma_f32_16x16x32_bf16 v[126:129], v[148:151], v[164:167], v[126:129]
	v_mfma_f32_16x16x32_bf16 v[122:125], v[156:159], v[164:167], v[122:125]
	v_mfma_f32_16x16x32_bf16 v[118:121], v[148:151], v[172:175], v[118:121]
	v_mfma_f32_16x16x32_bf16 v[114:117], v[156:159], v[172:175], v[114:117]
	v_mfma_f32_16x16x32_bf16 v[110:113], v[148:151], v[194:197], v[110:113]
	v_mfma_f32_16x16x32_bf16 v[106:109], v[156:159], v[194:197], v[106:109]
	v_mfma_f32_16x16x32_bf16 v[102:105], v[148:151], v[202:205], v[102:105]
	v_mfma_f32_16x16x32_bf16 v[98:101], v[156:159], v[202:205], v[98:101]
	s_barrier
	s_add_i32 s49, 0, 0x14000
	v_add_u32_e32 v176, s49, v141
	s_add_i32 s0, s48, s27
	ds_read_b128 v[206:209], v176
	ds_read_b128 v[210:213], v176 offset:1024
	ds_read_b128 v[214:217], v176 offset:2048
	ds_read_b128 v[218:221], v176 offset:3072
	v_lshl_add_u64 v[176:177], s[18:19], 0, v[4:5]
	s_mov_b32 m0, s0
	v_lshl_add_u64 v[186:187], s[18:19], 0, v[130:131]
	global_load_lds_dwordx4 v[176:177], off
	s_add_i32 m0, s0, 0x2000
	s_nop 0
	global_load_lds_dwordx4 v[186:187], off
	s_barrier
	s_waitcnt lgkmcnt(0)
	v_mfma_f32_16x16x32_bf16 v[70:73], v[206:209], v[160:163], v[70:73]
	v_mfma_f32_16x16x32_bf16 v[66:69], v[214:217], v[160:163], v[66:69]
	v_mfma_f32_16x16x32_bf16 v[54:57], v[206:209], v[168:171], v[54:57]
	v_mfma_f32_16x16x32_bf16 v[50:53], v[214:217], v[168:171], v[50:53]
	v_mfma_f32_16x16x32_bf16 v[46:49], v[206:209], v[190:193], v[46:49]
	v_mfma_f32_16x16x32_bf16 v[42:45], v[214:217], v[190:193], v[42:45]
	v_mfma_f32_16x16x32_bf16 v[38:41], v[206:209], v[198:201], v[38:41]
	v_mfma_f32_16x16x32_bf16 v[34:37], v[214:217], v[198:201], v[34:37]
	v_mfma_f32_16x16x32_bf16 v[70:73], v[210:213], v[164:167], v[70:73]
	v_mfma_f32_16x16x32_bf16 v[66:69], v[218:221], v[164:167], v[66:69]
	v_mfma_f32_16x16x32_bf16 v[54:57], v[210:213], v[172:175], v[54:57]
	v_mfma_f32_16x16x32_bf16 v[50:53], v[218:221], v[172:175], v[50:53]
	v_mfma_f32_16x16x32_bf16 v[46:49], v[210:213], v[194:197], v[46:49]
	v_mfma_f32_16x16x32_bf16 v[42:45], v[218:221], v[194:197], v[42:45]
	v_mfma_f32_16x16x32_bf16 v[38:41], v[210:213], v[202:205], v[38:41]
	v_mfma_f32_16x16x32_bf16 v[34:37], v[218:221], v[202:205], v[34:37]
	s_mov_b32 m0, s28
	v_lshl_add_u64 v[222:223], s[20:21], 0, v[134:135]
	s_barrier
	ds_read_b128 v[160:163], v143 offset:16384
	ds_read_b128 v[164:167], v143 offset:17408
	ds_read_b128 v[168:171], v143 offset:18432
	ds_read_b128 v[172:175], v143 offset:19456
	ds_read_b128 v[190:193], v143 offset:20480
	ds_read_b128 v[194:197], v143 offset:21504
	ds_read_b128 v[198:201], v143 offset:22528
	ds_read_b128 v[202:205], v143 offset:23552
	global_load_lds_dwordx4 v[222:223], off
	v_lshl_add_u64 v[224:225], s[20:21], 0, v[132:133]
	s_mov_b32 m0, s29
	s_nop 0
	global_load_lds_dwordx4 v[224:225], off
	s_barrier
	s_waitcnt lgkmcnt(0)
	v_mfma_f32_16x16x32_bf16 v[94:97], v[144:147], v[160:163], v[94:97]
	v_mfma_f32_16x16x32_bf16 v[90:93], v[152:155], v[160:163], v[90:93]
	v_mfma_f32_16x16x32_bf16 v[86:89], v[144:147], v[168:171], v[86:89]
	v_mfma_f32_16x16x32_bf16 v[82:85], v[152:155], v[168:171], v[82:85]
	v_mfma_f32_16x16x32_bf16 v[78:81], v[144:147], v[190:193], v[78:81]
	v_mfma_f32_16x16x32_bf16 v[74:77], v[152:155], v[190:193], v[74:77]
	v_mfma_f32_16x16x32_bf16 v[62:65], v[144:147], v[198:201], v[62:65]
	v_mfma_f32_16x16x32_bf16 v[58:61], v[152:155], v[198:201], v[58:61]
	v_mfma_f32_16x16x32_bf16 v[94:97], v[148:151], v[164:167], v[94:97]
	v_mfma_f32_16x16x32_bf16 v[90:93], v[156:159], v[164:167], v[90:93]
	v_mfma_f32_16x16x32_bf16 v[86:89], v[148:151], v[172:175], v[86:89]
	v_mfma_f32_16x16x32_bf16 v[82:85], v[156:159], v[172:175], v[82:85]
	v_mfma_f32_16x16x32_bf16 v[78:81], v[148:151], v[194:197], v[78:81]
	v_mfma_f32_16x16x32_bf16 v[74:77], v[156:159], v[194:197], v[74:77]
	v_mfma_f32_16x16x32_bf16 v[62:65], v[148:151], v[202:205], v[62:65]
	v_mfma_f32_16x16x32_bf16 v[58:61], v[156:159], v[202:205], v[58:61]
	s_barrier
; #define PG8_STAGE(bufoff, gbase, voff) do { _Pragma("unroll") for (int _i = 0; _i < 2; ++_i) \
;         __builtin_amdgcn_global_load_lds((const unsigned*)((const char*)(gbase) + (voff)[_i]), (LAS unsigned*)(lds + (bufoff) + ldsw + _i * 8192), 16, 0, 0); } while (0)
; #define PG8_LDA(dst, b, h) do { _Pragma("unroll") for (int m = 0; m < 4; ++m) _Pragma("unroll") for (int k = 0; k < 2; ++k) dst[m][k] = *(const LAS bf16x8*)(lds + PG8_SA(b, h) + aoff + m * 2048 + k * 1024); } while (0)
; #define PG8_LDB(dst, b, h) do { _Pragma("unroll") for (int n = 0; n < 2; ++n) _Pragma("unroll") for (int k = 0; k < 2; ++k) dst[n][k] = *(const LAS bf16x8*)(lds + PG8_SB(b, h) + boff + n * 2048 + k * 1024); } while (0)
; #define PG8_MMA(ai, bj, At, Bt) do { __builtin_amdgcn_s_setprio(1); _Pragma("unroll") for (int m = 0; m < 4; ++m) _Pragma("unroll") for (int n = 0; n < 2; ++n) _Pragma("unroll") for (int k = 0; k < 2; ++k) \
;         acc[ai][bj][m][n] = __builtin_amdgcn_mfma_f32_16x16x32_bf16(Bt[n][k], At[m][k], acc[ai][bj][m][n], 0, 0, 0); __builtin_amdgcn_s_setprio(0); } while (0)
; #define PG8_WAIT_V(n) asm volatile("s_waitcnt vmcnt(" #n ")" ::: "memory")
; #define PG8_WAIT_L(n) asm volatile("s_waitcnt lgkmcnt(" #n ")" ::: "memory")
; #define PG8_BAR __builtin_amdgcn_s_barrier()
; #define PG8_SCHED __builtin_amdgcn_sched_barrier(0)
; template <class Epi>
; __device__ __forceinline__ void gemm_phase(LAS unsigned char* lds, const Gemm g, const StaticOrder& S, const Epi& E) {
;     ...
;             PG8_STAGE(PG8_SB(0, 1), b2 + hstep, voffB);
;             PG8_WAIT_V(6); PG8_BAR; PG8_MMA(1, 1, At, B1); PG8_BAR;
;             PG8_LDB(B0, 1, 0); PG8_SCHED; PG8_LDA(At, 1, 0); PG8_STAGE(PG8_SA(0, 1), a2 + hstep, voffA);
;             PG8_WAIT_L(8); PG8_BAR; PG8_WAIT_L(0); PG8_MMA(0, 0, At, B0); PG8_BAR; PG8_SCHED;
;             PG8_LDB(B1, 1, 1); PG8_STAGE(PG8_SB(1, 0), b3, voffB);
;             PG8_BAR; PG8_WAIT_L(0); PG8_MMA(0, 1, At, B1); PG8_BAR;
;             PG8_LDA(At, 1, 1); PG8_STAGE(PG8_SA(1, 0), a3, voffA);
	s_add_u32 s0, s18, 0x20000
	s_addc_u32 s1, s19, 0
	s_add_i32 s48, s49, s27
	v_lshl_add_u64 v[144:145], s[0:1], 0, v[4:5]
	s_mov_b32 m0, s48
	s_nop 0
	global_load_lds_dwordx4 v[144:145], off
	v_lshl_add_u64 v[144:145], s[0:1], 0, v[130:131]
	s_add_i32 m0, s48, 0x2000
	s_nop 0
	global_load_lds_dwordx4 v[144:145], off
	s_waitcnt vmcnt(6)
	s_barrier
	v_mfma_f32_16x16x32_bf16 v[30:33], v[206:209], v[160:163], v[30:33]
	v_mfma_f32_16x16x32_bf16 v[26:29], v[214:217], v[160:163], v[26:29]
	v_mfma_f32_16x16x32_bf16 v[22:25], v[206:209], v[168:171], v[22:25]
	v_mfma_f32_16x16x32_bf16 v[18:21], v[214:217], v[168:171], v[18:21]
	v_mfma_f32_16x16x32_bf16 v[14:17], v[206:209], v[190:193], v[14:17]
	v_mfma_f32_16x16x32_bf16 v[10:13], v[214:217], v[190:193], v[10:13]
	v_mfma_f32_16x16x32_bf16 v[6:9], v[206:209], v[198:201], v[6:9]
	v_mfma_f32_16x16x32_bf16 v[0:3], v[214:217], v[198:201], v[0:3]
	v_mfma_f32_16x16x32_bf16 v[30:33], v[210:213], v[164:167], v[30:33]
	v_mfma_f32_16x16x32_bf16 v[26:29], v[218:221], v[164:167], v[26:29]
	v_mfma_f32_16x16x32_bf16 v[22:25], v[210:213], v[172:175], v[22:25]
	v_mfma_f32_16x16x32_bf16 v[18:21], v[218:221], v[172:175], v[18:21]
	v_mfma_f32_16x16x32_bf16 v[14:17], v[210:213], v[194:197], v[14:17]
	v_mfma_f32_16x16x32_bf16 v[10:13], v[218:221], v[194:197], v[10:13]
	v_mfma_f32_16x16x32_bf16 v[6:9], v[210:213], v[202:205], v[6:9]
	v_mfma_f32_16x16x32_bf16 v[0:3], v[218:221], v[202:205], v[0:3]
	s_add_i32 s48, 0, 0x18000
	v_add_u32_e32 v156, s48, v141
	s_barrier
	ds_read_b128 v[144:147], v156
	ds_read_b128 v[148:151], v156 offset:1024
	ds_read_b128 v[152:155], v156 offset:2048
	ds_read_b128 v[156:159], v156 offset:3072
	s_add_u32 s0, s20, 0x20000
	s_addc_u32 s1, s21, 0
	s_mov_b32 m0, s30
	v_lshl_add_u64 v[206:207], s[0:1], 0, v[134:135]
	ds_read_b128 v[160:163], v143 offset:32768
	ds_read_b128 v[164:167], v143 offset:33792
	ds_read_b128 v[168:171], v143 offset:34816
	ds_read_b128 v[172:175], v143 offset:35840
	ds_read_b128 v[190:193], v143 offset:36864
	ds_read_b128 v[194:197], v143 offset:37888
	ds_read_b128 v[198:201], v143 offset:38912
	ds_read_b128 v[202:205], v143 offset:39936
	global_load_lds_dwordx4 v[206:207], off
	v_lshl_add_u64 v[206:207], s[0:1], 0, v[132:133]
	s_mov_b32 m0, s31
	s_nop 0
	global_load_lds_dwordx4 v[206:207], off
	s_waitcnt lgkmcnt(8)
	s_barrier
	s_waitcnt lgkmcnt(0)
	v_mfma_f32_16x16x32_bf16 v[126:129], v[144:147], v[160:163], v[126:129]
	v_mfma_f32_16x16x32_bf16 v[122:125], v[152:155], v[160:163], v[122:125]
	v_mfma_f32_16x16x32_bf16 v[118:121], v[144:147], v[168:171], v[118:121]
	v_mfma_f32_16x16x32_bf16 v[114:117], v[152:155], v[168:171], v[114:117]
	v_mfma_f32_16x16x32_bf16 v[110:113], v[144:147], v[190:193], v[110:113]
	v_mfma_f32_16x16x32_bf16 v[106:109], v[152:155], v[190:193], v[106:109]
	v_mfma_f32_16x16x32_bf16 v[102:105], v[144:147], v[198:201], v[102:105]
	v_mfma_f32_16x16x32_bf16 v[98:101], v[152:155], v[198:201], v[98:101]
	v_mfma_f32_16x16x32_bf16 v[126:129], v[148:151], v[164:167], v[126:129]
	v_mfma_f32_16x16x32_bf16 v[122:125], v[156:159], v[164:167], v[122:125]
	v_mfma_f32_16x16x32_bf16 v[118:121], v[148:151], v[172:175], v[118:121]
	v_mfma_f32_16x16x32_bf16 v[114:117], v[156:159], v[172:175], v[114:117]
	v_mfma_f32_16x16x32_bf16 v[110:113], v[148:151], v[194:197], v[110:113]
	v_mfma_f32_16x16x32_bf16 v[106:109], v[156:159], v[194:197], v[106:109]
	v_mfma_f32_16x16x32_bf16 v[102:105], v[148:151], v[202:205], v[102:105]
	v_mfma_f32_16x16x32_bf16 v[98:101], v[156:159], v[202:205], v[98:101]
	s_barrier
	s_add_i32 s20, 0, 0x1c000
	s_add_i32 s0, s48, s27
	v_add_u32_e32 v218, s20, v141
	v_lshl_add_u64 v[176:177], v[176:177], 0, s[86:87]
	s_mov_b32 m0, s0
	ds_read_b128 v[206:209], v218
	ds_read_b128 v[210:213], v218 offset:1024
	ds_read_b128 v[214:217], v218 offset:2048
	ds_read_b128 v[218:221], v218 offset:3072
	global_load_lds_dwordx4 v[176:177], off
	v_lshl_add_u64 v[176:177], v[186:187], 0, s[86:87]
	s_add_i32 m0, s0, 0x2000
	s_nop 0
	global_load_lds_dwordx4 v[176:177], off
	s_barrier
	s_waitcnt lgkmcnt(0)
	v_mfma_f32_16x16x32_bf16 v[70:73], v[206:209], v[160:163], v[70:73]
	v_mfma_f32_16x16x32_bf16 v[66:69], v[214:217], v[160:163], v[66:69]
	v_mfma_f32_16x16x32_bf16 v[54:57], v[206:209], v[168:171], v[54:57]
	v_mfma_f32_16x16x32_bf16 v[50:53], v[214:217], v[168:171], v[50:53]
	v_mfma_f32_16x16x32_bf16 v[46:49], v[206:209], v[190:193], v[46:49]
	v_mfma_f32_16x16x32_bf16 v[42:45], v[214:217], v[190:193], v[42:45]
	v_mfma_f32_16x16x32_bf16 v[38:41], v[206:209], v[198:201], v[38:41]
	v_mfma_f32_16x16x32_bf16 v[34:37], v[214:217], v[198:201], v[34:37]
	v_mfma_f32_16x16x32_bf16 v[70:73], v[210:213], v[164:167], v[70:73]
	v_mfma_f32_16x16x32_bf16 v[66:69], v[218:221], v[164:167], v[66:69]
	v_mfma_f32_16x16x32_bf16 v[54:57], v[210:213], v[172:175], v[54:57]
	v_mfma_f32_16x16x32_bf16 v[50:53], v[218:221], v[172:175], v[50:53]
	v_mfma_f32_16x16x32_bf16 v[46:49], v[210:213], v[194:197], v[46:49]
	v_mfma_f32_16x16x32_bf16 v[42:45], v[218:221], v[194:197], v[42:45]
	v_mfma_f32_16x16x32_bf16 v[38:41], v[210:213], v[202:205], v[38:41]
	v_mfma_f32_16x16x32_bf16 v[34:37], v[218:221], v[202:205], v[34:37]
	s_mov_b32 m0, s34
	v_lshl_add_u64 v[176:177], v[222:223], 0, s[86:87]
	s_barrier
	ds_read_b128 v[160:163], v143 offset:49152
	ds_read_b128 v[164:167], v143 offset:50176
	ds_read_b128 v[168:171], v143 offset:51200
	ds_read_b128 v[172:175], v143 offset:52224
	ds_read_b128 v[190:193], v143 offset:53248
	ds_read_b128 v[194:197], v143 offset:54272
	ds_read_b128 v[198:201], v143 offset:55296
	ds_read_b128 v[202:205], v143 offset:56320
	global_load_lds_dwordx4 v[176:177], off
	v_lshl_add_u64 v[176:177], v[224:225], 0, s[86:87]
	s_mov_b32 m0, s35
	s_nop 0
	global_load_lds_dwordx4 v[176:177], off
	s_barrier
; __device__ __forceinline__ unsigned cvt_pk_bf16(float lo, float hi) { unsigned r; asm volatile("s_nop 0\n\tv_cvt_pk_bf16_f32 %0, %1, %2" : "=v"(r) : "v"(lo), "v"(hi)); return r; }
; #define PG8_STAGE(bufoff, gbase, voff) do { _Pragma("unroll") for (int _i = 0; _i < 2; ++_i) \
;         __builtin_amdgcn_global_load_lds((const unsigned*)((const char*)(gbase) + (voff)[_i]), (LAS unsigned*)(lds + (bufoff) + ldsw + _i * 8192), 16, 0, 0); } while (0)
; #define PG8_MMA(ai, bj, At, Bt) do { __builtin_amdgcn_s_setprio(1); _Pragma("unroll") for (int m = 0; m < 4; ++m) _Pragma("unroll") for (int n = 0; n < 2; ++n) _Pragma("unroll") for (int k = 0; k < 2; ++k) \
;         acc[ai][bj][m][n] = __builtin_amdgcn_mfma_f32_16x16x32_bf16(Bt[n][k], At[m][k], acc[ai][bj][m][n], 0, 0, 0); __builtin_amdgcn_s_setprio(0); } while (0)
; #define PG8_WAIT_V(n) asm volatile("s_waitcnt vmcnt(" #n ")" ::: "memory")
; #define PG8_WAIT_L(n) asm volatile("s_waitcnt lgkmcnt(" #n ")" ::: "memory")
; #define PG8_BAR __builtin_amdgcn_s_barrier()
; #define PG8_SCHED __builtin_amdgcn_sched_barrier(0)
; template <class Epi>
; __device__ __forceinline__ void gemm_phase(LAS unsigned char* lds, const Gemm g, const StaticOrder& S, const Epi& E) {
;     ...
;             PG8_BAR; PG8_WAIT_L(0); PG8_MMA(1, 0, At, B0); PG8_BAR; PG8_SCHED;
;             PG8_STAGE(PG8_SB(1, 1), b3 + hstep, voffB);
;             PG8_WAIT_V(6); PG8_BAR; PG8_MMA(1, 1, At, B1); PG8_BAR;
;         }
;         E(acc, cur, wr, wc, fr, fq);
;     __device__ __forceinline__ void operator()(const f32x4 (&acc)[2][2][4][2], const Unit& u, int wr, int wc, int fr, int fq) const {
;     ...
;         for (int bj = 0; bj < 2; ++bj) {
;             const f32x4 s0 = swv[2 * bj], s1 = swv[2 * bj + 1];
; #pragma unroll
;             for (int ai = 0; ai < 2; ++ai)
; #pragma unroll
;                 for (int m = 0; m < 4; ++m) { const int r = row0 + ai * 128 + m * 16;
;                     const float rstd = ai ? rb[m] : ra[m];
;                     const f32x4 v0 = acc[ai][bj][m][0] * rstd + s0, v1 = acc[ai][bj][m][1] * rstd + s1;
;                     uint4 st; st.x = cvt_pk_bf16(v0[0], v0[1]); st.y = cvt_pk_bf16(v0[2], v0[3]); st.z = cvt_pk_bf16(v1[0], v1[1]); st.w = cvt_pk_bf16(v1[2], v1[3]);
;                     *(uint4*)(O + (size_t)r * ldc + col0 + bj * 128) = st; }
	s_waitcnt lgkmcnt(0)
	v_mfma_f32_16x16x32_bf16 v[94:97], v[144:147], v[160:163], v[94:97]
	v_mfma_f32_16x16x32_bf16 v[90:93], v[152:155], v[160:163], v[90:93]
	v_mfma_f32_16x16x32_bf16 v[86:89], v[144:147], v[168:171], v[86:89]
	v_mfma_f32_16x16x32_bf16 v[82:85], v[152:155], v[168:171], v[82:85]
	v_mfma_f32_16x16x32_bf16 v[78:81], v[144:147], v[190:193], v[78:81]
	v_mfma_f32_16x16x32_bf16 v[74:77], v[152:155], v[190:193], v[74:77]
	v_mfma_f32_16x16x32_bf16 v[62:65], v[144:147], v[198:201], v[62:65]
	v_mfma_f32_16x16x32_bf16 v[58:61], v[152:155], v[198:201], v[58:61]
	v_mfma_f32_16x16x32_bf16 v[94:97], v[148:151], v[164:167], v[94:97]
	v_mfma_f32_16x16x32_bf16 v[90:93], v[156:159], v[164:167], v[90:93]
	v_mfma_f32_16x16x32_bf16 v[86:89], v[148:151], v[172:175], v[86:89]
	v_mfma_f32_16x16x32_bf16 v[82:85], v[156:159], v[172:175], v[82:85]
	v_mfma_f32_16x16x32_bf16 v[78:81], v[148:151], v[194:197], v[78:81]
	v_mfma_f32_16x16x32_bf16 v[74:77], v[156:159], v[194:197], v[74:77]
	v_mfma_f32_16x16x32_bf16 v[62:65], v[148:151], v[202:205], v[62:65]
	v_mfma_f32_16x16x32_bf16 v[58:61], v[156:159], v[202:205], v[58:61]
	s_barrier
	s_add_u32 s0, s18, 0x20080
	s_addc_u32 s1, s19, 0
	s_add_i32 s18, s20, s27
	v_lshl_add_u64 v[144:145], s[0:1], 0, v[4:5]
	s_mov_b32 m0, s18
	s_nop 0
	global_load_lds_dwordx4 v[144:145], off
	v_lshl_add_u64 v[144:145], s[0:1], 0, v[130:131]
	s_add_i32 m0, s18, 0x2000
	s_nop 0
	global_load_lds_dwordx4 v[144:145], off
	s_waitcnt vmcnt(6)
	s_barrier
	v_mfma_f32_16x16x32_bf16 v[30:33], v[206:209], v[160:163], v[30:33]
	v_mfma_f32_16x16x32_bf16 v[26:29], v[214:217], v[160:163], v[26:29]
	v_mfma_f32_16x16x32_bf16 v[22:25], v[206:209], v[168:171], v[22:25]
	v_mfma_f32_16x16x32_bf16 v[18:21], v[214:217], v[168:171], v[18:21]
	v_mfma_f32_16x16x32_bf16 v[14:17], v[206:209], v[190:193], v[14:17]
	v_mfma_f32_16x16x32_bf16 v[10:13], v[214:217], v[190:193], v[10:13]
	v_mfma_f32_16x16x32_bf16 v[6:9], v[206:209], v[198:201], v[6:9]
	v_mfma_f32_16x16x32_bf16 v[0:3], v[214:217], v[198:201], v[0:3]
	v_mfma_f32_16x16x32_bf16 v[30:33], v[210:213], v[164:167], v[30:33]
	v_mfma_f32_16x16x32_bf16 v[26:29], v[218:221], v[164:167], v[26:29]
	v_mfma_f32_16x16x32_bf16 v[22:25], v[210:213], v[172:175], v[22:25]
	v_mfma_f32_16x16x32_bf16 v[18:21], v[218:221], v[172:175], v[18:21]
	v_mfma_f32_16x16x32_bf16 v[14:17], v[210:213], v[194:197], v[14:17]
	v_mfma_f32_16x16x32_bf16 v[10:13], v[218:221], v[194:197], v[10:13]
	v_mfma_f32_16x16x32_bf16 v[6:9], v[210:213], v[202:205], v[6:9]
	v_mfma_f32_16x16x32_bf16 v[0:3], v[218:221], v[202:205], v[0:3]
	s_add_i32 s43, s43, 2
	s_add_u32 s16, s16, 0x100
	s_addc_u32 s17, s17, 0
	s_add_u32 s41, s41, 0x100
	s_addc_u32 s42, s42, 0
	s_cmp_gt_u32 s43, 5
	s_barrier
	s_cbranch_scc0 .LBB0_2732
	v_lshl_add_u32 v144, s38, 8, v140
	v_lshl_or_b32 v146, s37, 8, v142
	v_ashrrev_i32_e32 v145, 31, v144
	v_pk_add_f32 v[126:127], v[126:127], 0 op_sel_hi:[1,0]
	v_ashrrev_i32_e32 v147, 31, v146
	v_pk_add_f32 v[128:129], v[128:129], 0 op_sel_hi:[1,0]
	v_pk_add_f32 v[148:149], v[124:125], 0 op_sel_hi:[1,0]
	v_pk_add_f32 v[124:125], v[122:123], 0 op_sel_hi:[1,0]
	s_nop 0
	v_cvt_pk_bf16_f32 v122, v126, v127
	v_lshlrev_b64 v[126:127], 11, v[144:145]
	s_nop 0
	v_cvt_pk_bf16_f32 v123, v128, v129
	v_lshl_add_u64 v[126:127], s[6:7], 0, v[126:127]
	v_lshlrev_b64 v[128:129], 1, v[146:147]
	v_lshl_add_u64 v[126:127], v[126:127], 0, v[128:129]
	s_nop 0
	v_cvt_pk_bf16_f32 v124, v124, v125
	s_nop 0
	v_cvt_pk_bf16_f32 v125, v148, v149
	global_store_dwordx4 v[126:127], v[122:125], off
	v_pk_add_f32 v[118:119], v[118:119], 0 op_sel_hi:[1,0]
	v_pk_add_f32 v[120:121], v[120:121], 0 op_sel_hi:[1,0]
	v_or_b32_e32 v122, 16, v144
	v_ashrrev_i32_e32 v123, 31, v122
	v_pk_add_f32 v[124:125], v[116:117], 0 op_sel_hi:[1,0]
	v_pk_add_f32 v[116:117], v[114:115], 0 op_sel_hi:[1,0]
	s_nop 0
	v_cvt_pk_bf16_f32 v114, v118, v119
	v_lshlrev_b64 v[118:119], 11, v[122:123]
	v_lshl_add_u64 v[118:119], s[6:7], 0, v[118:119]
	v_lshl_add_u64 v[118:119], v[118:119], 0, v[128:129]
	s_nop 0
	v_cvt_pk_bf16_f32 v115, v120, v121
	s_nop 0
	v_cvt_pk_bf16_f32 v116, v116, v117
	s_nop 0
	v_cvt_pk_bf16_f32 v117, v124, v125
	global_store_dwordx4 v[118:119], v[114:117], off
	v_pk_add_f32 v[110:111], v[110:111], 0 op_sel_hi:[1,0]
	v_pk_add_f32 v[112:113], v[112:113], 0 op_sel_hi:[1,0]
	v_or_b32_e32 v114, 32, v144
	v_ashrrev_i32_e32 v115, 31, v114
	v_pk_add_f32 v[116:117], v[108:109], 0 op_sel_hi:[1,0]
	v_pk_add_f32 v[108:109], v[106:107], 0 op_sel_hi:[1,0]
	s_nop 0
	v_cvt_pk_bf16_f32 v106, v110, v111
	v_lshlrev_b64 v[110:111], 11, v[114:115]
	v_lshl_add_u64 v[110:111], s[6:7], 0, v[110:111]
	v_lshl_add_u64 v[110:111], v[110:111], 0, v[128:129]
	s_nop 0
	v_cvt_pk_bf16_f32 v107, v112, v113
	s_nop 0
	v_cvt_pk_bf16_f32 v108, v108, v109
	s_nop 0
	v_cvt_pk_bf16_f32 v109, v116, v117
	global_store_dwordx4 v[110:111], v[106:109], off
	v_pk_add_f32 v[102:103], v[102:103], 0 op_sel_hi:[1,0]
	v_pk_add_f32 v[104:105], v[104:105], 0 op_sel_hi:[1,0]
	v_or_b32_e32 v106, 48, v144
	v_ashrrev_i32_e32 v107, 31, v106
	v_pk_add_f32 v[108:109], v[100:101], 0 op_sel_hi:[1,0]
	v_pk_add_f32 v[100:101], v[98:99], 0 op_sel_hi:[1,0]
	s_nop 0
	v_cvt_pk_bf16_f32 v98, v102, v103
	v_lshlrev_b64 v[102:103], 11, v[106:107]
	v_lshl_add_u64 v[102:103], s[6:7], 0, v[102:103]
	s_nop 0
	v_cvt_pk_bf16_f32 v99, v104, v105
	v_lshl_add_u64 v[102:103], v[102:103], 0, v[128:129]
	v_pk_add_f32 v[96:97], v[96:97], 0 op_sel_hi:[1,0]
	s_nop 0
	v_cvt_pk_bf16_f32 v100, v100, v101
	s_nop 0
	v_cvt_pk_bf16_f32 v101, v108, v109
	global_store_dwordx4 v[102:103], v[98:101], off
	v_pk_add_f32 v[94:95], v[94:95], 0 op_sel_hi:[1,0]
	s_mov_b64 s[0:1], 0x40000
; __device__ __forceinline__ unsigned cvt_pk_bf16(float lo, float hi) { unsigned r; asm volatile("s_nop 0\n\tv_cvt_pk_bf16_f32 %0, %1, %2" : "=v"(r) : "v"(lo), "v"(hi)); return r; }
; #define PG8_WAIT_V(n) asm volatile("s_waitcnt vmcnt(" #n ")" ::: "memory")
; #define PG8_BAR __builtin_amdgcn_s_barrier()
; template <class Epi>
; __device__ __forceinline__ void gemm_phase(LAS unsigned char* lds, const Gemm g, const StaticOrder& S, const Epi& E) {
;     ...
;         if (!has_next) break;
; #pragma unroll
;         for (int a = 0; a < 2; ++a)
; #pragma unroll
;             for (int b = 0; b < 2; ++b)
; #pragma unroll
;                 for (int m = 0; m < 4; ++m)
; #pragma unroll
;                     for (int n = 0; n < 2; ++n) acc[a][b][m][n] = (f32x4){0.f, 0.f, 0.f, 0.f};
;         cur = nxt; cA = nA; cB = nB; ++ui;
;     }
;     PG8_WAIT_V(0);
;     if (wr == 0) PG8_BAR;
;     __device__ __forceinline__ void operator()(const f32x4 (&acc)[2][2][4][2], const Unit& u, int wr, int wc, int fr, int fq) const {
;     ...
;         for (int bj = 0; bj < 2; ++bj) {
;             const f32x4 s0 = swv[2 * bj], s1 = swv[2 * bj + 1];
; #pragma unroll
;             for (int ai = 0; ai < 2; ++ai)
; #pragma unroll
;                 for (int m = 0; m < 4; ++m) { const int r = row0 + ai * 128 + m * 16;
;                     const float rstd = ai ? rb[m] : ra[m];
;                     const f32x4 v0 = acc[ai][bj][m][0] * rstd + s0, v1 = acc[ai][bj][m][1] * rstd + s1;
;                     uint4 st; st.x = cvt_pk_bf16(v0[0], v0[1]); st.y = cvt_pk_bf16(v0[2], v0[3]); st.z = cvt_pk_bf16(v1[0], v1[1]); st.w = cvt_pk_bf16(v1[2], v1[3]);
;                     *(uint4*)(O + (size_t)r * ldc + col0 + bj * 128) = st; }
	v_pk_add_f32 v[98:99], v[92:93], 0 op_sel_hi:[1,0]
	v_pk_add_f32 v[92:93], v[90:91], 0 op_sel_hi:[1,0]
	s_nop 0
	v_cvt_pk_bf16_f32 v90, v94, v95
	s_nop 0
	v_cvt_pk_bf16_f32 v91, v96, v97
	v_add_co_u32_e32 v96, vcc, s85, v126
	v_lshl_add_u64 v[94:95], v[126:127], 0, s[0:1]
	s_nop 0
	v_addc_co_u32_e32 v97, vcc, 0, v127, vcc
	v_pk_add_f32 v[86:87], v[86:87], 0 op_sel_hi:[1,0]
	s_mov_b64 s[0:1], 0x48000
	s_nop 0
	v_cvt_pk_bf16_f32 v92, v92, v93
	s_nop 0
	v_cvt_pk_bf16_f32 v93, v98, v99
	global_store_dwordx4 v[96:97], v[90:93], off
	v_pk_add_f32 v[88:89], v[88:89], 0 op_sel_hi:[1,0]
	v_pk_add_f32 v[78:79], v[78:79], 0 op_sel_hi:[1,0]
	v_pk_add_f32 v[90:91], v[84:85], 0 op_sel_hi:[1,0]
	v_pk_add_f32 v[84:85], v[82:83], 0 op_sel_hi:[1,0]
	s_nop 0
	v_cvt_pk_bf16_f32 v82, v86, v87
	v_lshl_add_u64 v[86:87], v[126:127], 0, s[0:1]
	s_mov_b32 s0, 0x48000
	s_nop 0
	v_cvt_pk_bf16_f32 v83, v88, v89
	v_add_co_u32_e32 v88, vcc, s0, v126
	s_mov_b64 s[0:1], 0x50000
	s_nop 0
	v_addc_co_u32_e32 v89, vcc, 0, v127, vcc
	s_nop 0
	v_cvt_pk_bf16_f32 v84, v84, v85
	s_nop 0
	v_cvt_pk_bf16_f32 v85, v90, v91
	global_store_dwordx4 v[88:89], v[82:85], off
	v_pk_add_f32 v[80:81], v[80:81], 0 op_sel_hi:[1,0]
	v_pk_add_f32 v[62:63], v[62:63], 0 op_sel_hi:[1,0]
	v_pk_add_f32 v[82:83], v[76:77], 0 op_sel_hi:[1,0]
	v_pk_add_f32 v[76:77], v[74:75], 0 op_sel_hi:[1,0]
	s_nop 0
	v_cvt_pk_bf16_f32 v74, v78, v79
	v_lshl_add_u64 v[78:79], v[126:127], 0, s[0:1]
	s_mov_b32 s0, 0x50000
	s_nop 0
	v_cvt_pk_bf16_f32 v75, v80, v81
	v_add_co_u32_e32 v80, vcc, s0, v126
	s_mov_b64 s[0:1], 0x58000
	s_nop 0
	v_addc_co_u32_e32 v81, vcc, 0, v127, vcc
	s_nop 0
	v_cvt_pk_bf16_f32 v76, v76, v77
	s_nop 0
	v_cvt_pk_bf16_f32 v77, v82, v83
	global_store_dwordx4 v[80:81], v[74:77], off
	v_pk_add_f32 v[64:65], v[64:65], 0 op_sel_hi:[1,0]
	v_pk_add_f32 v[66:67], v[66:67], 0 op_sel_hi:[1,0]
	v_pk_add_f32 v[74:75], v[60:61], 0 op_sel_hi:[1,0]
	v_pk_add_f32 v[60:61], v[58:59], 0 op_sel_hi:[1,0]
	s_nop 0
	v_cvt_pk_bf16_f32 v58, v62, v63
	v_lshl_add_u64 v[62:63], v[126:127], 0, s[0:1]
	s_mov_b32 s0, 0x58000
	s_nop 0
	v_cvt_pk_bf16_f32 v59, v64, v65
	v_add_co_u32_e32 v64, vcc, s0, v126
	s_nop 0
	v_cvt_pk_bf16_f32 v60, v60, v61
	s_nop 0
	v_cvt_pk_bf16_f32 v61, v74, v75
	v_pk_add_f32 v[56:57], v[56:57], 0 op_sel_hi:[1,0]
	s_nop 0
	v_addc_co_u32_e32 v65, vcc, 0, v127, vcc
	global_store_dwordx4 v[64:65], v[58:61], off
	v_pk_add_f32 v[64:65], v[68:69], 0 op_sel_hi:[1,0]
	v_pk_add_f32 v[54:55], v[54:55], 0 op_sel_hi:[1,0]
	v_pk_add_f32 v[58:59], v[70:71], 0 op_sel_hi:[1,0]
	v_pk_add_f32 v[60:61], v[72:73], 0 op_sel_hi:[1,0]
	s_nop 0
	v_cvt_pk_bf16_f32 v58, v58, v59
	v_pk_add_f32 v[48:49], v[48:49], 0 op_sel_hi:[1,0]
	s_nop 0
	v_cvt_pk_bf16_f32 v59, v60, v61
	s_nop 0
	v_cvt_pk_bf16_f32 v60, v66, v67
	s_nop 0
	v_cvt_pk_bf16_f32 v61, v64, v65
	global_store_dwordx4 v[126:127], v[58:61], off offset:256
	v_pk_add_f32 v[46:47], v[46:47], 0 op_sel_hi:[1,0]
	v_pk_add_f32 v[40:41], v[40:41], 0 op_sel_hi:[1,0]
	v_pk_add_f32 v[58:59], v[52:53], 0 op_sel_hi:[1,0]
	v_pk_add_f32 v[52:53], v[50:51], 0 op_sel_hi:[1,0]
	s_nop 0
	v_cvt_pk_bf16_f32 v50, v54, v55
	s_nop 0
	v_cvt_pk_bf16_f32 v51, v56, v57
	v_pk_add_f32 v[38:39], v[38:39], 0 op_sel_hi:[1,0]
	s_nop 0
	v_cvt_pk_bf16_f32 v52, v52, v53
	s_nop 0
	v_cvt_pk_bf16_f32 v53, v58, v59
	global_store_dwordx4 v[118:119], v[50:53], off offset:256
	v_pk_add_f32 v[32:33], v[32:33], 0 op_sel_hi:[1,0]
	v_pk_add_f32 v[30:31], v[30:31], 0 op_sel_hi:[1,0]
	v_pk_add_f32 v[50:51], v[44:45], 0 op_sel_hi:[1,0]
	v_pk_add_f32 v[44:45], v[42:43], 0 op_sel_hi:[1,0]
	s_nop 0
	v_cvt_pk_bf16_f32 v42, v46, v47
	s_nop 0
	v_cvt_pk_bf16_f32 v43, v48, v49
	v_pk_add_f32 v[24:25], v[24:25], 0 op_sel_hi:[1,0]
	s_nop 0
	v_cvt_pk_bf16_f32 v44, v44, v45
	s_nop 0
	v_cvt_pk_bf16_f32 v45, v50, v51
	global_store_dwordx4 v[110:111], v[42:45], off offset:256
	v_pk_add_f32 v[22:23], v[22:23], 0 op_sel_hi:[1,0]
	v_pk_add_f32 v[16:17], v[16:17], 0 op_sel_hi:[1,0]
	v_pk_add_f32 v[42:43], v[36:37], 0 op_sel_hi:[1,0]
	v_pk_add_f32 v[36:37], v[34:35], 0 op_sel_hi:[1,0]
	s_nop 0
	v_cvt_pk_bf16_f32 v34, v38, v39
	s_nop 0
	v_cvt_pk_bf16_f32 v35, v40, v41
	v_pk_add_f32 v[14:15], v[14:15], 0 op_sel_hi:[1,0]
	s_nop 0
	v_cvt_pk_bf16_f32 v36, v36, v37
	s_nop 0
	v_cvt_pk_bf16_f32 v37, v42, v43
	global_store_dwordx4 v[102:103], v[34:37], off offset:256
	s_and_b64 vcc, exec, s[4:5]
	s_mov_b32 s37, s8
	v_pk_add_f32 v[34:35], v[28:29], 0 op_sel_hi:[1,0]
	v_pk_add_f32 v[28:29], v[26:27], 0 op_sel_hi:[1,0]
	s_nop 0
	v_cvt_pk_bf16_f32 v26, v30, v31
	s_nop 0
	v_cvt_pk_bf16_f32 v27, v32, v33
	s_mov_b32 s38, s10
	s_nop 0
	v_cvt_pk_bf16_f32 v28, v28, v29
	s_nop 0
	v_cvt_pk_bf16_f32 v29, v34, v35
	global_store_dwordx4 v[94:95], v[26:29], off offset:256
	s_mov_b64 s[18:19], s[14:15]
	s_mov_b64 s[16:17], s[12:13]
	v_pk_add_f32 v[26:27], v[20:21], 0 op_sel_hi:[1,0]
	v_pk_add_f32 v[20:21], v[18:19], 0 op_sel_hi:[1,0]
	s_nop 0
	v_cvt_pk_bf16_f32 v18, v22, v23
	s_nop 0
	v_cvt_pk_bf16_f32 v19, v24, v25
	v_pk_add_f32 v[8:9], v[8:9], 0 op_sel_hi:[1,0]
	s_nop 0
	v_cvt_pk_bf16_f32 v20, v20, v21
	s_nop 0
	v_cvt_pk_bf16_f32 v21, v26, v27
	global_store_dwordx4 v[86:87], v[18:21], off offset:256
	v_pk_add_f32 v[6:7], v[6:7], 0 op_sel_hi:[1,0]
	s_nop 0
	v_pk_add_f32 v[18:19], v[12:13], 0 op_sel_hi:[1,0]
	v_pk_add_f32 v[12:13], v[10:11], 0 op_sel_hi:[1,0]
	s_nop 0
	v_cvt_pk_bf16_f32 v10, v14, v15
	s_nop 0
	v_cvt_pk_bf16_f32 v11, v16, v17
	s_nop 0
	s_nop 0
	v_cvt_pk_bf16_f32 v12, v12, v13
	s_nop 0
	v_cvt_pk_bf16_f32 v13, v18, v19
	global_store_dwordx4 v[78:79], v[10:13], off offset:256
	s_nop 1
	v_pk_add_f32 v[10:11], v[2:3], 0 op_sel_hi:[1,0]
	v_pk_add_f32 v[2:3], v[0:1], 0 op_sel_hi:[1,0]
	s_nop 0
	v_cvt_pk_bf16_f32 v0, v6, v7
	s_nop 0
	v_cvt_pk_bf16_f32 v1, v8, v9
	s_nop 0
	s_nop 0
	v_cvt_pk_bf16_f32 v2, v2, v3
	s_nop 0
	v_cvt_pk_bf16_f32 v3, v10, v11
	global_store_dwordx4 v[62:63], v[0:3], off offset:256
	s_cbranch_vccz .LBB0_2725
	s_waitcnt vmcnt(0)
	s_cmpk_gt_u32 s22, 0xff
	s_cbranch_scc1 .LBB0_2736
	s_barrier

; #define PG8_STAGE(bufoff, gbase, voff) do { _Pragma("unroll") for (int _i = 0; _i < 2; ++_i) \
;         __builtin_amdgcn_global_load_lds((const unsigned*)((const char*)(gbase) + (voff)[_i]), (LAS unsigned*)(lds + (bufoff) + ldsw + _i * 8192), 16, 0, 0); } while (0)
; #define PG8_LDA(dst, b, h) do { _Pragma("unroll") for (int m = 0; m < 4; ++m) _Pragma("unroll") for (int k = 0; k < 2; ++k) dst[m][k] = *(const LAS bf16x8*)(lds + PG8_SA(b, h) + aoff + m * 2048 + k * 1024); } while (0)
; #define PG8_LDB(dst, b, h) do { _Pragma("unroll") for (int n = 0; n < 2; ++n) _Pragma("unroll") for (int k = 0; k < 2; ++k) dst[n][k] = *(const LAS bf16x8*)(lds + PG8_SB(b, h) + boff + n * 2048 + k * 1024); } while (0)
; #define PG8_MMA(ai, bj, At, Bt) do { __builtin_amdgcn_s_setprio(1); _Pragma("unroll") for (int m = 0; m < 4; ++m) _Pragma("unroll") for (int n = 0; n < 2; ++n) _Pragma("unroll") for (int k = 0; k < 2; ++k) \
;         acc[ai][bj][m][n] = __builtin_amdgcn_mfma_f32_16x16x32_bf16(Bt[n][k], At[m][k], acc[ai][bj][m][n], 0, 0, 0); __builtin_amdgcn_s_setprio(0); } while (0)
; #define PG8_WAIT_L(n) asm volatile("s_waitcnt lgkmcnt(" #n ")" ::: "memory")
; #define PG8_BAR __builtin_amdgcn_s_barrier()
; #define PG8_SCHED __builtin_amdgcn_sched_barrier(0)
; template <class Epi>
; __device__ __forceinline__ void gemm_phase(LAS unsigned char* lds, const Gemm g, const StaticOrder& S, const Epi& E) {
;     ...
;         for (int t = 0; t < nt; t += 2) {
;             const bool last = (t == nt - 2);
;             const char* a1 = cA + (size_t)(t + 1) * kstep;
;             const char* a2 = last ? nA : cA + (size_t)(t + 2) * kstep; const char* b2 = last ? nB : cB + (size_t)(t + 2) * kstep;
;             const char* a3 = a2 + kstep; const char* b3 = b2 + kstep;
;             PG8_LDB(B0, 0, 0); PG8_SCHED; PG8_LDA(At, 0, 0); PG8_STAGE(PG8_SA(1, 1), a1 + hstep, voffA);
;             PG8_WAIT_L(8); PG8_BAR; PG8_WAIT_L(0); PG8_MMA(0, 0, At, B0); PG8_BAR; PG8_SCHED;
;             PG8_LDB(B1, 0, 1); PG8_STAGE(PG8_SB(0, 0), b2, voffB);
;             PG8_BAR; PG8_WAIT_L(0); PG8_MMA(0, 1, At, B1); PG8_BAR;
;             PG8_LDA(At, 0, 1); PG8_STAGE(PG8_SA(0, 0), a2, voffA);
;             PG8_BAR; PG8_WAIT_L(0); PG8_MMA(1, 0, At, B0); PG8_BAR; PG8_SCHED;
.LBB0_2801:
	s_add_u32 s0, s6, 0xfffc0080
	s_addc_u32 s1, s7, -1
	s_add_i32 s55, 0, 0x10000
	v_add_u32_e32 v130, s55, v243
	ds_read_b128 v[34:37], v130
	ds_read_b128 v[38:41], v130 offset:1024
	ds_read_b128 v[122:125], v130 offset:2048
	ds_read_b128 v[130:133], v130 offset:3072
	s_cmp_eq_u32 s54, 12
	s_cselect_b32 s25, s17, s1
	s_cselect_b32 s24, s49, s0
	s_cselect_b32 s23, s15, s52
	s_cselect_b32 s22, s50, s51
	v_lshl_add_u64 v[186:187], s[6:7], 0, v[196:197]
	s_add_i32 m0, s34, 0xc000
	ds_read_b128 v[146:149], v245
	ds_read_b128 v[150:153], v245 offset:1024
	ds_read_b128 v[154:157], v245 offset:2048
	ds_read_b128 v[158:161], v245 offset:3072
	ds_read_b128 v[162:165], v245 offset:4096
	ds_read_b128 v[166:169], v245 offset:5120
	ds_read_b128 v[170:173], v245 offset:6144
	ds_read_b128 v[174:177], v245 offset:7168
	global_load_lds_dwordx4 v[186:187], off
	v_lshl_add_u64 v[186:187], s[6:7], 0, v[198:199]
	s_add_i32 m0, s34, 0xe000
	s_nop 0
	global_load_lds_dwordx4 v[186:187], off
	s_waitcnt lgkmcnt(8)
	s_barrier
	s_waitcnt lgkmcnt(0)
	v_mfma_f32_16x16x32_bf16 v[142:145], v[34:37], v[146:149], v[142:145]
	v_mfma_f32_16x16x32_bf16 v[138:141], v[122:125], v[146:149], v[138:141]
	v_mfma_f32_16x16x32_bf16 v[134:137], v[34:37], v[154:157], v[134:137]
	v_mfma_f32_16x16x32_bf16 v[126:129], v[122:125], v[154:157], v[126:129]
	v_mfma_f32_16x16x32_bf16 v[118:121], v[34:37], v[162:165], v[118:121]
	v_mfma_f32_16x16x32_bf16 v[114:117], v[122:125], v[162:165], v[114:117]
	v_mfma_f32_16x16x32_bf16 v[110:113], v[34:37], v[170:173], v[110:113]
	v_mfma_f32_16x16x32_bf16 v[106:109], v[122:125], v[170:173], v[106:109]
	v_mfma_f32_16x16x32_bf16 v[142:145], v[38:41], v[150:153], v[142:145]
	v_mfma_f32_16x16x32_bf16 v[138:141], v[130:133], v[150:153], v[138:141]
	v_mfma_f32_16x16x32_bf16 v[134:137], v[38:41], v[158:161], v[134:137]
	v_mfma_f32_16x16x32_bf16 v[126:129], v[130:133], v[158:161], v[126:129]
	v_mfma_f32_16x16x32_bf16 v[118:121], v[38:41], v[166:169], v[118:121]
	v_mfma_f32_16x16x32_bf16 v[114:117], v[130:133], v[166:169], v[114:117]
	v_mfma_f32_16x16x32_bf16 v[110:113], v[38:41], v[174:177], v[110:113]
	v_mfma_f32_16x16x32_bf16 v[106:109], v[130:133], v[174:177], v[106:109]
	s_barrier
	s_add_i32 s56, 0, 0x14000
	v_add_u32_e32 v186, s56, v243
	s_add_i32 s0, s55, s31
	ds_read_b128 v[200:203], v186
	ds_read_b128 v[204:207], v186 offset:1024
	ds_read_b128 v[208:211], v186 offset:2048
	ds_read_b128 v[212:215], v186 offset:3072
	v_lshl_add_u64 v[186:187], s[22:23], 0, v[4:5]
	s_mov_b32 m0, s0
	v_lshl_add_u64 v[216:217], s[22:23], 0, v[190:191]
	global_load_lds_dwordx4 v[186:187], off
	s_add_i32 m0, s0, 0x2000
	s_nop 0
	global_load_lds_dwordx4 v[216:217], off
	s_barrier
	s_waitcnt lgkmcnt(0)
	v_mfma_f32_16x16x32_bf16 v[70:73], v[200:203], v[146:149], v[70:73]
	v_mfma_f32_16x16x32_bf16 v[66:69], v[208:211], v[146:149], v[66:69]
	v_mfma_f32_16x16x32_bf16 v[62:65], v[200:203], v[154:157], v[62:65]
	v_mfma_f32_16x16x32_bf16 v[58:61], v[208:211], v[154:157], v[58:61]
	v_mfma_f32_16x16x32_bf16 v[54:57], v[200:203], v[162:165], v[54:57]
	v_mfma_f32_16x16x32_bf16 v[50:53], v[208:211], v[162:165], v[50:53]
	v_mfma_f32_16x16x32_bf16 v[46:49], v[200:203], v[170:173], v[46:49]
	v_mfma_f32_16x16x32_bf16 v[42:45], v[208:211], v[170:173], v[42:45]
	v_mfma_f32_16x16x32_bf16 v[70:73], v[204:207], v[150:153], v[70:73]
	v_mfma_f32_16x16x32_bf16 v[66:69], v[212:215], v[150:153], v[66:69]
	v_mfma_f32_16x16x32_bf16 v[62:65], v[204:207], v[158:161], v[62:65]
	v_mfma_f32_16x16x32_bf16 v[58:61], v[212:215], v[158:161], v[58:61]
	v_mfma_f32_16x16x32_bf16 v[54:57], v[204:207], v[166:169], v[54:57]
	v_mfma_f32_16x16x32_bf16 v[50:53], v[212:215], v[166:169], v[50:53]
	v_mfma_f32_16x16x32_bf16 v[46:49], v[204:207], v[174:177], v[46:49]
	v_mfma_f32_16x16x32_bf16 v[42:45], v[212:215], v[174:177], v[42:45]
	s_mov_b32 m0, s34
	v_lshl_add_u64 v[218:219], s[24:25], 0, v[194:195]
	s_barrier
	ds_read_b128 v[146:149], v245 offset:16384
	ds_read_b128 v[150:153], v245 offset:17408
	ds_read_b128 v[154:157], v245 offset:18432
	ds_read_b128 v[158:161], v245 offset:19456
	ds_read_b128 v[162:165], v245 offset:20480
	ds_read_b128 v[166:169], v245 offset:21504
	ds_read_b128 v[170:173], v245 offset:22528
	ds_read_b128 v[174:177], v245 offset:23552
	global_load_lds_dwordx4 v[218:219], off
	v_lshl_add_u64 v[220:221], s[24:25], 0, v[192:193]
	s_mov_b32 m0, s35
	s_nop 0
	global_load_lds_dwordx4 v[220:221], off
	s_barrier
	s_waitcnt lgkmcnt(0)
	v_mfma_f32_16x16x32_bf16 v[102:105], v[34:37], v[146:149], v[102:105]
	v_mfma_f32_16x16x32_bf16 v[98:101], v[122:125], v[146:149], v[98:101]
	v_mfma_f32_16x16x32_bf16 v[94:97], v[34:37], v[154:157], v[94:97]
	v_mfma_f32_16x16x32_bf16 v[90:93], v[122:125], v[154:157], v[90:93]
	v_mfma_f32_16x16x32_bf16 v[86:89], v[34:37], v[162:165], v[86:89]
	v_mfma_f32_16x16x32_bf16 v[82:85], v[122:125], v[162:165], v[82:85]
	v_mfma_f32_16x16x32_bf16 v[34:37], v[34:37], v[170:173], v[78:81]
	v_mfma_f32_16x16x32_bf16 v[102:105], v[38:41], v[150:153], v[102:105]
	v_mfma_f32_16x16x32_bf16 v[98:101], v[130:133], v[150:153], v[98:101]
	v_mfma_f32_16x16x32_bf16 v[94:97], v[38:41], v[158:161], v[94:97]
	v_mfma_f32_16x16x32_bf16 v[90:93], v[130:133], v[158:161], v[90:93]
	v_mfma_f32_16x16x32_bf16 v[86:89], v[38:41], v[166:169], v[86:89]
	v_mfma_f32_16x16x32_bf16 v[82:85], v[130:133], v[166:169], v[82:85]
	v_mfma_f32_16x16x32_bf16 v[34:37], v[38:41], v[174:177], v[34:37]
	v_mfma_f32_16x16x32_bf16 v[38:41], v[122:125], v[170:173], v[74:77]
	v_mfma_f32_16x16x32_bf16 v[38:41], v[130:133], v[174:177], v[38:41]
	s_barrier
; #define PG8_STAGE(bufoff, gbase, voff) do { _Pragma("unroll") for (int _i = 0; _i < 2; ++_i) \
;         __builtin_amdgcn_global_load_lds((const unsigned*)((const char*)(gbase) + (voff)[_i]), (LAS unsigned*)(lds + (bufoff) + ldsw + _i * 8192), 16, 0, 0); } while (0)
; #define PG8_LDA(dst, b, h) do { _Pragma("unroll") for (int m = 0; m < 4; ++m) _Pragma("unroll") for (int k = 0; k < 2; ++k) dst[m][k] = *(const LAS bf16x8*)(lds + PG8_SA(b, h) + aoff + m * 2048 + k * 1024); } while (0)
; #define PG8_LDB(dst, b, h) do { _Pragma("unroll") for (int n = 0; n < 2; ++n) _Pragma("unroll") for (int k = 0; k < 2; ++k) dst[n][k] = *(const LAS bf16x8*)(lds + PG8_SB(b, h) + boff + n * 2048 + k * 1024); } while (0)
; #define PG8_MMA(ai, bj, At, Bt) do { __builtin_amdgcn_s_setprio(1); _Pragma("unroll") for (int m = 0; m < 4; ++m) _Pragma("unroll") for (int n = 0; n < 2; ++n) _Pragma("unroll") for (int k = 0; k < 2; ++k) \
;         acc[ai][bj][m][n] = __builtin_amdgcn_mfma_f32_16x16x32_bf16(Bt[n][k], At[m][k], acc[ai][bj][m][n], 0, 0, 0); __builtin_amdgcn_s_setprio(0); } while (0)
; #define PG8_WAIT_V(n) asm volatile("s_waitcnt vmcnt(" #n ")" ::: "memory")
; #define PG8_WAIT_L(n) asm volatile("s_waitcnt lgkmcnt(" #n ")" ::: "memory")
; #define PG8_BAR __builtin_amdgcn_s_barrier()
; #define PG8_SCHED __builtin_amdgcn_sched_barrier(0)
; template <class Epi>
; __device__ __forceinline__ void gemm_phase(LAS unsigned char* lds, const Gemm g, const StaticOrder& S, const Epi& E) {
;     ...
;             PG8_STAGE(PG8_SB(0, 1), b2 + hstep, voffB);
;             PG8_WAIT_V(6); PG8_BAR; PG8_MMA(1, 1, At, B1); PG8_BAR;
;             PG8_LDB(B0, 1, 0); PG8_SCHED; PG8_LDA(At, 1, 0); PG8_STAGE(PG8_SA(0, 1), a2 + hstep, voffA);
;             PG8_WAIT_L(8); PG8_BAR; PG8_WAIT_L(0); PG8_MMA(0, 0, At, B0); PG8_BAR; PG8_SCHED;
;             PG8_LDB(B1, 1, 1); PG8_STAGE(PG8_SB(1, 0), b3, voffB);
;             PG8_BAR; PG8_WAIT_L(0); PG8_MMA(0, 1, At, B1); PG8_BAR;
;             PG8_LDA(At, 1, 1); PG8_STAGE(PG8_SA(1, 0), a3, voffA);
;             PG8_BAR; PG8_WAIT_L(0); PG8_MMA(1, 0, At, B0); PG8_BAR; PG8_SCHED;
;             PG8_STAGE(PG8_SB(1, 1), b3 + hstep, voffB);
;             PG8_WAIT_V(6); PG8_BAR; PG8_MMA(1, 1, At, B1); PG8_BAR;
	s_add_u32 s0, s22, 0x40000
	s_addc_u32 s1, s23, 0
	s_add_i32 s55, s56, s31
	v_lshl_add_u64 v[74:75], s[0:1], 0, v[4:5]
	s_mov_b32 m0, s55
	s_nop 0
	global_load_lds_dwordx4 v[74:75], off
	v_lshl_add_u64 v[74:75], s[0:1], 0, v[190:191]
	s_add_i32 m0, s55, 0x2000
	s_nop 0
	global_load_lds_dwordx4 v[74:75], off
	s_waitcnt vmcnt(6)
	s_barrier
	v_mfma_f32_16x16x32_bf16 v[30:33], v[200:203], v[146:149], v[30:33]
	v_mfma_f32_16x16x32_bf16 v[26:29], v[208:211], v[146:149], v[26:29]
	v_mfma_f32_16x16x32_bf16 v[22:25], v[200:203], v[154:157], v[22:25]
	v_mfma_f32_16x16x32_bf16 v[18:21], v[208:211], v[154:157], v[18:21]
	v_mfma_f32_16x16x32_bf16 v[14:17], v[200:203], v[162:165], v[14:17]
	v_mfma_f32_16x16x32_bf16 v[10:13], v[208:211], v[162:165], v[10:13]
	v_mfma_f32_16x16x32_bf16 v[6:9], v[200:203], v[170:173], v[6:9]
	v_mfma_f32_16x16x32_bf16 v[0:3], v[208:211], v[170:173], v[0:3]
	v_mfma_f32_16x16x32_bf16 v[30:33], v[204:207], v[150:153], v[30:33]
	v_mfma_f32_16x16x32_bf16 v[26:29], v[212:215], v[150:153], v[26:29]
	v_mfma_f32_16x16x32_bf16 v[22:25], v[204:207], v[158:161], v[22:25]
	v_mfma_f32_16x16x32_bf16 v[18:21], v[212:215], v[158:161], v[18:21]
	v_mfma_f32_16x16x32_bf16 v[14:17], v[204:207], v[166:169], v[14:17]
	v_mfma_f32_16x16x32_bf16 v[10:13], v[212:215], v[166:169], v[10:13]
	v_mfma_f32_16x16x32_bf16 v[6:9], v[204:207], v[174:177], v[6:9]
	v_mfma_f32_16x16x32_bf16 v[0:3], v[212:215], v[174:177], v[0:3]
	s_add_i32 s55, 0, 0x18000
	v_add_u32_e32 v130, s55, v243
	s_barrier
	ds_read_b128 v[74:77], v130
	ds_read_b128 v[78:81], v130 offset:1024
	ds_read_b128 v[122:125], v130 offset:2048
	ds_read_b128 v[130:133], v130 offset:3072
	s_add_u32 s0, s24, 0x40000
	s_addc_u32 s1, s25, 0
	s_mov_b32 m0, s36
	v_lshl_add_u64 v[200:201], s[0:1], 0, v[194:195]
	ds_read_b128 v[146:149], v245 offset:32768
	ds_read_b128 v[150:153], v245 offset:33792
	ds_read_b128 v[154:157], v245 offset:34816
	ds_read_b128 v[158:161], v245 offset:35840
	ds_read_b128 v[162:165], v245 offset:36864
	ds_read_b128 v[166:169], v245 offset:37888
	ds_read_b128 v[170:173], v245 offset:38912
	ds_read_b128 v[174:177], v245 offset:39936
	global_load_lds_dwordx4 v[200:201], off
	v_lshl_add_u64 v[200:201], s[0:1], 0, v[192:193]
	s_mov_b32 m0, s37
	s_nop 0
	global_load_lds_dwordx4 v[200:201], off
	s_waitcnt lgkmcnt(8)
	s_barrier
	s_waitcnt lgkmcnt(0)
	v_mfma_f32_16x16x32_bf16 v[142:145], v[74:77], v[146:149], v[142:145]
	v_mfma_f32_16x16x32_bf16 v[138:141], v[122:125], v[146:149], v[138:141]
	v_mfma_f32_16x16x32_bf16 v[134:137], v[74:77], v[154:157], v[134:137]
	v_mfma_f32_16x16x32_bf16 v[126:129], v[122:125], v[154:157], v[126:129]
	v_mfma_f32_16x16x32_bf16 v[118:121], v[74:77], v[162:165], v[118:121]
	v_mfma_f32_16x16x32_bf16 v[114:117], v[122:125], v[162:165], v[114:117]
	v_mfma_f32_16x16x32_bf16 v[110:113], v[74:77], v[170:173], v[110:113]
	v_mfma_f32_16x16x32_bf16 v[106:109], v[122:125], v[170:173], v[106:109]
	v_mfma_f32_16x16x32_bf16 v[142:145], v[78:81], v[150:153], v[142:145]
	v_mfma_f32_16x16x32_bf16 v[138:141], v[130:133], v[150:153], v[138:141]
	v_mfma_f32_16x16x32_bf16 v[134:137], v[78:81], v[158:161], v[134:137]
	v_mfma_f32_16x16x32_bf16 v[126:129], v[130:133], v[158:161], v[126:129]
	v_mfma_f32_16x16x32_bf16 v[118:121], v[78:81], v[166:169], v[118:121]
	v_mfma_f32_16x16x32_bf16 v[114:117], v[130:133], v[166:169], v[114:117]
	v_mfma_f32_16x16x32_bf16 v[110:113], v[78:81], v[174:177], v[110:113]
	v_mfma_f32_16x16x32_bf16 v[106:109], v[130:133], v[174:177], v[106:109]
	s_barrier
	s_add_i32 s24, 0, 0x1c000
	s_add_i32 s0, s55, s31
	v_add_u32_e32 v212, s24, v243
	v_lshl_add_u64 v[186:187], v[186:187], 0, s[86:87]
	s_mov_b32 m0, s0
	ds_read_b128 v[200:203], v212
	ds_read_b128 v[204:207], v212 offset:1024
	ds_read_b128 v[208:211], v212 offset:2048
	ds_read_b128 v[212:215], v212 offset:3072
	global_load_lds_dwordx4 v[186:187], off
	v_lshl_add_u64 v[186:187], v[216:217], 0, s[86:87]
	s_add_i32 m0, s0, 0x2000
	s_nop 0
	global_load_lds_dwordx4 v[186:187], off
	s_barrier
	s_waitcnt lgkmcnt(0)
	v_mfma_f32_16x16x32_bf16 v[70:73], v[200:203], v[146:149], v[70:73]
	v_mfma_f32_16x16x32_bf16 v[66:69], v[208:211], v[146:149], v[66:69]
	v_mfma_f32_16x16x32_bf16 v[62:65], v[200:203], v[154:157], v[62:65]
	v_mfma_f32_16x16x32_bf16 v[58:61], v[208:211], v[154:157], v[58:61]
	v_mfma_f32_16x16x32_bf16 v[54:57], v[200:203], v[162:165], v[54:57]
	v_mfma_f32_16x16x32_bf16 v[50:53], v[208:211], v[162:165], v[50:53]
	v_mfma_f32_16x16x32_bf16 v[46:49], v[200:203], v[170:173], v[46:49]
	v_mfma_f32_16x16x32_bf16 v[42:45], v[208:211], v[170:173], v[42:45]
	v_mfma_f32_16x16x32_bf16 v[70:73], v[204:207], v[150:153], v[70:73]
	v_mfma_f32_16x16x32_bf16 v[66:69], v[212:215], v[150:153], v[66:69]
	v_mfma_f32_16x16x32_bf16 v[62:65], v[204:207], v[158:161], v[62:65]
	v_mfma_f32_16x16x32_bf16 v[58:61], v[212:215], v[158:161], v[58:61]
	v_mfma_f32_16x16x32_bf16 v[54:57], v[204:207], v[166:169], v[54:57]
	v_mfma_f32_16x16x32_bf16 v[50:53], v[212:215], v[166:169], v[50:53]
	v_mfma_f32_16x16x32_bf16 v[46:49], v[204:207], v[174:177], v[46:49]
	v_mfma_f32_16x16x32_bf16 v[42:45], v[212:215], v[174:177], v[42:45]
	s_mov_b32 m0, s40
	v_lshl_add_u64 v[186:187], v[218:219], 0, s[86:87]
	s_barrier
; #define PG8_STAGE(bufoff, gbase, voff) do { _Pragma("unroll") for (int _i = 0; _i < 2; ++_i) \
;         __builtin_amdgcn_global_load_lds((const unsigned*)((const char*)(gbase) + (voff)[_i]), (LAS unsigned*)(lds + (bufoff) + ldsw + _i * 8192), 16, 0, 0); } while (0)
; #define PG8_LDA(dst, b, h) do { _Pragma("unroll") for (int m = 0; m < 4; ++m) _Pragma("unroll") for (int k = 0; k < 2; ++k) dst[m][k] = *(const LAS bf16x8*)(lds + PG8_SA(b, h) + aoff + m * 2048 + k * 1024); } while (0)
; #define PG8_WAIT_V(n) asm volatile("s_waitcnt vmcnt(" #n ")" ::: "memory")
; template <class Epi>
; __device__ __forceinline__ void gemm_phase(LAS unsigned char* lds, const Gemm g, const StaticOrder& S, const Epi& E) {
;     ...
;             PG8_WAIT_V(6); PG8_BAR; PG8_MMA(1, 1, At, B1); PG8_BAR;
;             PG8_LDB(B0, 1, 0); PG8_SCHED; PG8_LDA(At, 1, 0); PG8_STAGE(PG8_SA(0, 1), a2 + hstep, voffA);
;             PG8_WAIT_L(8); PG8_BAR; PG8_WAIT_L(0); PG8_MMA(0, 0, At, B0); PG8_BAR; PG8_SCHED;
;             PG8_LDB(B1, 1, 1); PG8_STAGE(PG8_SB(1, 0), b3, voffB);
;             PG8_BAR; PG8_WAIT_L(0); PG8_MMA(0, 1, At, B1); PG8_BAR;
;             PG8_LDA(At, 1, 1); PG8_STAGE(PG8_SA(1, 0), a3, voffA);
;             PG8_BAR; PG8_WAIT_L(0); PG8_MMA(1, 0, At, B0); PG8_BAR; PG8_SCHED;
;             PG8_STAGE(PG8_SB(1, 1), b3 + hstep, voffB);
;             PG8_WAIT_V(6); PG8_BAR; PG8_MMA(1, 1, At, B1); PG8_BAR;
;     __device__ __forceinline__ void operator()(const f32x4 (&acc)[2][2][4][2], const Unit& u, int wr, int wc, int fr, int fq) const {
;         const int row0 = u.pm * 256 + wr * 64 + fr, col0 = u.pn * 256 + wc * 32 + 8 * fq;
;         f32x4 ra, rb; load_rstd(ss, row0, ra, rb);
;         const float* swp = sw + (size_t)(u.pm >> 3) * 3072 + col0;
;         const f32x4 swv[4] = {*(const f32x4*)(swp), *(const f32x4*)(swp + 4), *(const f32x4*)(swp + 128), *(const f32x4*)(swp + 132)};
; #pragma unroll
;         for (int bj = 0; bj < 2; ++bj) {
;             const f32x4 s0 = swv[2 * bj], s1 = swv[2 * bj + 1];
; #pragma unroll
;             for (int ai = 0; ai < 2; ++ai) {
;                 uint4 yld[4], zld[4];
; #pragma unroll
;                 for (int i = 0; i < 4; ++i) { const size_t off = (size_t)(row0 + ai * 128 + i * 16) * DM + col0 + bj * 128;
;                     yld[i] = *(const uint4*)(Y + off); zld[i] = first ? make_uint4(0u, 0u, 0u, 0u) : *(const uint4*)(Z + off); }
	ds_read_b128 v[146:149], v245 offset:49152
	ds_read_b128 v[150:153], v245 offset:50176
	ds_read_b128 v[154:157], v245 offset:51200
	ds_read_b128 v[158:161], v245 offset:52224
	ds_read_b128 v[162:165], v245 offset:53248
	ds_read_b128 v[166:169], v245 offset:54272
	ds_read_b128 v[170:173], v245 offset:55296
	ds_read_b128 v[174:177], v245 offset:56320
	global_load_lds_dwordx4 v[186:187], off
	v_lshl_add_u64 v[186:187], v[220:221], 0, s[86:87]
	s_mov_b32 m0, s41
	s_nop 0
	global_load_lds_dwordx4 v[186:187], off
	s_barrier
	s_waitcnt lgkmcnt(0)
	v_mfma_f32_16x16x32_bf16 v[102:105], v[74:77], v[146:149], v[102:105]
	v_mfma_f32_16x16x32_bf16 v[94:97], v[74:77], v[154:157], v[94:97]
	v_mfma_f32_16x16x32_bf16 v[86:89], v[74:77], v[162:165], v[86:89]
	v_mfma_f32_16x16x32_bf16 v[34:37], v[74:77], v[170:173], v[34:37]
	v_mfma_f32_16x16x32_bf16 v[102:105], v[78:81], v[150:153], v[102:105]
	v_mfma_f32_16x16x32_bf16 v[98:101], v[122:125], v[146:149], v[98:101]
	v_mfma_f32_16x16x32_bf16 v[94:97], v[78:81], v[158:161], v[94:97]
	v_mfma_f32_16x16x32_bf16 v[90:93], v[122:125], v[154:157], v[90:93]
	v_mfma_f32_16x16x32_bf16 v[86:89], v[78:81], v[166:169], v[86:89]
	v_mfma_f32_16x16x32_bf16 v[82:85], v[122:125], v[162:165], v[82:85]
	v_mfma_f32_16x16x32_bf16 v[78:81], v[78:81], v[174:177], v[34:37]
	v_mfma_f32_16x16x32_bf16 v[34:37], v[122:125], v[170:173], v[38:41]
	v_mfma_f32_16x16x32_bf16 v[98:101], v[130:133], v[150:153], v[98:101]
	v_mfma_f32_16x16x32_bf16 v[90:93], v[130:133], v[158:161], v[90:93]
	v_mfma_f32_16x16x32_bf16 v[82:85], v[130:133], v[166:169], v[82:85]
	v_mfma_f32_16x16x32_bf16 v[74:77], v[130:133], v[174:177], v[34:37]
	s_barrier
	s_add_u32 s0, s22, 0x40080
	s_addc_u32 s1, s23, 0
	s_add_i32 s22, s24, s31
	v_lshl_add_u64 v[34:35], s[0:1], 0, v[4:5]
	s_mov_b32 m0, s22
	s_nop 0
	global_load_lds_dwordx4 v[34:35], off
	v_lshl_add_u64 v[34:35], s[0:1], 0, v[190:191]
	s_add_i32 m0, s22, 0x2000
	s_nop 0
	global_load_lds_dwordx4 v[34:35], off
	s_waitcnt vmcnt(6)
	s_barrier
	v_mfma_f32_16x16x32_bf16 v[30:33], v[200:203], v[146:149], v[30:33]
	v_mfma_f32_16x16x32_bf16 v[26:29], v[208:211], v[146:149], v[26:29]
	v_mfma_f32_16x16x32_bf16 v[22:25], v[200:203], v[154:157], v[22:25]
	v_mfma_f32_16x16x32_bf16 v[18:21], v[208:211], v[154:157], v[18:21]
	v_mfma_f32_16x16x32_bf16 v[14:17], v[200:203], v[162:165], v[14:17]
	v_mfma_f32_16x16x32_bf16 v[10:13], v[208:211], v[162:165], v[10:13]
	v_mfma_f32_16x16x32_bf16 v[6:9], v[200:203], v[170:173], v[6:9]
	v_mfma_f32_16x16x32_bf16 v[0:3], v[208:211], v[170:173], v[0:3]
	v_mfma_f32_16x16x32_bf16 v[30:33], v[204:207], v[150:153], v[30:33]
	v_mfma_f32_16x16x32_bf16 v[26:29], v[212:215], v[150:153], v[26:29]
	v_mfma_f32_16x16x32_bf16 v[22:25], v[204:207], v[158:161], v[22:25]
	v_mfma_f32_16x16x32_bf16 v[18:21], v[212:215], v[158:161], v[18:21]
	v_mfma_f32_16x16x32_bf16 v[14:17], v[204:207], v[166:169], v[14:17]
	v_mfma_f32_16x16x32_bf16 v[10:13], v[212:215], v[166:169], v[10:13]
	v_mfma_f32_16x16x32_bf16 v[6:9], v[204:207], v[174:177], v[6:9]
	v_mfma_f32_16x16x32_bf16 v[0:3], v[212:215], v[174:177], v[0:3]
	s_add_i32 s54, s54, 2
	s_add_u32 s6, s6, 0x100
	s_addc_u32 s7, s7, 0
	s_add_u32 s51, s51, 0x100
	s_addc_u32 s52, s52, 0
	s_cmp_gt_u32 s54, 13
	s_barrier
	s_cbranch_scc0 .LBB0_2801
	v_lshl_add_u32 v218, s43, 8, v242
	v_ashrrev_i32_e32 v219, 31, v218
	v_lshl_add_u64 v[34:35], v[218:219], 2, s[12:13]
	s_ashr_i32 s0, s43, 3
	global_load_dword v206, v[34:35], off
	global_load_dword v204, v[34:35], off offset:64
	global_load_dword v187, v[34:35], off offset:128
	global_load_dword v186, v[34:35], off offset:192
	global_load_dword v246, v[34:35], off offset:512
	global_load_dword v209, v[34:35], off offset:576
	global_load_dword v207, v[34:35], off offset:640
	global_load_dword v205, v[34:35], off offset:704
	s_mul_hi_i32 s1, s0, 0x3000
	s_mulk_i32 s0, 0x3000
	v_lshl_or_b32 v200, s48, 8, v244
	s_add_u32 s0, s38, s0
	s_addc_u32 s1, s39, s1
	v_ashrrev_i32_e32 v201, 31, v200
	v_lshl_add_u64 v[38:39], v[200:201], 2, s[0:1]
	v_lshlrev_b64 v[210:211], 10, v[218:219]
	global_load_dwordx4 v[122:125], v[38:39], off offset:16
	global_load_dwordx4 v[130:133], v[38:39], off
	global_load_dwordx4 v[34:37], v[38:39], off offset:528
	s_nop 0
	global_load_dwordx4 v[38:41], v[38:39], off offset:512
	v_lshl_add_u64 v[146:147], v[210:211], 0, v[200:201]
	v_lshl_add_u64 v[148:149], v[146:147], 1, s[10:11]
	global_load_dwordx4 v[174:177], v[148:149], off
	v_cndmask_b32_e64 v148, 0, 1, s[88:89]
	v_mov_b32_e32 v162, 0
	v_cmp_ne_u32_e64 s[6:7], 1, v148
	s_andn2_b64 vcc, exec, s[88:89]
	v_mov_b32_e32 v170, 0
	v_mov_b32_e32 v171, 0
	v_mov_b32_e32 v172, 0
	v_mov_b32_e32 v173, 0
	s_cbranch_vccnz .LBB0_2804
	v_lshl_add_u64 v[146:147], v[146:147], 1, s[8:9]
	global_load_dwordx4 v[170:173], v[146:147], off

; #define PG8_STAGE(bufoff, gbase, voff) do { _Pragma("unroll") for (int _i = 0; _i < 2; ++_i) \
;         __builtin_amdgcn_global_load_lds((const unsigned*)((const char*)(gbase) + (voff)[_i]), (LAS unsigned*)(lds + (bufoff) + ldsw + _i * 8192), 16, 0, 0); } while (0)
; #define PG8_LDA(dst, b, h) do { _Pragma("unroll") for (int m = 0; m < 4; ++m) _Pragma("unroll") for (int k = 0; k < 2; ++k) dst[m][k] = *(const LAS bf16x8*)(lds + PG8_SA(b, h) + aoff + m * 2048 + k * 1024); } while (0)
; #define PG8_LDB(dst, b, h) do { _Pragma("unroll") for (int n = 0; n < 2; ++n) _Pragma("unroll") for (int k = 0; k < 2; ++k) dst[n][k] = *(const LAS bf16x8*)(lds + PG8_SB(b, h) + boff + n * 2048 + k * 1024); } while (0)
; #define PG8_MMA(ai, bj, At, Bt) do { __builtin_amdgcn_s_setprio(1); _Pragma("unroll") for (int m = 0; m < 4; ++m) _Pragma("unroll") for (int n = 0; n < 2; ++n) _Pragma("unroll") for (int k = 0; k < 2; ++k) \
;         acc[ai][bj][m][n] = __builtin_amdgcn_mfma_f32_16x16x32_bf16(Bt[n][k], At[m][k], acc[ai][bj][m][n], 0, 0, 0); __builtin_amdgcn_s_setprio(0); } while (0)
; #define PG8_WAIT_L(n) asm volatile("s_waitcnt lgkmcnt(" #n ")" ::: "memory")
; #define PG8_BAR __builtin_amdgcn_s_barrier()
; #define PG8_SCHED __builtin_amdgcn_sched_barrier(0)
; template <class Epi>
; __device__ __forceinline__ void gemm_phase(LAS unsigned char* lds, const Gemm g, const StaticOrder& S, const Epi& E) {
;     ...
;         for (int t = 0; t < nt; t += 2) {
;             const bool last = (t == nt - 2);
;             const char* a1 = cA + (size_t)(t + 1) * kstep;
;             const char* a2 = last ? nA : cA + (size_t)(t + 2) * kstep; const char* b2 = last ? nB : cB + (size_t)(t + 2) * kstep;
;             const char* a3 = a2 + kstep; const char* b3 = b2 + kstep;
;             PG8_LDB(B0, 0, 0); PG8_SCHED; PG8_LDA(At, 0, 0); PG8_STAGE(PG8_SA(1, 1), a1 + hstep, voffA);
;             PG8_WAIT_L(8); PG8_BAR; PG8_WAIT_L(0); PG8_MMA(0, 0, At, B0); PG8_BAR; PG8_SCHED;
;             PG8_LDB(B1, 0, 1); PG8_STAGE(PG8_SB(0, 0), b2, voffB);
;             PG8_BAR; PG8_WAIT_L(0); PG8_MMA(0, 1, At, B1); PG8_BAR;
;             PG8_LDA(At, 0, 1); PG8_STAGE(PG8_SA(0, 0), a2, voffA);
;             PG8_BAR; PG8_WAIT_L(0); PG8_MMA(1, 0, At, B0); PG8_BAR; PG8_SCHED;
.LBB0_2897:
	s_add_u32 s0, s18, 0xfffc0080
	s_addc_u32 s1, s19, -1
	s_add_i32 s54, 0, 0x10000
	v_add_u32_e32 v78, s54, v161
	ds_read_b128 v[66:69], v78
	ds_read_b128 v[70:73], v78 offset:1024
	ds_read_b128 v[74:77], v78 offset:2048
	ds_read_b128 v[78:81], v78 offset:3072
	s_cmp_eq_u32 s52, 12
	s_cselect_b32 s23, s13, s1
	s_cselect_b32 s22, s48, s0
	s_cselect_b32 s21, s11, s51
	s_cselect_b32 s20, s49, s50
	v_lshl_add_u64 v[156:157], s[18:19], 0, v[152:153]
	s_add_i32 m0, s30, 0xc000
	ds_read_b128 v[168:171], v165
	ds_read_b128 v[172:175], v165 offset:1024
	ds_read_b128 v[190:193], v165 offset:2048
	ds_read_b128 v[194:197], v165 offset:3072
	ds_read_b128 v[198:201], v165 offset:4096
	ds_read_b128 v[202:205], v165 offset:5120
	ds_read_b128 v[206:209], v165 offset:6144
	ds_read_b128 v[210:213], v165 offset:7168
	global_load_lds_dwordx4 v[156:157], off
	v_lshl_add_u64 v[156:157], s[18:19], 0, v[154:155]
	s_add_i32 m0, s30, 0xe000
	s_nop 0
	global_load_lds_dwordx4 v[156:157], off
	s_waitcnt lgkmcnt(8)
	s_barrier
	s_waitcnt lgkmcnt(0)
	v_mfma_f32_16x16x32_bf16 v[142:145], v[66:69], v[168:171], v[142:145]
	v_mfma_f32_16x16x32_bf16 v[138:141], v[74:77], v[168:171], v[138:141]
	v_mfma_f32_16x16x32_bf16 v[126:129], v[66:69], v[190:193], v[126:129]
	v_mfma_f32_16x16x32_bf16 v[122:125], v[74:77], v[190:193], v[122:125]
	v_mfma_f32_16x16x32_bf16 v[110:113], v[66:69], v[198:201], v[110:113]
	v_mfma_f32_16x16x32_bf16 v[106:109], v[74:77], v[198:201], v[106:109]
	v_mfma_f32_16x16x32_bf16 v[94:97], v[66:69], v[206:209], v[94:97]
	v_mfma_f32_16x16x32_bf16 v[90:93], v[74:77], v[206:209], v[90:93]
	v_mfma_f32_16x16x32_bf16 v[142:145], v[70:73], v[172:175], v[142:145]
	v_mfma_f32_16x16x32_bf16 v[138:141], v[78:81], v[172:175], v[138:141]
	v_mfma_f32_16x16x32_bf16 v[126:129], v[70:73], v[194:197], v[126:129]
	v_mfma_f32_16x16x32_bf16 v[122:125], v[78:81], v[194:197], v[122:125]
	v_mfma_f32_16x16x32_bf16 v[110:113], v[70:73], v[202:205], v[110:113]
	v_mfma_f32_16x16x32_bf16 v[106:109], v[78:81], v[202:205], v[106:109]
	v_mfma_f32_16x16x32_bf16 v[94:97], v[70:73], v[210:213], v[94:97]
	v_mfma_f32_16x16x32_bf16 v[90:93], v[78:81], v[210:213], v[90:93]
	s_barrier
	s_add_i32 s0, 0, 0x14000
	v_add_u32_e32 v156, s0, v161
	s_add_i32 s1, s54, s29
	ds_read_b128 v[214:217], v156
	ds_read_b128 v[218:221], v156 offset:1024
	ds_read_b128 v[222:225], v156 offset:2048
	ds_read_b128 v[242:245], v156 offset:3072
	v_lshl_add_u64 v[156:157], s[20:21], 0, v[4:5]
	s_mov_b32 m0, s1
	v_lshl_add_u64 v[176:177], s[20:21], 0, v[146:147]
	global_load_lds_dwordx4 v[156:157], off
	s_add_i32 m0, s1, 0x2000
	s_nop 0
	global_load_lds_dwordx4 v[176:177], off
	s_barrier
	s_waitcnt lgkmcnt(0)
	v_mfma_f32_16x16x32_bf16 v[134:137], v[214:217], v[168:171], v[134:137]
	v_mfma_f32_16x16x32_bf16 v[130:133], v[222:225], v[168:171], v[130:133]
	v_mfma_f32_16x16x32_bf16 v[118:121], v[214:217], v[190:193], v[118:121]
	v_mfma_f32_16x16x32_bf16 v[114:117], v[222:225], v[190:193], v[114:117]
	v_mfma_f32_16x16x32_bf16 v[102:105], v[214:217], v[198:201], v[102:105]
	v_mfma_f32_16x16x32_bf16 v[98:101], v[222:225], v[198:201], v[98:101]
	v_mfma_f32_16x16x32_bf16 v[86:89], v[214:217], v[206:209], v[86:89]
	v_mfma_f32_16x16x32_bf16 v[82:85], v[222:225], v[206:209], v[82:85]
	v_mfma_f32_16x16x32_bf16 v[134:137], v[218:221], v[172:175], v[134:137]
	v_mfma_f32_16x16x32_bf16 v[130:133], v[242:245], v[172:175], v[130:133]
	v_mfma_f32_16x16x32_bf16 v[118:121], v[218:221], v[194:197], v[118:121]
	v_mfma_f32_16x16x32_bf16 v[114:117], v[242:245], v[194:197], v[114:117]
	v_mfma_f32_16x16x32_bf16 v[102:105], v[218:221], v[202:205], v[102:105]
	v_mfma_f32_16x16x32_bf16 v[98:101], v[242:245], v[202:205], v[98:101]
	v_mfma_f32_16x16x32_bf16 v[86:89], v[218:221], v[210:213], v[86:89]
	v_mfma_f32_16x16x32_bf16 v[82:85], v[242:245], v[210:213], v[82:85]
	s_mov_b32 m0, s30
	v_lshl_add_u64 v[186:187], s[22:23], 0, v[150:151]
	s_barrier
	ds_read_b128 v[168:171], v165 offset:16384
	ds_read_b128 v[172:175], v165 offset:17408
	ds_read_b128 v[190:193], v165 offset:18432
	ds_read_b128 v[194:197], v165 offset:19456
	ds_read_b128 v[198:201], v165 offset:20480
	ds_read_b128 v[202:205], v165 offset:21504
	ds_read_b128 v[206:209], v165 offset:22528
	ds_read_b128 v[210:213], v165 offset:23552
	global_load_lds_dwordx4 v[186:187], off
	v_lshl_add_u64 v[226:227], s[22:23], 0, v[148:149]
	s_mov_b32 m0, s31
	s_nop 0
	global_load_lds_dwordx4 v[226:227], off
	s_barrier
	s_waitcnt lgkmcnt(0)
	v_mfma_f32_16x16x32_bf16 v[62:65], v[66:69], v[168:171], v[62:65]
	v_mfma_f32_16x16x32_bf16 v[58:61], v[74:77], v[168:171], v[58:61]
	v_mfma_f32_16x16x32_bf16 v[46:49], v[66:69], v[190:193], v[46:49]
	v_mfma_f32_16x16x32_bf16 v[42:45], v[74:77], v[190:193], v[42:45]
	v_mfma_f32_16x16x32_bf16 v[30:33], v[66:69], v[198:201], v[30:33]
	v_mfma_f32_16x16x32_bf16 v[26:29], v[74:77], v[198:201], v[26:29]
	v_mfma_f32_16x16x32_bf16 v[14:17], v[66:69], v[206:209], v[14:17]
	v_mfma_f32_16x16x32_bf16 v[10:13], v[74:77], v[206:209], v[10:13]
	v_mfma_f32_16x16x32_bf16 v[62:65], v[70:73], v[172:175], v[62:65]
	v_mfma_f32_16x16x32_bf16 v[58:61], v[78:81], v[172:175], v[58:61]
	v_mfma_f32_16x16x32_bf16 v[46:49], v[70:73], v[194:197], v[46:49]
	v_mfma_f32_16x16x32_bf16 v[42:45], v[78:81], v[194:197], v[42:45]
	v_mfma_f32_16x16x32_bf16 v[30:33], v[70:73], v[202:205], v[30:33]
	v_mfma_f32_16x16x32_bf16 v[26:29], v[78:81], v[202:205], v[26:29]
	v_mfma_f32_16x16x32_bf16 v[14:17], v[70:73], v[210:213], v[14:17]
	v_mfma_f32_16x16x32_bf16 v[10:13], v[78:81], v[210:213], v[10:13]
	s_barrier
; #define PG8_STAGE(bufoff, gbase, voff) do { _Pragma("unroll") for (int _i = 0; _i < 2; ++_i) \
;         __builtin_amdgcn_global_load_lds((const unsigned*)((const char*)(gbase) + (voff)[_i]), (LAS unsigned*)(lds + (bufoff) + ldsw + _i * 8192), 16, 0, 0); } while (0)
; #define PG8_LDA(dst, b, h) do { _Pragma("unroll") for (int m = 0; m < 4; ++m) _Pragma("unroll") for (int k = 0; k < 2; ++k) dst[m][k] = *(const LAS bf16x8*)(lds + PG8_SA(b, h) + aoff + m * 2048 + k * 1024); } while (0)
; #define PG8_LDB(dst, b, h) do { _Pragma("unroll") for (int n = 0; n < 2; ++n) _Pragma("unroll") for (int k = 0; k < 2; ++k) dst[n][k] = *(const LAS bf16x8*)(lds + PG8_SB(b, h) + boff + n * 2048 + k * 1024); } while (0)
; #define PG8_MMA(ai, bj, At, Bt) do { __builtin_amdgcn_s_setprio(1); _Pragma("unroll") for (int m = 0; m < 4; ++m) _Pragma("unroll") for (int n = 0; n < 2; ++n) _Pragma("unroll") for (int k = 0; k < 2; ++k) \
;         acc[ai][bj][m][n] = __builtin_amdgcn_mfma_f32_16x16x32_bf16(Bt[n][k], At[m][k], acc[ai][bj][m][n], 0, 0, 0); __builtin_amdgcn_s_setprio(0); } while (0)
; #define PG8_WAIT_V(n) asm volatile("s_waitcnt vmcnt(" #n ")" ::: "memory")
; #define PG8_WAIT_L(n) asm volatile("s_waitcnt lgkmcnt(" #n ")" ::: "memory")
; #define PG8_BAR __builtin_amdgcn_s_barrier()
; #define PG8_SCHED __builtin_amdgcn_sched_barrier(0)
; template <class Epi>
; __device__ __forceinline__ void gemm_phase(LAS unsigned char* lds, const Gemm g, const StaticOrder& S, const Epi& E) {
;     ...
;             PG8_STAGE(PG8_SB(0, 1), b2 + hstep, voffB);
;             PG8_WAIT_V(6); PG8_BAR; PG8_MMA(1, 1, At, B1); PG8_BAR;
;             PG8_LDB(B0, 1, 0); PG8_SCHED; PG8_LDA(At, 1, 0); PG8_STAGE(PG8_SA(0, 1), a2 + hstep, voffA);
;             PG8_WAIT_L(8); PG8_BAR; PG8_WAIT_L(0); PG8_MMA(0, 0, At, B0); PG8_BAR; PG8_SCHED;
;             PG8_LDB(B1, 1, 1); PG8_STAGE(PG8_SB(1, 0), b3, voffB);
;             PG8_BAR; PG8_WAIT_L(0); PG8_MMA(0, 1, At, B1); PG8_BAR;
;             PG8_LDA(At, 1, 1); PG8_STAGE(PG8_SA(1, 0), a3, voffA);
;             PG8_BAR; PG8_WAIT_L(0); PG8_MMA(1, 0, At, B0); PG8_BAR; PG8_SCHED;
	s_add_u32 s54, s20, 0x40000
	s_addc_u32 s55, s21, 0
	s_add_i32 s0, s0, s29
	v_lshl_add_u64 v[66:67], s[54:55], 0, v[4:5]
	s_mov_b32 m0, s0
	s_nop 0
	global_load_lds_dwordx4 v[66:67], off
	v_lshl_add_u64 v[66:67], s[54:55], 0, v[146:147]
	s_add_i32 m0, s0, 0x2000
	s_nop 0
	global_load_lds_dwordx4 v[66:67], off
	s_waitcnt vmcnt(6)
	s_barrier
	v_mfma_f32_16x16x32_bf16 v[54:57], v[214:217], v[168:171], v[54:57]
	v_mfma_f32_16x16x32_bf16 v[50:53], v[222:225], v[168:171], v[50:53]
	v_mfma_f32_16x16x32_bf16 v[38:41], v[214:217], v[190:193], v[38:41]
	v_mfma_f32_16x16x32_bf16 v[34:37], v[222:225], v[190:193], v[34:37]
	v_mfma_f32_16x16x32_bf16 v[22:25], v[214:217], v[198:201], v[22:25]
	v_mfma_f32_16x16x32_bf16 v[18:21], v[222:225], v[198:201], v[18:21]
	v_mfma_f32_16x16x32_bf16 v[6:9], v[214:217], v[206:209], v[6:9]
	v_mfma_f32_16x16x32_bf16 v[0:3], v[222:225], v[206:209], v[0:3]
	v_mfma_f32_16x16x32_bf16 v[54:57], v[218:221], v[172:175], v[54:57]
	v_mfma_f32_16x16x32_bf16 v[50:53], v[242:245], v[172:175], v[50:53]
	v_mfma_f32_16x16x32_bf16 v[38:41], v[218:221], v[194:197], v[38:41]
	v_mfma_f32_16x16x32_bf16 v[34:37], v[242:245], v[194:197], v[34:37]
	v_mfma_f32_16x16x32_bf16 v[22:25], v[218:221], v[202:205], v[22:25]
	v_mfma_f32_16x16x32_bf16 v[18:21], v[242:245], v[202:205], v[18:21]
	v_mfma_f32_16x16x32_bf16 v[6:9], v[218:221], v[210:213], v[6:9]
	v_mfma_f32_16x16x32_bf16 v[0:3], v[242:245], v[210:213], v[0:3]
	s_add_i32 s0, 0, 0x18000
	v_add_u32_e32 v78, s0, v161
	s_barrier
	ds_read_b128 v[66:69], v78
	ds_read_b128 v[70:73], v78 offset:1024
	ds_read_b128 v[74:77], v78 offset:2048
	ds_read_b128 v[78:81], v78 offset:3072
	s_add_u32 s22, s22, 0x40000
	s_addc_u32 s23, s23, 0
	s_mov_b32 m0, s34
	v_lshl_add_u64 v[214:215], s[22:23], 0, v[150:151]
	ds_read_b128 v[168:171], v165 offset:32768
	ds_read_b128 v[172:175], v165 offset:33792
	ds_read_b128 v[190:193], v165 offset:34816
	ds_read_b128 v[194:197], v165 offset:35840
	ds_read_b128 v[198:201], v165 offset:36864
	ds_read_b128 v[202:205], v165 offset:37888
	ds_read_b128 v[206:209], v165 offset:38912
	ds_read_b128 v[210:213], v165 offset:39936
	global_load_lds_dwordx4 v[214:215], off
	v_lshl_add_u64 v[214:215], s[22:23], 0, v[148:149]
	s_mov_b32 m0, s35
	s_nop 0
	global_load_lds_dwordx4 v[214:215], off
	s_waitcnt lgkmcnt(8)
	s_barrier
	s_waitcnt lgkmcnt(0)
	v_mfma_f32_16x16x32_bf16 v[142:145], v[66:69], v[168:171], v[142:145]
	v_mfma_f32_16x16x32_bf16 v[138:141], v[74:77], v[168:171], v[138:141]
	v_mfma_f32_16x16x32_bf16 v[126:129], v[66:69], v[190:193], v[126:129]
	v_mfma_f32_16x16x32_bf16 v[122:125], v[74:77], v[190:193], v[122:125]
	v_mfma_f32_16x16x32_bf16 v[110:113], v[66:69], v[198:201], v[110:113]
	v_mfma_f32_16x16x32_bf16 v[106:109], v[74:77], v[198:201], v[106:109]
	v_mfma_f32_16x16x32_bf16 v[94:97], v[66:69], v[206:209], v[94:97]
	v_mfma_f32_16x16x32_bf16 v[90:93], v[74:77], v[206:209], v[90:93]
	v_mfma_f32_16x16x32_bf16 v[142:145], v[70:73], v[172:175], v[142:145]
	v_mfma_f32_16x16x32_bf16 v[138:141], v[78:81], v[172:175], v[138:141]
	v_mfma_f32_16x16x32_bf16 v[126:129], v[70:73], v[194:197], v[126:129]
	v_mfma_f32_16x16x32_bf16 v[122:125], v[78:81], v[194:197], v[122:125]
	v_mfma_f32_16x16x32_bf16 v[110:113], v[70:73], v[202:205], v[110:113]
	v_mfma_f32_16x16x32_bf16 v[106:109], v[78:81], v[202:205], v[106:109]
	v_mfma_f32_16x16x32_bf16 v[94:97], v[70:73], v[210:213], v[94:97]
	v_mfma_f32_16x16x32_bf16 v[90:93], v[78:81], v[210:213], v[90:93]
	s_barrier
	s_add_i32 s1, 0, 0x1c000
	s_add_i32 s0, s0, s29
	v_add_u32_e32 v158, s1, v161
	v_lshl_add_u64 v[156:157], v[156:157], 0, s[86:87]
	s_mov_b32 m0, s0
	ds_read_b128 v[214:217], v158
	ds_read_b128 v[218:221], v158 offset:1024
	ds_read_b128 v[222:225], v158 offset:2048
	ds_read_b128 v[242:245], v158 offset:3072
	global_load_lds_dwordx4 v[156:157], off
	v_lshl_add_u64 v[156:157], v[176:177], 0, s[86:87]
	s_add_i32 m0, s0, 0x2000
	s_nop 0
	global_load_lds_dwordx4 v[156:157], off
	s_barrier
	s_waitcnt lgkmcnt(0)
	v_mfma_f32_16x16x32_bf16 v[134:137], v[214:217], v[168:171], v[134:137]
	v_mfma_f32_16x16x32_bf16 v[130:133], v[222:225], v[168:171], v[130:133]
	v_mfma_f32_16x16x32_bf16 v[118:121], v[214:217], v[190:193], v[118:121]
	v_mfma_f32_16x16x32_bf16 v[114:117], v[222:225], v[190:193], v[114:117]
	v_mfma_f32_16x16x32_bf16 v[102:105], v[214:217], v[198:201], v[102:105]
	v_mfma_f32_16x16x32_bf16 v[98:101], v[222:225], v[198:201], v[98:101]
	v_mfma_f32_16x16x32_bf16 v[86:89], v[214:217], v[206:209], v[86:89]
	v_mfma_f32_16x16x32_bf16 v[82:85], v[222:225], v[206:209], v[82:85]
	v_mfma_f32_16x16x32_bf16 v[134:137], v[218:221], v[172:175], v[134:137]
	v_mfma_f32_16x16x32_bf16 v[130:133], v[242:245], v[172:175], v[130:133]
	v_mfma_f32_16x16x32_bf16 v[118:121], v[218:221], v[194:197], v[118:121]
	v_mfma_f32_16x16x32_bf16 v[114:117], v[242:245], v[194:197], v[114:117]
	v_mfma_f32_16x16x32_bf16 v[102:105], v[218:221], v[202:205], v[102:105]
	v_mfma_f32_16x16x32_bf16 v[98:101], v[242:245], v[202:205], v[98:101]
	v_mfma_f32_16x16x32_bf16 v[86:89], v[218:221], v[210:213], v[86:89]
	v_mfma_f32_16x16x32_bf16 v[82:85], v[242:245], v[210:213], v[82:85]
	s_mov_b32 m0, s38
	v_lshl_add_u64 v[156:157], v[186:187], 0, s[86:87]
	s_barrier
	ds_read_b128 v[168:171], v165 offset:49152
	ds_read_b128 v[172:175], v165 offset:50176
	ds_read_b128 v[190:193], v165 offset:51200
	ds_read_b128 v[194:197], v165 offset:52224
	ds_read_b128 v[198:201], v165 offset:53248
	ds_read_b128 v[202:205], v165 offset:54272
	ds_read_b128 v[206:209], v165 offset:55296
	ds_read_b128 v[210:213], v165 offset:56320
	global_load_lds_dwordx4 v[156:157], off
	v_lshl_add_u64 v[156:157], v[226:227], 0, s[86:87]
	s_mov_b32 m0, s39
	s_nop 0
	global_load_lds_dwordx4 v[156:157], off
	s_barrier
; #define PG8_STAGE(bufoff, gbase, voff) do { _Pragma("unroll") for (int _i = 0; _i < 2; ++_i) \
;         __builtin_amdgcn_global_load_lds((const unsigned*)((const char*)(gbase) + (voff)[_i]), (LAS unsigned*)(lds + (bufoff) + ldsw + _i * 8192), 16, 0, 0); } while (0)
; #define PG8_MMA(ai, bj, At, Bt) do { __builtin_amdgcn_s_setprio(1); _Pragma("unroll") for (int m = 0; m < 4; ++m) _Pragma("unroll") for (int n = 0; n < 2; ++n) _Pragma("unroll") for (int k = 0; k < 2; ++k) \
;         acc[ai][bj][m][n] = __builtin_amdgcn_mfma_f32_16x16x32_bf16(Bt[n][k], At[m][k], acc[ai][bj][m][n], 0, 0, 0); __builtin_amdgcn_s_setprio(0); } while (0)
; #define PG8_WAIT_V(n) asm volatile("s_waitcnt vmcnt(" #n ")" ::: "memory")
; #define PG8_WAIT_L(n) asm volatile("s_waitcnt lgkmcnt(" #n ")" ::: "memory")
; #define PG8_BAR __builtin_amdgcn_s_barrier()
; #define PG8_SCHED __builtin_amdgcn_sched_barrier(0)
; template <class Epi>
; __device__ __forceinline__ void gemm_phase(LAS unsigned char* lds, const Gemm g, const StaticOrder& S, const Epi& E) {
;     ...
;             PG8_BAR; PG8_WAIT_L(0); PG8_MMA(1, 0, At, B0); PG8_BAR; PG8_SCHED;
;             PG8_STAGE(PG8_SB(1, 1), b3 + hstep, voffB);
;             PG8_WAIT_V(6); PG8_BAR; PG8_MMA(1, 1, At, B1); PG8_BAR;
;     __device__ __forceinline__ void operator()(const f32x4 (&acc)[2][2][4][2], const Unit& u, int wr, int wc, int fr, int fq) const {
;         const int row0 = u.pm * 256 + wr * 64 + fr, hc0 = u.pn * 128 + wc * 32 + fq * 8;
;         const float* swp = sw + (size_t)(u.pm >> 3) * 5632 + u.pn * 256 + wc * 32 + 8 * fq;
;         f32x4 ra, rb; load_rstd(ss, row0, ra, rb);
;         const f32x4 sg0 = *(const f32x4*)(swp), sg1 = *(const f32x4*)(swp + 4), su0 = *(const f32x4*)(swp + 128), su1 = *(const f32x4*)(swp + 132);
	s_waitcnt lgkmcnt(0)
	v_mfma_f32_16x16x32_bf16 v[62:65], v[66:69], v[168:171], v[62:65]
	v_mfma_f32_16x16x32_bf16 v[58:61], v[74:77], v[168:171], v[58:61]
	v_mfma_f32_16x16x32_bf16 v[46:49], v[66:69], v[190:193], v[46:49]
	v_mfma_f32_16x16x32_bf16 v[42:45], v[74:77], v[190:193], v[42:45]
	v_mfma_f32_16x16x32_bf16 v[30:33], v[66:69], v[198:201], v[30:33]
	v_mfma_f32_16x16x32_bf16 v[26:29], v[74:77], v[198:201], v[26:29]
	v_mfma_f32_16x16x32_bf16 v[14:17], v[66:69], v[206:209], v[14:17]
	v_mfma_f32_16x16x32_bf16 v[10:13], v[74:77], v[206:209], v[10:13]
	v_mfma_f32_16x16x32_bf16 v[62:65], v[70:73], v[172:175], v[62:65]
	v_mfma_f32_16x16x32_bf16 v[58:61], v[78:81], v[172:175], v[58:61]
	v_mfma_f32_16x16x32_bf16 v[46:49], v[70:73], v[194:197], v[46:49]
	v_mfma_f32_16x16x32_bf16 v[42:45], v[78:81], v[194:197], v[42:45]
	v_mfma_f32_16x16x32_bf16 v[30:33], v[70:73], v[202:205], v[30:33]
	v_mfma_f32_16x16x32_bf16 v[26:29], v[78:81], v[202:205], v[26:29]
	v_mfma_f32_16x16x32_bf16 v[14:17], v[70:73], v[210:213], v[14:17]
	v_mfma_f32_16x16x32_bf16 v[10:13], v[78:81], v[210:213], v[10:13]
	s_barrier
	s_add_u32 s20, s20, 0x40080
	s_addc_u32 s21, s21, 0
	s_add_i32 s0, s1, s29
	v_lshl_add_u64 v[66:67], s[20:21], 0, v[4:5]
	s_mov_b32 m0, s0
	s_nop 0
	global_load_lds_dwordx4 v[66:67], off
	v_lshl_add_u64 v[66:67], s[20:21], 0, v[146:147]
	s_add_i32 m0, s0, 0x2000
	s_nop 0
	global_load_lds_dwordx4 v[66:67], off
	s_waitcnt vmcnt(6)
	s_barrier
	v_mfma_f32_16x16x32_bf16 v[54:57], v[214:217], v[168:171], v[54:57]
	v_mfma_f32_16x16x32_bf16 v[50:53], v[222:225], v[168:171], v[50:53]
	v_mfma_f32_16x16x32_bf16 v[38:41], v[214:217], v[190:193], v[38:41]
	v_mfma_f32_16x16x32_bf16 v[34:37], v[222:225], v[190:193], v[34:37]
	v_mfma_f32_16x16x32_bf16 v[22:25], v[214:217], v[198:201], v[22:25]
	v_mfma_f32_16x16x32_bf16 v[18:21], v[222:225], v[198:201], v[18:21]
	v_mfma_f32_16x16x32_bf16 v[6:9], v[214:217], v[206:209], v[6:9]
	v_mfma_f32_16x16x32_bf16 v[0:3], v[222:225], v[206:209], v[0:3]
	v_mfma_f32_16x16x32_bf16 v[54:57], v[218:221], v[172:175], v[54:57]
	v_mfma_f32_16x16x32_bf16 v[50:53], v[242:245], v[172:175], v[50:53]
	v_mfma_f32_16x16x32_bf16 v[38:41], v[218:221], v[194:197], v[38:41]
	v_mfma_f32_16x16x32_bf16 v[34:37], v[242:245], v[194:197], v[34:37]
	v_mfma_f32_16x16x32_bf16 v[22:25], v[218:221], v[202:205], v[22:25]
	v_mfma_f32_16x16x32_bf16 v[18:21], v[242:245], v[202:205], v[18:21]
	v_mfma_f32_16x16x32_bf16 v[6:9], v[218:221], v[210:213], v[6:9]
	v_mfma_f32_16x16x32_bf16 v[0:3], v[242:245], v[210:213], v[0:3]
	s_add_i32 s52, s52, 2
	s_add_u32 s18, s18, 0x100
	s_addc_u32 s19, s19, 0
	s_add_u32 s50, s50, 0x100
	s_addc_u32 s51, s51, 0
	s_cmp_gt_u32 s52, 13
	s_barrier
	s_cbranch_scc0 .LBB0_2897
	v_lshl_add_u32 v156, s43, 8, v159
	v_ashrrev_i32_e32 v157, 31, v156
	v_lshl_add_u64 v[66:67], v[156:157], 2, s[8:9]
	global_load_dword v190, v[66:67], off
	global_load_dword v191, v[66:67], off offset:64
	global_load_dword v192, v[66:67], off offset:128
	global_load_dword v193, v[66:67], off offset:192
	global_load_dword v194, v[66:67], off offset:512
	global_load_dword v195, v[66:67], off offset:576
	global_load_dword v196, v[66:67], off offset:640
	global_load_dword v197, v[66:67], off offset:704
	s_ashr_i32 s0, s43, 3
	s_mul_hi_i32 s1, s0, 0x5800
	s_mulk_i32 s0, 0x5800
	s_add_u32 s0, s36, s0
	s_addc_u32 s1, s37, s1
	s_lshl_b32 s18, s42, 8
	s_ashr_i32 s19, s18, 31
	s_lshl_b64 s[18:19], s[18:19], 2
	s_add_u32 s0, s0, s18
	s_addc_u32 s1, s1, s19
	s_add_u32 s18, s0, s41
	s_addc_u32 s19, s1, 0
	v_lshl_or_b32 v170, s42, 7, v163
	v_ashrrev_i32_e32 v171, 31, v170
	global_load_dwordx4 v[66:69], v167, s[18:19] offset:16
	global_load_dwordx4 v[74:77], v167, s[18:19]
	global_load_dwordx4 v[70:73], v167, s[18:19] offset:528
	global_load_dwordx4 v[78:81], v167, s[18:19] offset:512
	s_and_b64 vcc, exec, s[4:5]
	s_mov_b32 s42, s10
	s_mov_b32 s43, s12
	s_mov_b64 s[20:21], s[16:17]
	s_waitcnt vmcnt(4)
	v_fmamk_f32 v198, v190, 0x3a800000, v229
	v_rsq_f32_e32 v174, v198
	v_fmamk_f32 v198, v194, 0x3a800000, v229
	v_rsq_f32_e32 v164, v198
	v_fmamk_f32 v198, v191, 0x3a800000, v229
	v_rsq_f32_e32 v172, v198
	v_fmamk_f32 v198, v195, 0x3a800000, v229
	v_rsq_f32_e32 v162, v198
	v_fmamk_f32 v198, v192, 0x3a800000, v229
	v_rsq_f32_e32 v168, v198
	v_fmamk_f32 v198, v196, 0x3a800000, v229
	v_rsq_f32_e32 v160, v198
	v_fmamk_f32 v198, v193, 0x3a800000, v229
	v_fmamk_f32 v199, v197, 0x3a800000, v229
	v_rsq_f32_e32 v166, v198
	v_rsq_f32_e32 v158, v199
	s_waitcnt vmcnt(0)
; __device__ __forceinline__ unsigned cvt_pk_bf16(float lo, float hi) { unsigned r; asm volatile("s_nop 0\n\tv_cvt_pk_bf16_f32 %0, %1, %2" : "=v"(r) : "v"(lo), "v"(hi)); return r; }
; __device__ __forceinline__ float siluf_(float x) { return x * __builtin_amdgcn_rcpf(1.f + __expf(-x)); }
;     __device__ __forceinline__ void operator()(const f32x4 (&acc)[2][2][4][2], const Unit& u, int wr, int wc, int fr, int fq) const {
;     ...
;             for (int m = 0; m < 4; ++m) { const int r = row0 + ai * 128 + m * 16;
;                 const float rstd = ai ? rb[m] : ra[m];
;                 const f32x4 g0 = acc[ai][0][m][0] * rstd + sg0, g1 = acc[ai][0][m][1] * rstd + sg1, u0 = acc[ai][1][m][0] * rstd + su0, u1 = acc[ai][1][m][1] * rstd + su1;
;                 uint4 st; st.x = cvt_pk_bf16(siluf_(g0[0]) * u0[0], siluf_(g0[1]) * u0[1]); st.y = cvt_pk_bf16(siluf_(g0[2]) * u0[2], siluf_(g0[3]) * u0[3]);
;                 st.z = cvt_pk_bf16(siluf_(g1[0]) * u1[0], siluf_(g1[1]) * u1[1]); st.w = cvt_pk_bf16(siluf_(g1[2]) * u1[2], siluf_(g1[3]) * u1[3]);
;                 *(uint4*)(hid + (size_t)r * DFF + hc0) = st; }
	v_pk_fma_f32 v[138:139], v[138:139], v[174:175], v[66:67] op_sel_hi:[1,0,1]
	v_pk_fma_f32 v[142:143], v[142:143], v[174:175], v[74:75] op_sel_hi:[1,0,1]
	v_pk_fma_f32 v[144:145], v[144:145], v[174:175], v[76:77] op_sel_hi:[1,0,1]
	v_pk_fma_f32 v[176:177], v[134:135], v[174:175], v[78:79] op_sel_hi:[1,0,1]
	v_pk_fma_f32 v[134:135], v[132:133], v[174:175], v[72:73] op_sel_hi:[1,0,1]
	v_pk_fma_f32 v[132:133], v[130:131], v[174:175], v[70:71] op_sel_hi:[1,0,1]
	v_mul_f32_e32 v130, 0xbfb8aa3b, v142
	v_mul_f32_e32 v131, 0xbfb8aa3b, v143
	v_exp_f32_e32 v130, v130
	v_exp_f32_e32 v131, v131
	v_pk_fma_f32 v[136:137], v[136:137], v[174:175], v[80:81] op_sel_hi:[1,0,1]
	v_pk_fma_f32 v[140:141], v[140:141], v[174:175], v[68:69] op_sel_hi:[1,0,1]
	v_add_f32_e32 v130, 1.0, v130
	v_add_f32_e32 v131, 1.0, v131
	v_rcp_f32_e32 v130, v130
	v_rcp_f32_e32 v131, v131
	v_pk_fma_f32 v[126:127], v[126:127], v[172:173], v[74:75] op_sel_hi:[1,0,1]
	v_pk_fma_f32 v[118:119], v[118:119], v[172:173], v[78:79] op_sel_hi:[1,0,1]
	v_mul_f32_e32 v130, v142, v130
	v_mul_f32_e32 v131, v143, v131
	v_mul_f32_e32 v130, v176, v130
	v_mul_f32_e32 v131, v177, v131
	s_nop 0
	v_cvt_pk_bf16_f32 v130, v130, v131
	v_mul_f32_e32 v131, 0xbfb8aa3b, v144
	v_exp_f32_e32 v131, v131
	v_pk_fma_f32 v[128:129], v[128:129], v[172:173], v[76:77] op_sel_hi:[1,0,1]
	v_pk_fma_f32 v[120:121], v[120:121], v[172:173], v[80:81] op_sel_hi:[1,0,1]
	v_pk_fma_f32 v[122:123], v[122:123], v[172:173], v[66:67] op_sel_hi:[1,0,1]
	v_add_f32_e32 v131, 1.0, v131
	v_rcp_f32_e32 v131, v131
	v_pk_fma_f32 v[124:125], v[124:125], v[172:173], v[68:69] op_sel_hi:[1,0,1]
	v_pk_fma_f32 v[110:111], v[110:111], v[168:169], v[74:75] op_sel_hi:[1,0,1]
	v_pk_fma_f32 v[102:103], v[102:103], v[168:169], v[78:79] op_sel_hi:[1,0,1]
	v_mul_f32_e32 v131, v144, v131
	v_mul_f32_e32 v131, v136, v131
	v_mul_f32_e32 v136, 0xbfb8aa3b, v145
	v_exp_f32_e32 v136, v136
	v_pk_fma_f32 v[112:113], v[112:113], v[168:169], v[76:77] op_sel_hi:[1,0,1]
	v_pk_fma_f32 v[104:105], v[104:105], v[168:169], v[80:81] op_sel_hi:[1,0,1]
	v_pk_fma_f32 v[106:107], v[106:107], v[168:169], v[66:67] op_sel_hi:[1,0,1]
	v_add_f32_e32 v136, 1.0, v136
	v_rcp_f32_e32 v136, v136
	v_pk_fma_f32 v[108:109], v[108:109], v[168:169], v[68:69] op_sel_hi:[1,0,1]
	v_pk_fma_f32 v[94:95], v[94:95], v[166:167], v[74:75] op_sel_hi:[1,0,1]
	v_pk_fma_f32 v[86:87], v[86:87], v[166:167], v[78:79] op_sel_hi:[1,0,1]
	v_mul_f32_e32 v136, v145, v136
	v_mul_f32_e32 v136, v137, v136
	s_nop 0
	v_cvt_pk_bf16_f32 v131, v131, v136
	v_mul_f32_e32 v136, 0xbfb8aa3b, v138
	v_exp_f32_e32 v136, v136
	v_pk_fma_f32 v[96:97], v[96:97], v[166:167], v[76:77] op_sel_hi:[1,0,1]
	v_pk_fma_f32 v[88:89], v[88:89], v[166:167], v[80:81] op_sel_hi:[1,0,1]
	v_pk_fma_f32 v[90:91], v[90:91], v[166:167], v[66:67] op_sel_hi:[1,0,1]
	v_add_f32_e32 v136, 1.0, v136
	v_rcp_f32_e32 v136, v136
	v_pk_fma_f32 v[92:93], v[92:93], v[166:167], v[68:69] op_sel_hi:[1,0,1]
	v_pk_fma_f32 v[62:63], v[62:63], v[164:165], v[74:75] op_sel_hi:[1,0,1]
	v_pk_fma_f32 v[54:55], v[54:55], v[164:165], v[78:79] op_sel_hi:[1,0,1]
	v_mul_f32_e32 v136, v138, v136
	v_mul_f32_e32 v132, v132, v136
	v_mul_f32_e32 v136, 0xbfb8aa3b, v139
	v_exp_f32_e32 v136, v136
	v_pk_fma_f32 v[64:65], v[64:65], v[164:165], v[76:77] op_sel_hi:[1,0,1]
	v_pk_fma_f32 v[56:57], v[56:57], v[164:165], v[80:81] op_sel_hi:[1,0,1]
	v_pk_fma_f32 v[58:59], v[58:59], v[164:165], v[66:67] op_sel_hi:[1,0,1]
	v_add_f32_e32 v136, 1.0, v136
	v_rcp_f32_e32 v136, v136
	v_pk_fma_f32 v[60:61], v[60:61], v[164:165], v[68:69] op_sel_hi:[1,0,1]
	v_pk_fma_f32 v[46:47], v[46:47], v[162:163], v[74:75] op_sel_hi:[1,0,1]
	v_pk_fma_f32 v[38:39], v[38:39], v[162:163], v[78:79] op_sel_hi:[1,0,1]
	v_mul_f32_e32 v136, v139, v136
	v_mul_f32_e32 v133, v133, v136
	s_nop 0
	v_cvt_pk_bf16_f32 v132, v132, v133
	v_mul_f32_e32 v133, 0xbfb8aa3b, v140
	v_exp_f32_e32 v133, v133
	v_lshlrev_b64 v[136:137], 1, v[170:171]
	v_pk_fma_f32 v[48:49], v[48:49], v[162:163], v[76:77] op_sel_hi:[1,0,1]
	v_pk_fma_f32 v[40:41], v[40:41], v[162:163], v[80:81] op_sel_hi:[1,0,1]
	v_add_f32_e32 v133, 1.0, v133
	v_rcp_f32_e32 v133, v133
	v_pk_fma_f32 v[42:43], v[42:43], v[162:163], v[66:67] op_sel_hi:[1,0,1]
	v_pk_fma_f32 v[44:45], v[44:45], v[162:163], v[68:69] op_sel_hi:[1,0,1]
	v_pk_fma_f32 v[30:31], v[30:31], v[160:161], v[74:75] op_sel_hi:[1,0,1]
	v_mul_f32_e32 v133, v140, v133
	v_mul_f32_e32 v133, v134, v133
	v_mul_f32_e32 v134, 0xbfb8aa3b, v141
	v_exp_f32_e32 v134, v134
	v_pk_fma_f32 v[22:23], v[22:23], v[160:161], v[78:79] op_sel_hi:[1,0,1]
	v_pk_fma_f32 v[32:33], v[32:33], v[160:161], v[76:77] op_sel_hi:[1,0,1]
	v_pk_fma_f32 v[24:25], v[24:25], v[160:161], v[80:81] op_sel_hi:[1,0,1]
	v_add_f32_e32 v134, 1.0, v134
	v_rcp_f32_e32 v134, v134
	v_pk_fma_f32 v[26:27], v[26:27], v[160:161], v[66:67] op_sel_hi:[1,0,1]
	v_pk_fma_f32 v[28:29], v[28:29], v[160:161], v[68:69] op_sel_hi:[1,0,1]
	v_pk_fma_f32 v[14:15], v[14:15], v[158:159], v[74:75] op_sel_hi:[1,0,1]
	v_mul_f32_e32 v134, v141, v134
	v_mul_f32_e32 v134, v135, v134
	s_nop 0
	v_cvt_pk_bf16_f32 v133, v133, v134
	v_mov_b64_e32 v[134:135], s[6:7]
	v_mad_i64_i32 v[138:139], s[18:19], v156, s74, v[134:135]
	v_lshl_add_u64 v[138:139], v[138:139], 0, v[136:137]
	global_store_dwordx4 v[138:139], v[130:133], off
	v_pk_fma_f32 v[6:7], v[6:7], v[158:159], v[78:79] op_sel_hi:[1,0,1]
	v_pk_fma_f32 v[16:17], v[16:17], v[158:159], v[76:77] op_sel_hi:[1,0,1]
	v_pk_fma_f32 v[130:131], v[116:117], v[172:173], v[72:73] op_sel_hi:[1,0,1]
	v_pk_fma_f32 v[116:117], v[114:115], v[172:173], v[70:71] op_sel_hi:[1,0,1]
	v_mul_f32_e32 v114, 0xbfb8aa3b, v126
	v_mul_f32_e32 v115, 0xbfb8aa3b, v127
; __device__ __forceinline__ unsigned cvt_pk_bf16(float lo, float hi) { unsigned r; asm volatile("s_nop 0\n\tv_cvt_pk_bf16_f32 %0, %1, %2" : "=v"(r) : "v"(lo), "v"(hi)); return r; }
; __device__ __forceinline__ float siluf_(float x) { return x * __builtin_amdgcn_rcpf(1.f + __expf(-x)); }
;     __device__ __forceinline__ void operator()(const f32x4 (&acc)[2][2][4][2], const Unit& u, int wr, int wc, int fr, int fq) const {
;     ...
;             for (int m = 0; m < 4; ++m) { const int r = row0 + ai * 128 + m * 16;
;                 const float rstd = ai ? rb[m] : ra[m];
;                 const f32x4 g0 = acc[ai][0][m][0] * rstd + sg0, g1 = acc[ai][0][m][1] * rstd + sg1, u0 = acc[ai][1][m][0] * rstd + su0, u1 = acc[ai][1][m][1] * rstd + su1;
;                 uint4 st; st.x = cvt_pk_bf16(siluf_(g0[0]) * u0[0], siluf_(g0[1]) * u0[1]); st.y = cvt_pk_bf16(siluf_(g0[2]) * u0[2], siluf_(g0[3]) * u0[3]);
;                 st.z = cvt_pk_bf16(siluf_(g1[0]) * u1[0], siluf_(g1[1]) * u1[1]); st.w = cvt_pk_bf16(siluf_(g1[2]) * u1[2], siluf_(g1[3]) * u1[3]);
;                 *(uint4*)(hid + (size_t)r * DFF + hc0) = st; }
	v_exp_f32_e32 v114, v114
	v_exp_f32_e32 v115, v115
	v_or_b32_e32 v132, 16, v156
	v_pk_fma_f32 v[8:9], v[8:9], v[158:159], v[80:81] op_sel_hi:[1,0,1]
	v_add_f32_e32 v114, 1.0, v114
	v_add_f32_e32 v115, 1.0, v115
	v_rcp_f32_e32 v114, v114
	v_rcp_f32_e32 v115, v115
	v_pk_fma_f32 v[10:11], v[10:11], v[158:159], v[66:67] op_sel_hi:[1,0,1]
	v_pk_fma_f32 v[12:13], v[12:13], v[158:159], v[68:69] op_sel_hi:[1,0,1]
	v_mul_f32_e32 v114, v126, v114
	v_mul_f32_e32 v115, v127, v115
	v_mul_f32_e32 v114, v118, v114
	v_mul_f32_e32 v115, v119, v115
	s_nop 0
	v_cvt_pk_bf16_f32 v114, v114, v115
	v_mul_f32_e32 v115, 0xbfb8aa3b, v128
	v_mul_f32_e32 v118, 0xbfb8aa3b, v129
	v_exp_f32_e32 v115, v115
	v_exp_f32_e32 v118, v118
	v_add_f32_e32 v115, 1.0, v115
	v_add_f32_e32 v118, 1.0, v118
	v_rcp_f32_e32 v115, v115
	v_rcp_f32_e32 v118, v118
	v_mul_f32_e32 v115, v128, v115
	v_mul_f32_e32 v118, v129, v118
	v_mul_f32_e32 v115, v120, v115
	v_mul_f32_e32 v118, v121, v118
	s_nop 0
	v_cvt_pk_bf16_f32 v115, v115, v118
	v_mul_f32_e32 v118, 0xbfb8aa3b, v122
	v_exp_f32_e32 v118, v118
	s_nop 0
	v_add_f32_e32 v118, 1.0, v118
	v_rcp_f32_e32 v118, v118
	s_nop 0
	v_mul_f32_e32 v118, v122, v118
	v_mul_f32_e32 v116, v116, v118
	v_mul_f32_e32 v118, 0xbfb8aa3b, v123
	v_exp_f32_e32 v118, v118
	s_nop 0
	v_add_f32_e32 v118, 1.0, v118
	v_rcp_f32_e32 v118, v118
	s_nop 0
	v_mul_f32_e32 v118, v123, v118
	v_mul_f32_e32 v117, v117, v118
	s_nop 0
	v_cvt_pk_bf16_f32 v116, v116, v117
	v_mul_f32_e32 v117, 0xbfb8aa3b, v124
	v_mul_f32_e32 v118, 0xbfb8aa3b, v125
	v_exp_f32_e32 v117, v117
	v_exp_f32_e32 v118, v118
	v_add_f32_e32 v117, 1.0, v117
	v_add_f32_e32 v118, 1.0, v118
	v_rcp_f32_e32 v117, v117
	v_rcp_f32_e32 v118, v118
	v_mul_f32_e32 v117, v124, v117
	v_mul_f32_e32 v118, v125, v118
	v_mul_f32_e32 v117, v130, v117
	v_mul_f32_e32 v118, v131, v118
	s_nop 0
	v_cvt_pk_bf16_f32 v117, v117, v118
	v_mad_i64_i32 v[118:119], s[18:19], v132, s74, v[134:135]
	v_lshl_add_u64 v[118:119], v[118:119], 0, v[136:137]
	global_store_dwordx4 v[118:119], v[114:117], off
	s_nop 1
	v_pk_fma_f32 v[114:115], v[100:101], v[168:169], v[72:73] op_sel_hi:[1,0,1]
	v_pk_fma_f32 v[100:101], v[98:99], v[168:169], v[70:71] op_sel_hi:[1,0,1]
	v_mul_f32_e32 v98, 0xbfb8aa3b, v110
	v_mul_f32_e32 v99, 0xbfb8aa3b, v111
	v_exp_f32_e32 v98, v98
	v_exp_f32_e32 v99, v99
	v_or_b32_e32 v116, 32, v156
	v_add_f32_e32 v98, 1.0, v98
	v_add_f32_e32 v99, 1.0, v99
	v_rcp_f32_e32 v98, v98
	v_rcp_f32_e32 v99, v99
	v_mul_f32_e32 v98, v110, v98
	v_mul_f32_e32 v99, v111, v99
	v_mul_f32_e32 v98, v102, v98
	v_mul_f32_e32 v99, v103, v99
	s_nop 0
	v_cvt_pk_bf16_f32 v98, v98, v99
	v_mul_f32_e32 v99, 0xbfb8aa3b, v112
	v_mul_f32_e32 v102, 0xbfb8aa3b, v113
	v_exp_f32_e32 v99, v99
	v_exp_f32_e32 v102, v102
	v_add_f32_e32 v99, 1.0, v99
	v_add_f32_e32 v102, 1.0, v102
	v_rcp_f32_e32 v99, v99
	v_rcp_f32_e32 v102, v102
	v_mul_f32_e32 v99, v112, v99
	v_mul_f32_e32 v102, v113, v102
	v_mul_f32_e32 v99, v104, v99
	v_mul_f32_e32 v102, v105, v102
	s_nop 0
	v_cvt_pk_bf16_f32 v99, v99, v102
	v_mul_f32_e32 v102, 0xbfb8aa3b, v106
	v_exp_f32_e32 v102, v102
	s_nop 0
	v_add_f32_e32 v102, 1.0, v102
	v_rcp_f32_e32 v102, v102
	s_nop 0
	v_mul_f32_e32 v102, v106, v102
	v_mul_f32_e32 v100, v100, v102
	v_mul_f32_e32 v102, 0xbfb8aa3b, v107
	v_exp_f32_e32 v102, v102
	s_nop 0
	v_add_f32_e32 v102, 1.0, v102
	v_rcp_f32_e32 v102, v102
	s_nop 0
	v_mul_f32_e32 v102, v107, v102
	v_mul_f32_e32 v101, v101, v102
	s_nop 0
	v_cvt_pk_bf16_f32 v100, v100, v101
	v_mul_f32_e32 v101, 0xbfb8aa3b, v108
	v_mul_f32_e32 v102, 0xbfb8aa3b, v109
	v_exp_f32_e32 v101, v101
	v_exp_f32_e32 v102, v102
	v_add_f32_e32 v101, 1.0, v101
	v_add_f32_e32 v102, 1.0, v102
	v_rcp_f32_e32 v101, v101
	v_rcp_f32_e32 v102, v102
	v_mul_f32_e32 v101, v108, v101
	v_mul_f32_e32 v102, v109, v102
	v_mul_f32_e32 v101, v114, v101
	v_mul_f32_e32 v102, v115, v102
	s_nop 0
	v_cvt_pk_bf16_f32 v101, v101, v102
	v_mad_i64_i32 v[102:103], s[18:19], v116, s74, v[134:135]
	v_lshl_add_u64 v[102:103], v[102:103], 0, v[136:137]
	global_store_dwordx4 v[102:103], v[98:101], off
	s_nop 1
	v_pk_fma_f32 v[98:99], v[84:85], v[166:167], v[72:73] op_sel_hi:[1,0,1]
	v_pk_fma_f32 v[84:85], v[82:83], v[166:167], v[70:71] op_sel_hi:[1,0,1]
	v_mul_f32_e32 v82, 0xbfb8aa3b, v94
	v_mul_f32_e32 v83, 0xbfb8aa3b, v95
	v_exp_f32_e32 v82, v82
	v_exp_f32_e32 v83, v83
	v_or_b32_e32 v100, 48, v156
	v_add_f32_e32 v82, 1.0, v82
	v_add_f32_e32 v83, 1.0, v83
	v_rcp_f32_e32 v82, v82
	v_rcp_f32_e32 v83, v83
	v_mul_f32_e32 v82, v94, v82
	v_mul_f32_e32 v83, v95, v83
	v_mul_f32_e32 v82, v86, v82
	v_mul_f32_e32 v83, v87, v83
	s_nop 0
	v_cvt_pk_bf16_f32 v82, v82, v83
	v_mul_f32_e32 v83, 0xbfb8aa3b, v96
	v_mul_f32_e32 v86, 0xbfb8aa3b, v97
	v_exp_f32_e32 v83, v83
	v_exp_f32_e32 v86, v86
	v_add_f32_e32 v83, 1.0, v83
	v_add_f32_e32 v86, 1.0, v86
	v_rcp_f32_e32 v83, v83
	v_rcp_f32_e32 v86, v86
	v_mul_f32_e32 v83, v96, v83
	v_mul_f32_e32 v86, v97, v86
	v_mul_f32_e32 v83, v88, v83
	v_mul_f32_e32 v86, v89, v86
	s_nop 0
	v_cvt_pk_bf16_f32 v83, v83, v86
	v_mul_f32_e32 v86, 0xbfb8aa3b, v90
	v_exp_f32_e32 v86, v86
	s_nop 0
	v_add_f32_e32 v86, 1.0, v86
	v_rcp_f32_e32 v86, v86
	s_nop 0
	v_mul_f32_e32 v86, v90, v86
	v_mul_f32_e32 v84, v84, v86
	v_mul_f32_e32 v86, 0xbfb8aa3b, v91
	v_exp_f32_e32 v86, v86
	s_nop 0
	v_add_f32_e32 v86, 1.0, v86
	v_rcp_f32_e32 v86, v86
	s_nop 0
	v_mul_f32_e32 v86, v91, v86
	v_mul_f32_e32 v85, v85, v86
	s_nop 0
	v_cvt_pk_bf16_f32 v84, v84, v85
	v_mul_f32_e32 v85, 0xbfb8aa3b, v92
	v_mul_f32_e32 v86, 0xbfb8aa3b, v93
	v_exp_f32_e32 v85, v85
	v_exp_f32_e32 v86, v86
	v_add_f32_e32 v85, 1.0, v85
	v_add_f32_e32 v86, 1.0, v86
	v_rcp_f32_e32 v85, v85
	v_rcp_f32_e32 v86, v86
; __device__ __forceinline__ unsigned cvt_pk_bf16(float lo, float hi) { unsigned r; asm volatile("s_nop 0\n\tv_cvt_pk_bf16_f32 %0, %1, %2" : "=v"(r) : "v"(lo), "v"(hi)); return r; }
; __device__ __forceinline__ float siluf_(float x) { return x * __builtin_amdgcn_rcpf(1.f + __expf(-x)); }
;     __device__ __forceinline__ void operator()(const f32x4 (&acc)[2][2][4][2], const Unit& u, int wr, int wc, int fr, int fq) const {
;     ...
;             for (int m = 0; m < 4; ++m) { const int r = row0 + ai * 128 + m * 16;
;                 const float rstd = ai ? rb[m] : ra[m];
;                 const f32x4 g0 = acc[ai][0][m][0] * rstd + sg0, g1 = acc[ai][0][m][1] * rstd + sg1, u0 = acc[ai][1][m][0] * rstd + su0, u1 = acc[ai][1][m][1] * rstd + su1;
;                 uint4 st; st.x = cvt_pk_bf16(siluf_(g0[0]) * u0[0], siluf_(g0[1]) * u0[1]); st.y = cvt_pk_bf16(siluf_(g0[2]) * u0[2], siluf_(g0[3]) * u0[3]);
;                 st.z = cvt_pk_bf16(siluf_(g1[0]) * u1[0], siluf_(g1[1]) * u1[1]); st.w = cvt_pk_bf16(siluf_(g1[2]) * u1[2], siluf_(g1[3]) * u1[3]);
;                 *(uint4*)(hid + (size_t)r * DFF + hc0) = st; }
	v_mul_f32_e32 v85, v92, v85
	v_mul_f32_e32 v86, v93, v86
	v_mul_f32_e32 v85, v98, v85
	v_mul_f32_e32 v86, v99, v86
	s_nop 0
	v_cvt_pk_bf16_f32 v85, v85, v86
	v_mad_i64_i32 v[86:87], s[18:19], v100, s74, v[134:135]
	v_lshl_add_u64 v[86:87], v[86:87], 0, v[136:137]
	global_store_dwordx4 v[86:87], v[82:85], off
	s_nop 1
	v_pk_fma_f32 v[82:83], v[52:53], v[164:165], v[72:73] op_sel_hi:[1,0,1]
	v_pk_fma_f32 v[52:53], v[50:51], v[164:165], v[70:71] op_sel_hi:[1,0,1]
	v_mul_f32_e32 v50, 0xbfb8aa3b, v62
	v_mul_f32_e32 v51, 0xbfb8aa3b, v63
	v_exp_f32_e32 v50, v50
	v_exp_f32_e32 v51, v51
	v_add_u32_e32 v84, 0x80, v156
	v_add_f32_e32 v50, 1.0, v50
	v_add_f32_e32 v51, 1.0, v51
	v_rcp_f32_e32 v50, v50
	v_rcp_f32_e32 v51, v51
	v_mul_f32_e32 v50, v62, v50
	v_mul_f32_e32 v51, v63, v51
	v_mul_f32_e32 v50, v54, v50
	v_mul_f32_e32 v51, v55, v51
	s_nop 0
	v_cvt_pk_bf16_f32 v50, v50, v51
	v_mul_f32_e32 v51, 0xbfb8aa3b, v64
	v_mul_f32_e32 v54, 0xbfb8aa3b, v65
	v_exp_f32_e32 v51, v51
	v_exp_f32_e32 v54, v54
	v_add_f32_e32 v51, 1.0, v51
	v_add_f32_e32 v54, 1.0, v54
	v_rcp_f32_e32 v51, v51
	v_rcp_f32_e32 v54, v54
	v_mul_f32_e32 v51, v64, v51
	v_mul_f32_e32 v54, v65, v54
	v_mul_f32_e32 v51, v56, v51
	v_mul_f32_e32 v54, v57, v54
	s_nop 0
	v_cvt_pk_bf16_f32 v51, v51, v54
	v_mul_f32_e32 v54, 0xbfb8aa3b, v58
	v_exp_f32_e32 v54, v54
	s_nop 0
	v_add_f32_e32 v54, 1.0, v54
	v_rcp_f32_e32 v54, v54
	s_nop 0
	v_mul_f32_e32 v54, v58, v54
	v_mul_f32_e32 v52, v52, v54
	v_mul_f32_e32 v54, 0xbfb8aa3b, v59
	v_exp_f32_e32 v54, v54
	s_nop 0
	v_add_f32_e32 v54, 1.0, v54
	v_rcp_f32_e32 v54, v54
	s_nop 0
	v_mul_f32_e32 v54, v59, v54
	v_mul_f32_e32 v53, v53, v54
	s_nop 0
	v_cvt_pk_bf16_f32 v52, v52, v53
	v_mul_f32_e32 v53, 0xbfb8aa3b, v60
	v_mul_f32_e32 v54, 0xbfb8aa3b, v61
	v_exp_f32_e32 v53, v53
	v_exp_f32_e32 v54, v54
	v_add_f32_e32 v53, 1.0, v53
	v_add_f32_e32 v54, 1.0, v54
	v_rcp_f32_e32 v53, v53
	v_rcp_f32_e32 v54, v54
	v_mul_f32_e32 v53, v60, v53
	v_mul_f32_e32 v54, v61, v54
	v_mul_f32_e32 v53, v82, v53
	v_mul_f32_e32 v54, v83, v54
	s_nop 0
	v_cvt_pk_bf16_f32 v53, v53, v54
	v_mad_i64_i32 v[54:55], s[18:19], v84, s74, v[134:135]
	v_lshl_add_u64 v[54:55], v[54:55], 0, v[136:137]
	global_store_dwordx4 v[54:55], v[50:53], off
	s_nop 1
	v_pk_fma_f32 v[50:51], v[36:37], v[162:163], v[72:73] op_sel_hi:[1,0,1]
	v_pk_fma_f32 v[36:37], v[34:35], v[162:163], v[70:71] op_sel_hi:[1,0,1]
	v_mul_f32_e32 v34, 0xbfb8aa3b, v46
	v_mul_f32_e32 v35, 0xbfb8aa3b, v47
	v_exp_f32_e32 v34, v34
	v_exp_f32_e32 v35, v35
	v_add_u32_e32 v52, 0x90, v156
	v_add_f32_e32 v34, 1.0, v34
	v_add_f32_e32 v35, 1.0, v35
	v_rcp_f32_e32 v34, v34
	v_rcp_f32_e32 v35, v35
	v_mul_f32_e32 v34, v46, v34
	v_mul_f32_e32 v35, v47, v35
	v_mul_f32_e32 v34, v38, v34
	v_mul_f32_e32 v35, v39, v35
	s_nop 0
	v_cvt_pk_bf16_f32 v34, v34, v35
	v_mul_f32_e32 v35, 0xbfb8aa3b, v48
	v_mul_f32_e32 v38, 0xbfb8aa3b, v49
	v_exp_f32_e32 v35, v35
	v_exp_f32_e32 v38, v38
	v_add_f32_e32 v35, 1.0, v35
	v_add_f32_e32 v38, 1.0, v38
	v_rcp_f32_e32 v35, v35
	v_rcp_f32_e32 v38, v38
	v_mul_f32_e32 v35, v48, v35
	v_mul_f32_e32 v38, v49, v38
	v_mul_f32_e32 v35, v40, v35
	v_mul_f32_e32 v38, v41, v38
	s_nop 0
	v_cvt_pk_bf16_f32 v35, v35, v38
	v_mul_f32_e32 v38, 0xbfb8aa3b, v42
	v_exp_f32_e32 v38, v38
	s_nop 0
	v_add_f32_e32 v38, 1.0, v38
	v_rcp_f32_e32 v38, v38
	s_nop 0
	v_mul_f32_e32 v38, v42, v38
	v_mul_f32_e32 v36, v36, v38
	v_mul_f32_e32 v38, 0xbfb8aa3b, v43
	v_exp_f32_e32 v38, v38
	s_nop 0
	v_add_f32_e32 v38, 1.0, v38
	v_rcp_f32_e32 v38, v38
	s_nop 0
	v_mul_f32_e32 v38, v43, v38
	v_mul_f32_e32 v37, v37, v38
	s_nop 0
	v_cvt_pk_bf16_f32 v36, v36, v37
	v_mul_f32_e32 v37, 0xbfb8aa3b, v44
	v_mul_f32_e32 v38, 0xbfb8aa3b, v45
	v_exp_f32_e32 v37, v37
	v_exp_f32_e32 v38, v38
	v_add_f32_e32 v37, 1.0, v37
	v_add_f32_e32 v38, 1.0, v38
	v_rcp_f32_e32 v37, v37
	v_rcp_f32_e32 v38, v38
	v_mul_f32_e32 v37, v44, v37
	v_mul_f32_e32 v38, v45, v38
	v_mul_f32_e32 v37, v50, v37
	v_mul_f32_e32 v38, v51, v38
	s_nop 0
	v_cvt_pk_bf16_f32 v37, v37, v38
; __device__ __forceinline__ unsigned cvt_pk_bf16(float lo, float hi) { unsigned r; asm volatile("s_nop 0\n\tv_cvt_pk_bf16_f32 %0, %1, %2" : "=v"(r) : "v"(lo), "v"(hi)); return r; }
; __device__ __forceinline__ float siluf_(float x) { return x * __builtin_amdgcn_rcpf(1.f + __expf(-x)); }
;     __device__ __forceinline__ void operator()(const f32x4 (&acc)[2][2][4][2], const Unit& u, int wr, int wc, int fr, int fq) const {
;     ...
;             for (int m = 0; m < 4; ++m) { const int r = row0 + ai * 128 + m * 16;
;                 const float rstd = ai ? rb[m] : ra[m];
;                 const f32x4 g0 = acc[ai][0][m][0] * rstd + sg0, g1 = acc[ai][0][m][1] * rstd + sg1, u0 = acc[ai][1][m][0] * rstd + su0, u1 = acc[ai][1][m][1] * rstd + su1;
;                 uint4 st; st.x = cvt_pk_bf16(siluf_(g0[0]) * u0[0], siluf_(g0[1]) * u0[1]); st.y = cvt_pk_bf16(siluf_(g0[2]) * u0[2], siluf_(g0[3]) * u0[3]);
;                 st.z = cvt_pk_bf16(siluf_(g1[0]) * u1[0], siluf_(g1[1]) * u1[1]); st.w = cvt_pk_bf16(siluf_(g1[2]) * u1[2], siluf_(g1[3]) * u1[3]);
;                 *(uint4*)(hid + (size_t)r * DFF + hc0) = st; }
	v_mad_i64_i32 v[38:39], s[18:19], v52, s74, v[134:135]
	v_lshl_add_u64 v[38:39], v[38:39], 0, v[136:137]
	global_store_dwordx4 v[38:39], v[34:37], off
	s_nop 1
	v_pk_fma_f32 v[34:35], v[20:21], v[160:161], v[72:73] op_sel_hi:[1,0,1]
	v_pk_fma_f32 v[20:21], v[18:19], v[160:161], v[70:71] op_sel_hi:[1,0,1]
	v_mul_f32_e32 v18, 0xbfb8aa3b, v30
	v_mul_f32_e32 v19, 0xbfb8aa3b, v31
	v_exp_f32_e32 v18, v18
	v_exp_f32_e32 v19, v19
	v_add_u32_e32 v36, 0xa0, v156
	v_add_f32_e32 v18, 1.0, v18
	v_add_f32_e32 v19, 1.0, v19
	v_rcp_f32_e32 v18, v18
	v_rcp_f32_e32 v19, v19
	v_mul_f32_e32 v18, v30, v18
	v_mul_f32_e32 v19, v31, v19
	v_mul_f32_e32 v18, v22, v18
	v_mul_f32_e32 v19, v23, v19
	s_nop 0
	v_cvt_pk_bf16_f32 v18, v18, v19
	v_mul_f32_e32 v19, 0xbfb8aa3b, v32
	v_mul_f32_e32 v22, 0xbfb8aa3b, v33
	v_exp_f32_e32 v19, v19
	v_exp_f32_e32 v22, v22
	v_add_f32_e32 v19, 1.0, v19
	v_add_f32_e32 v22, 1.0, v22
	v_rcp_f32_e32 v19, v19
	v_rcp_f32_e32 v22, v22
	v_mul_f32_e32 v19, v32, v19
	v_mul_f32_e32 v22, v33, v22
	v_mul_f32_e32 v19, v24, v19
	v_mul_f32_e32 v22, v25, v22
	s_nop 0
	v_cvt_pk_bf16_f32 v19, v19, v22
	v_mul_f32_e32 v22, 0xbfb8aa3b, v26
	v_exp_f32_e32 v22, v22
	s_nop 0
	v_add_f32_e32 v22, 1.0, v22
	v_rcp_f32_e32 v22, v22
	s_nop 0
	v_mul_f32_e32 v22, v26, v22
	v_mul_f32_e32 v20, v20, v22
	v_mul_f32_e32 v22, 0xbfb8aa3b, v27
	v_exp_f32_e32 v22, v22
	s_nop 0
	v_add_f32_e32 v22, 1.0, v22
	v_rcp_f32_e32 v22, v22
	s_nop 0
	v_mul_f32_e32 v22, v27, v22
	v_mul_f32_e32 v21, v21, v22
	s_nop 0
	v_cvt_pk_bf16_f32 v20, v20, v21
	v_mul_f32_e32 v21, 0xbfb8aa3b, v28
	v_mul_f32_e32 v22, 0xbfb8aa3b, v29
	v_exp_f32_e32 v21, v21
	v_exp_f32_e32 v22, v22
	v_add_f32_e32 v21, 1.0, v21
	v_add_f32_e32 v22, 1.0, v22
	v_rcp_f32_e32 v21, v21
	v_rcp_f32_e32 v22, v22
	v_mul_f32_e32 v21, v28, v21
	v_mul_f32_e32 v22, v29, v22
	v_mul_f32_e32 v21, v34, v21
	v_mul_f32_e32 v22, v35, v22
	s_nop 0
	v_cvt_pk_bf16_f32 v21, v21, v22
	v_mad_i64_i32 v[22:23], s[18:19], v36, s74, v[134:135]
	v_lshl_add_u64 v[22:23], v[22:23], 0, v[136:137]
	global_store_dwordx4 v[22:23], v[18:21], off
	s_nop 1
	v_pk_fma_f32 v[18:19], v[2:3], v[158:159], v[72:73] op_sel_hi:[1,0,1]
	v_pk_fma_f32 v[2:3], v[0:1], v[158:159], v[70:71] op_sel_hi:[1,0,1]
	v_mul_f32_e32 v0, 0xbfb8aa3b, v14
	v_mul_f32_e32 v1, 0xbfb8aa3b, v15
	v_exp_f32_e32 v0, v0
	v_exp_f32_e32 v1, v1
	v_add_u32_e32 v20, 0xb0, v156
	v_add_f32_e32 v0, 1.0, v0
	v_add_f32_e32 v1, 1.0, v1
	v_rcp_f32_e32 v0, v0
	v_rcp_f32_e32 v1, v1
	v_mul_f32_e32 v0, v14, v0
	v_mul_f32_e32 v1, v15, v1
	v_mul_f32_e32 v0, v6, v0
	v_mul_f32_e32 v1, v7, v1
	s_nop 0
	v_cvt_pk_bf16_f32 v0, v0, v1
	v_mul_f32_e32 v1, 0xbfb8aa3b, v16
	v_mul_f32_e32 v6, 0xbfb8aa3b, v17
	v_exp_f32_e32 v1, v1
	v_exp_f32_e32 v6, v6
	v_add_f32_e32 v1, 1.0, v1
	v_add_f32_e32 v6, 1.0, v6
	v_rcp_f32_e32 v1, v1
	v_rcp_f32_e32 v6, v6
	v_mul_f32_e32 v1, v16, v1
	v_mul_f32_e32 v6, v17, v6
	v_mul_f32_e32 v1, v8, v1
	v_mul_f32_e32 v6, v9, v6
	s_nop 0
	v_cvt_pk_bf16_f32 v1, v1, v6
	v_mul_f32_e32 v6, 0xbfb8aa3b, v10
	v_exp_f32_e32 v6, v6
	s_nop 0
	v_add_f32_e32 v6, 1.0, v6
	v_rcp_f32_e32 v6, v6
	s_nop 0
	v_mul_f32_e32 v6, v10, v6
	v_mul_f32_e32 v2, v2, v6
	v_mul_f32_e32 v6, 0xbfb8aa3b, v11
	v_exp_f32_e32 v6, v6
	s_nop 0
	v_add_f32_e32 v6, 1.0, v6
	v_rcp_f32_e32 v6, v6
	s_nop 0
	v_mul_f32_e32 v6, v11, v6
	v_mul_f32_e32 v3, v3, v6
	s_nop 0
	v_cvt_pk_bf16_f32 v2, v2, v3
	v_mul_f32_e32 v3, 0xbfb8aa3b, v12
	v_mul_f32_e32 v6, 0xbfb8aa3b, v13
	v_exp_f32_e32 v3, v3
	v_exp_f32_e32 v6, v6
	v_add_f32_e32 v3, 1.0, v3
	v_add_f32_e32 v6, 1.0, v6
	v_rcp_f32_e32 v3, v3
	v_rcp_f32_e32 v6, v6
	v_mul_f32_e32 v3, v12, v3
	v_mul_f32_e32 v6, v13, v6
	v_mul_f32_e32 v3, v18, v3
	v_mul_f32_e32 v6, v19, v6
	s_nop 0
	v_cvt_pk_bf16_f32 v3, v3, v6
	v_mad_i64_i32 v[6:7], s[18:19], v20, s74, v[134:135]
	v_lshl_add_u64 v[6:7], v[6:7], 0, v[136:137]
	s_mov_b64 s[18:19], s[14:15]
	global_store_dwordx4 v[6:7], v[0:3], off
	s_cbranch_vccz .LBB0_2894
	s_waitcnt vmcnt(0)
	s_cmpk_gt_u32 s24, 0xff
	s_cbranch_scc1 .LBB0_2901
	s_barrier

; #define PG8_STAGE(bufoff, gbase, voff) do { _Pragma("unroll") for (int _i = 0; _i < 2; ++_i) \
;         __builtin_amdgcn_global_load_lds((const unsigned*)((const char*)(gbase) + (voff)[_i]), (LAS unsigned*)(lds + (bufoff) + ldsw + _i * 8192), 16, 0, 0); } while (0)
; #define PG8_LDA(dst, b, h) do { _Pragma("unroll") for (int m = 0; m < 4; ++m) _Pragma("unroll") for (int k = 0; k < 2; ++k) dst[m][k] = *(const LAS bf16x8*)(lds + PG8_SA(b, h) + aoff + m * 2048 + k * 1024); } while (0)
; #define PG8_LDB(dst, b, h) do { _Pragma("unroll") for (int n = 0; n < 2; ++n) _Pragma("unroll") for (int k = 0; k < 2; ++k) dst[n][k] = *(const LAS bf16x8*)(lds + PG8_SB(b, h) + boff + n * 2048 + k * 1024); } while (0)
; #define PG8_MMA(ai, bj, At, Bt) do { __builtin_amdgcn_s_setprio(1); _Pragma("unroll") for (int m = 0; m < 4; ++m) _Pragma("unroll") for (int n = 0; n < 2; ++n) _Pragma("unroll") for (int k = 0; k < 2; ++k) \
;         acc[ai][bj][m][n] = __builtin_amdgcn_mfma_f32_16x16x32_bf16(Bt[n][k], At[m][k], acc[ai][bj][m][n], 0, 0, 0); __builtin_amdgcn_s_setprio(0); } while (0)
; #define PG8_WAIT_L(n) asm volatile("s_waitcnt lgkmcnt(" #n ")" ::: "memory")
; #define PG8_BAR __builtin_amdgcn_s_barrier()
; #define PG8_SCHED __builtin_amdgcn_sched_barrier(0)
; template <class Epi>
; __device__ __forceinline__ void gemm_phase(LAS unsigned char* lds, const Gemm g, const StaticOrder& S, const Epi& E) {
;     ...
;         for (int t = 0; t < nt; t += 2) {
;             const bool last = (t == nt - 2);
;             const char* a1 = cA + (size_t)(t + 1) * kstep;
;             const char* a2 = last ? nA : cA + (size_t)(t + 2) * kstep; const char* b2 = last ? nB : cB + (size_t)(t + 2) * kstep;
;             const char* a3 = a2 + kstep; const char* b3 = b2 + kstep;
;             PG8_LDB(B0, 0, 0); PG8_SCHED; PG8_LDA(At, 0, 0); PG8_STAGE(PG8_SA(1, 1), a1 + hstep, voffA);
;             PG8_WAIT_L(8); PG8_BAR; PG8_WAIT_L(0); PG8_MMA(0, 0, At, B0); PG8_BAR; PG8_SCHED;
;             PG8_LDB(B1, 0, 1); PG8_STAGE(PG8_SB(0, 0), b2, voffB);
;             PG8_BAR; PG8_WAIT_L(0); PG8_MMA(0, 1, At, B1); PG8_BAR;
;             PG8_LDA(At, 0, 1); PG8_STAGE(PG8_SA(0, 0), a2, voffA);
;             PG8_BAR; PG8_WAIT_L(0); PG8_MMA(1, 0, At, B0); PG8_BAR; PG8_SCHED;
.LBB0_2974:
	s_add_i32 s64, s26, 2
	s_add_u32 s0, s8, 0x80
	s_addc_u32 s1, s9, 0
	s_add_i32 s65, 0, 0x10000
	v_add_u32_e32 v4, s65, v245
	ds_read_b128 v[132:135], v4
	ds_read_b128 v[136:139], v4 offset:1024
	ds_read_b128 v[140:143], v4 offset:2048
	ds_read_b128 v[144:147], v4 offset:3072
	s_cmp_eq_u32 s57, s26
	s_cselect_b32 s26, s24, s0
	s_cselect_b32 s27, s25, s1
	s_cselect_b32 s29, s11, s63
	s_cselect_b32 s28, s10, s62
	v_lshl_add_u64 v[6:7], s[8:9], 0, v[164:165]
	s_add_i32 m0, s39, 0xc000
	ds_read_b128 v[148:151], v249
	ds_read_b128 v[152:155], v249 offset:1024
	ds_read_b128 v[156:159], v249 offset:2048
	ds_read_b128 v[168:171], v249 offset:3072
	ds_read_b128 v[172:175], v249 offset:4096
	ds_read_b128 v[190:193], v249 offset:5120
	ds_read_b128 v[194:197], v249 offset:6144
	ds_read_b128 v[198:201], v249 offset:7168
	global_load_lds_dwordx4 v[6:7], off
	v_lshl_add_u64 v[6:7], s[8:9], 0, v[166:167]
	s_add_i32 m0, s39, 0xe000
	s_nop 0
	global_load_lds_dwordx4 v[6:7], off
	s_waitcnt lgkmcnt(8)
	s_barrier
	s_waitcnt lgkmcnt(0)
	v_mfma_f32_16x16x32_bf16 v[80:83], v[132:135], v[148:151], v[80:83]
	v_mfma_f32_16x16x32_bf16 v[104:107], v[140:143], v[148:151], v[104:107]
	v_mfma_f32_16x16x32_bf16 v[128:131], v[132:135], v[156:159], v[128:131]
	v_mfma_f32_16x16x32_bf16 v[100:103], v[140:143], v[156:159], v[100:103]
	v_mfma_f32_16x16x32_bf16 v[124:127], v[132:135], v[172:175], v[124:127]
	v_mfma_f32_16x16x32_bf16 v[96:99], v[140:143], v[172:175], v[96:99]
	v_mfma_f32_16x16x32_bf16 v[120:123], v[132:135], v[194:197], v[120:123]
	v_mfma_f32_16x16x32_bf16 v[88:91], v[140:143], v[194:197], v[88:91]
	v_mfma_f32_16x16x32_bf16 v[80:83], v[136:139], v[152:155], v[80:83]
	v_mfma_f32_16x16x32_bf16 v[104:107], v[144:147], v[152:155], v[104:107]
	v_mfma_f32_16x16x32_bf16 v[128:131], v[136:139], v[168:171], v[128:131]
	v_mfma_f32_16x16x32_bf16 v[100:103], v[144:147], v[168:171], v[100:103]
	v_mfma_f32_16x16x32_bf16 v[124:127], v[136:139], v[190:193], v[124:127]
	v_mfma_f32_16x16x32_bf16 v[96:99], v[144:147], v[190:193], v[96:99]
	v_mfma_f32_16x16x32_bf16 v[120:123], v[136:139], v[198:201], v[120:123]
	v_mfma_f32_16x16x32_bf16 v[88:91], v[144:147], v[198:201], v[88:91]
	s_barrier
	s_add_i32 s70, 0, 0x14000
	s_add_i32 s0, s65, s34
	v_add_u32_e32 v4, s70, v245
	v_lshl_add_u64 v[176:177], s[28:29], 0, v[162:163]
	s_mov_b32 m0, s0
	ds_read_b128 v[202:205], v4
	ds_read_b128 v[206:209], v4 offset:1024
	ds_read_b128 v[210:213], v4 offset:2048
	ds_read_b128 v[214:217], v4 offset:3072
	global_load_lds_dwordx4 v[176:177], off
	v_lshl_add_u64 v[186:187], s[28:29], 0, v[160:161]
	s_add_i32 m0, s0, 0x2000
	s_nop 0
	global_load_lds_dwordx4 v[186:187], off
	s_barrier
	s_waitcnt lgkmcnt(0)
	v_mfma_f32_16x16x32_bf16 v[64:67], v[202:205], v[148:151], v[64:67]
	v_mfma_f32_16x16x32_bf16 v[32:35], v[210:213], v[148:151], v[32:35]
	v_mfma_f32_16x16x32_bf16 v[60:63], v[202:205], v[156:159], v[60:63]
	v_mfma_f32_16x16x32_bf16 v[28:31], v[210:213], v[156:159], v[28:31]
	v_mfma_f32_16x16x32_bf16 v[56:59], v[202:205], v[172:175], v[56:59]
	v_mfma_f32_16x16x32_bf16 v[24:27], v[210:213], v[172:175], v[24:27]
	v_mfma_f32_16x16x32_bf16 v[52:55], v[202:205], v[194:197], v[52:55]
	v_mfma_f32_16x16x32_bf16 v[20:23], v[210:213], v[194:197], v[20:23]
	v_mfma_f32_16x16x32_bf16 v[64:67], v[206:209], v[152:155], v[64:67]
	v_mfma_f32_16x16x32_bf16 v[32:35], v[214:217], v[152:155], v[32:35]
	v_mfma_f32_16x16x32_bf16 v[60:63], v[206:209], v[168:171], v[60:63]
	v_mfma_f32_16x16x32_bf16 v[28:31], v[214:217], v[168:171], v[28:31]
	v_mfma_f32_16x16x32_bf16 v[56:59], v[206:209], v[190:193], v[56:59]
	v_mfma_f32_16x16x32_bf16 v[24:27], v[214:217], v[190:193], v[24:27]
	v_mfma_f32_16x16x32_bf16 v[52:55], v[206:209], v[198:201], v[52:55]
	v_mfma_f32_16x16x32_bf16 v[20:23], v[214:217], v[198:201], v[20:23]
	s_mov_b32 m0, s39
	v_lshl_add_u64 v[218:219], s[26:27], 0, v[162:163]
	s_barrier
	ds_read_b128 v[148:151], v249 offset:16384
	ds_read_b128 v[152:155], v249 offset:17408
	ds_read_b128 v[156:159], v249 offset:18432
	ds_read_b128 v[168:171], v249 offset:19456
	ds_read_b128 v[172:175], v249 offset:20480
	ds_read_b128 v[190:193], v249 offset:21504
	ds_read_b128 v[194:197], v249 offset:22528
	ds_read_b128 v[198:201], v249 offset:23552
	global_load_lds_dwordx4 v[218:219], off
	v_lshl_add_u64 v[220:221], s[26:27], 0, v[160:161]
	s_mov_b32 m0, s40
	s_nop 0
	global_load_lds_dwordx4 v[220:221], off
	s_barrier
	s_waitcnt lgkmcnt(0)
	v_mfma_f32_16x16x32_bf16 v[92:95], v[132:135], v[148:151], v[92:95]
	v_mfma_f32_16x16x32_bf16 v[84:87], v[140:143], v[148:151], v[84:87]
	v_mfma_f32_16x16x32_bf16 v[116:119], v[132:135], v[156:159], v[116:119]
	v_mfma_f32_16x16x32_bf16 v[76:79], v[140:143], v[156:159], v[76:79]
	v_mfma_f32_16x16x32_bf16 v[112:115], v[132:135], v[172:175], v[112:115]
	v_mfma_f32_16x16x32_bf16 v[72:75], v[140:143], v[172:175], v[72:75]
	v_mfma_f32_16x16x32_bf16 v[108:111], v[132:135], v[194:197], v[108:111]
	v_mfma_f32_16x16x32_bf16 v[68:71], v[140:143], v[194:197], v[68:71]
	v_mfma_f32_16x16x32_bf16 v[92:95], v[136:139], v[152:155], v[92:95]
	v_mfma_f32_16x16x32_bf16 v[84:87], v[144:147], v[152:155], v[84:87]
	v_mfma_f32_16x16x32_bf16 v[116:119], v[136:139], v[168:171], v[116:119]
	v_mfma_f32_16x16x32_bf16 v[76:79], v[144:147], v[168:171], v[76:79]
	v_mfma_f32_16x16x32_bf16 v[112:115], v[136:139], v[190:193], v[112:115]
	v_mfma_f32_16x16x32_bf16 v[72:75], v[144:147], v[190:193], v[72:75]
	v_mfma_f32_16x16x32_bf16 v[108:111], v[136:139], v[198:201], v[108:111]
	v_mfma_f32_16x16x32_bf16 v[68:71], v[144:147], v[198:201], v[68:71]
	s_barrier
; #define PG8_STAGE(bufoff, gbase, voff) do { _Pragma("unroll") for (int _i = 0; _i < 2; ++_i) \
;         __builtin_amdgcn_global_load_lds((const unsigned*)((const char*)(gbase) + (voff)[_i]), (LAS unsigned*)(lds + (bufoff) + ldsw + _i * 8192), 16, 0, 0); } while (0)
; #define PG8_LDA(dst, b, h) do { _Pragma("unroll") for (int m = 0; m < 4; ++m) _Pragma("unroll") for (int k = 0; k < 2; ++k) dst[m][k] = *(const LAS bf16x8*)(lds + PG8_SA(b, h) + aoff + m * 2048 + k * 1024); } while (0)
; #define PG8_LDB(dst, b, h) do { _Pragma("unroll") for (int n = 0; n < 2; ++n) _Pragma("unroll") for (int k = 0; k < 2; ++k) dst[n][k] = *(const LAS bf16x8*)(lds + PG8_SB(b, h) + boff + n * 2048 + k * 1024); } while (0)
; #define PG8_MMA(ai, bj, At, Bt) do { __builtin_amdgcn_s_setprio(1); _Pragma("unroll") for (int m = 0; m < 4; ++m) _Pragma("unroll") for (int n = 0; n < 2; ++n) _Pragma("unroll") for (int k = 0; k < 2; ++k) \
;         acc[ai][bj][m][n] = __builtin_amdgcn_mfma_f32_16x16x32_bf16(Bt[n][k], At[m][k], acc[ai][bj][m][n], 0, 0, 0); __builtin_amdgcn_s_setprio(0); } while (0)
; #define PG8_WAIT_V(n) asm volatile("s_waitcnt vmcnt(" #n ")" ::: "memory")
; #define PG8_WAIT_L(n) asm volatile("s_waitcnt lgkmcnt(" #n ")" ::: "memory")
; #define PG8_BAR __builtin_amdgcn_s_barrier()
; #define PG8_SCHED __builtin_amdgcn_sched_barrier(0)
; template <class Epi>
; __device__ __forceinline__ void gemm_phase(LAS unsigned char* lds, const Gemm g, const StaticOrder& S, const Epi& E) {
;     ...
;             PG8_BAR; PG8_WAIT_L(0); PG8_MMA(1, 0, At, B0); PG8_BAR; PG8_SCHED;
;             PG8_STAGE(PG8_SB(0, 1), b2 + hstep, voffB);
;             PG8_WAIT_V(6); PG8_BAR; PG8_MMA(1, 1, At, B1); PG8_BAR;
;             PG8_LDB(B0, 1, 0); PG8_SCHED; PG8_LDA(At, 1, 0); PG8_STAGE(PG8_SA(0, 1), a2 + hstep, voffA);
;             PG8_WAIT_L(8); PG8_BAR; PG8_WAIT_L(0); PG8_MMA(0, 0, At, B0); PG8_BAR; PG8_SCHED;
;             PG8_LDB(B1, 1, 1); PG8_STAGE(PG8_SB(1, 0), b3, voffB);
;             PG8_BAR; PG8_WAIT_L(0); PG8_MMA(0, 1, At, B1); PG8_BAR;
;             PG8_LDA(At, 1, 1); PG8_STAGE(PG8_SA(1, 0), a3, voffA);
;             PG8_BAR; PG8_WAIT_L(0); PG8_MMA(1, 0, At, B0); PG8_BAR; PG8_SCHED;
	s_add_u32 s0, s28, s52
	s_addc_u32 s1, s29, 0
	s_add_i32 s28, s70, s34
	v_lshl_add_u64 v[222:223], s[0:1], 0, v[162:163]
	s_mov_b32 m0, s28
	v_lshl_add_u64 v[224:225], s[0:1], 0, v[160:161]
	global_load_lds_dwordx4 v[222:223], off
	s_add_i32 m0, s28, 0x2000
	s_nop 0
	global_load_lds_dwordx4 v[224:225], off
	s_waitcnt vmcnt(6)
	s_barrier
	v_mfma_f32_16x16x32_bf16 v[48:51], v[202:205], v[148:151], v[48:51]
	v_mfma_f32_16x16x32_bf16 v[16:19], v[210:213], v[148:151], v[16:19]
	v_mfma_f32_16x16x32_bf16 v[44:47], v[202:205], v[156:159], v[44:47]
	v_mfma_f32_16x16x32_bf16 v[12:15], v[210:213], v[156:159], v[12:15]
	v_mfma_f32_16x16x32_bf16 v[40:43], v[202:205], v[172:175], v[40:43]
	v_mfma_f32_16x16x32_bf16 v[6:9], v[210:213], v[172:175], v[8:11]
	v_mfma_f32_16x16x32_bf16 v[36:39], v[202:205], v[194:197], v[36:39]
	v_mfma_f32_16x16x32_bf16 v[0:3], v[210:213], v[194:197], v[0:3]
	v_mfma_f32_16x16x32_bf16 v[48:51], v[206:209], v[152:155], v[48:51]
	v_mfma_f32_16x16x32_bf16 v[16:19], v[214:217], v[152:155], v[16:19]
	v_mfma_f32_16x16x32_bf16 v[44:47], v[206:209], v[168:171], v[44:47]
	v_mfma_f32_16x16x32_bf16 v[12:15], v[214:217], v[168:171], v[12:15]
	v_mfma_f32_16x16x32_bf16 v[40:43], v[206:209], v[190:193], v[40:43]
	v_mfma_f32_16x16x32_bf16 v[6:9], v[214:217], v[190:193], v[6:9]
	v_mfma_f32_16x16x32_bf16 v[36:39], v[206:209], v[198:201], v[36:39]
	v_mfma_f32_16x16x32_bf16 v[0:3], v[214:217], v[198:201], v[0:3]
	s_add_i32 s28, 0, 0x18000
	v_add_u32_e32 v4, s28, v245
	s_barrier
	ds_read_b128 v[132:135], v4
	ds_read_b128 v[136:139], v4 offset:1024
	ds_read_b128 v[140:143], v4 offset:2048
	ds_read_b128 v[144:147], v4 offset:3072
	s_add_u32 s0, s26, s52
	s_addc_u32 s1, s27, 0
	s_mov_b32 m0, s41
	v_lshl_add_u64 v[10:11], s[0:1], 0, v[162:163]
	ds_read_b128 v[148:151], v249 offset:32768
	ds_read_b128 v[152:155], v249 offset:33792
	ds_read_b128 v[156:159], v249 offset:34816
	ds_read_b128 v[168:171], v249 offset:35840
	ds_read_b128 v[172:175], v249 offset:36864
	ds_read_b128 v[190:193], v249 offset:37888
	ds_read_b128 v[194:197], v249 offset:38912
	ds_read_b128 v[198:201], v249 offset:39936
	global_load_lds_dwordx4 v[10:11], off
	v_lshl_add_u64 v[10:11], s[0:1], 0, v[160:161]
	s_mov_b32 m0, s42
	s_nop 0
	global_load_lds_dwordx4 v[10:11], off
	s_waitcnt lgkmcnt(8)
	s_barrier
	s_waitcnt lgkmcnt(0)
	v_mfma_f32_16x16x32_bf16 v[80:83], v[132:135], v[148:151], v[80:83]
	v_mfma_f32_16x16x32_bf16 v[104:107], v[140:143], v[148:151], v[104:107]
	v_mfma_f32_16x16x32_bf16 v[128:131], v[132:135], v[156:159], v[128:131]
	v_mfma_f32_16x16x32_bf16 v[100:103], v[140:143], v[156:159], v[100:103]
	v_mfma_f32_16x16x32_bf16 v[124:127], v[132:135], v[172:175], v[124:127]
	v_mfma_f32_16x16x32_bf16 v[96:99], v[140:143], v[172:175], v[96:99]
	v_mfma_f32_16x16x32_bf16 v[120:123], v[132:135], v[194:197], v[120:123]
	v_mfma_f32_16x16x32_bf16 v[88:91], v[140:143], v[194:197], v[88:91]
	v_mfma_f32_16x16x32_bf16 v[80:83], v[136:139], v[152:155], v[80:83]
	v_mfma_f32_16x16x32_bf16 v[104:107], v[144:147], v[152:155], v[104:107]
	v_mfma_f32_16x16x32_bf16 v[128:131], v[136:139], v[168:171], v[128:131]
	v_mfma_f32_16x16x32_bf16 v[100:103], v[144:147], v[168:171], v[100:103]
	v_mfma_f32_16x16x32_bf16 v[124:127], v[136:139], v[190:193], v[124:127]
	v_mfma_f32_16x16x32_bf16 v[96:99], v[144:147], v[190:193], v[96:99]
	v_mfma_f32_16x16x32_bf16 v[120:123], v[136:139], v[198:201], v[120:123]
	v_mfma_f32_16x16x32_bf16 v[88:91], v[144:147], v[198:201], v[88:91]
	s_barrier
	s_add_i32 s0, 0, 0x1c000
	s_add_i32 s1, s28, s34
	v_add_u32_e32 v4, s0, v245
	v_lshl_add_u64 v[10:11], v[176:177], 0, s[86:87]
	s_mov_b32 m0, s1
	ds_read_b128 v[202:205], v4
	ds_read_b128 v[206:209], v4 offset:1024
	ds_read_b128 v[210:213], v4 offset:2048
	ds_read_b128 v[214:217], v4 offset:3072
	global_load_lds_dwordx4 v[10:11], off
	v_lshl_add_u64 v[10:11], v[186:187], 0, s[86:87]
	s_add_i32 m0, s1, 0x2000
	s_nop 0
	global_load_lds_dwordx4 v[10:11], off
	s_barrier
	s_waitcnt lgkmcnt(0)
	v_mfma_f32_16x16x32_bf16 v[64:67], v[202:205], v[148:151], v[64:67]
	v_mfma_f32_16x16x32_bf16 v[32:35], v[210:213], v[148:151], v[32:35]
	v_mfma_f32_16x16x32_bf16 v[60:63], v[202:205], v[156:159], v[60:63]
	v_mfma_f32_16x16x32_bf16 v[28:31], v[210:213], v[156:159], v[28:31]
	v_mfma_f32_16x16x32_bf16 v[56:59], v[202:205], v[172:175], v[56:59]
	v_mfma_f32_16x16x32_bf16 v[24:27], v[210:213], v[172:175], v[24:27]
	v_mfma_f32_16x16x32_bf16 v[52:55], v[202:205], v[194:197], v[52:55]
	v_mfma_f32_16x16x32_bf16 v[20:23], v[210:213], v[194:197], v[20:23]
	v_mfma_f32_16x16x32_bf16 v[64:67], v[206:209], v[152:155], v[64:67]
	v_mfma_f32_16x16x32_bf16 v[32:35], v[214:217], v[152:155], v[32:35]
	v_mfma_f32_16x16x32_bf16 v[60:63], v[206:209], v[168:171], v[60:63]
	v_mfma_f32_16x16x32_bf16 v[28:31], v[214:217], v[168:171], v[28:31]
	v_mfma_f32_16x16x32_bf16 v[56:59], v[206:209], v[190:193], v[56:59]
	v_mfma_f32_16x16x32_bf16 v[24:27], v[214:217], v[190:193], v[24:27]
	v_mfma_f32_16x16x32_bf16 v[52:55], v[206:209], v[198:201], v[52:55]
	v_mfma_f32_16x16x32_bf16 v[20:23], v[214:217], v[198:201], v[20:23]
	s_mov_b32 m0, s55
	v_lshl_add_u64 v[10:11], v[218:219], 0, s[86:87]
	s_barrier
; #define PG8_STAGE(bufoff, gbase, voff) do { _Pragma("unroll") for (int _i = 0; _i < 2; ++_i) \
;         __builtin_amdgcn_global_load_lds((const unsigned*)((const char*)(gbase) + (voff)[_i]), (LAS unsigned*)(lds + (bufoff) + ldsw + _i * 8192), 16, 0, 0); } while (0)
; #define PG8_LDA(dst, b, h) do { _Pragma("unroll") for (int m = 0; m < 4; ++m) _Pragma("unroll") for (int k = 0; k < 2; ++k) dst[m][k] = *(const LAS bf16x8*)(lds + PG8_SA(b, h) + aoff + m * 2048 + k * 1024); } while (0)
; #define PG8_MMA(ai, bj, At, Bt) do { __builtin_amdgcn_s_setprio(1); _Pragma("unroll") for (int m = 0; m < 4; ++m) _Pragma("unroll") for (int n = 0; n < 2; ++n) _Pragma("unroll") for (int k = 0; k < 2; ++k) \
;         acc[ai][bj][m][n] = __builtin_amdgcn_mfma_f32_16x16x32_bf16(Bt[n][k], At[m][k], acc[ai][bj][m][n], 0, 0, 0); __builtin_amdgcn_s_setprio(0); } while (0)
; #define PG8_WAIT_V(n) asm volatile("s_waitcnt vmcnt(" #n ")" ::: "memory")
; template <class Epi>
; __device__ __forceinline__ void gemm_phase(LAS unsigned char* lds, const Gemm g, const StaticOrder& S, const Epi& E) {
;     ...
;             PG8_BAR; PG8_WAIT_L(0); PG8_MMA(0, 1, At, B1); PG8_BAR;
;             PG8_LDA(At, 1, 1); PG8_STAGE(PG8_SA(1, 0), a3, voffA);
;             PG8_BAR; PG8_WAIT_L(0); PG8_MMA(1, 0, At, B0); PG8_BAR; PG8_SCHED;
;             PG8_STAGE(PG8_SB(1, 1), b3 + hstep, voffB);
;             PG8_WAIT_V(6); PG8_BAR; PG8_MMA(1, 1, At, B1); PG8_BAR;
;     __device__ __forceinline__ void operator()(const f32x4 (&acc)[2][2][4][2], const Unit& u, int wr, int wc, int fr, int fq) const {
;         const int row0 = u.pm * 256 + wr * 64 + fr, col0 = u.pn * 256 + wc * 32 + 4 * fq;
;         const float* mvp = mv + (size_t)(u.pm >> 3) * 9216 + col0;
;         const float fac = __builtin_amdgcn_readfirstlane(ffn) ? 0.5f : 1.f;
;         const bool hb = __builtin_amdgcn_readfirstlane(has_next) != 0;
;         f32x4 rs0 = (f32x4){0.f, 0.f, 0.f, 0.f}, rs1 = rs0;
; #pragma unroll
;         for (int bj = 0; bj < 2; ++bj)
; #pragma unroll
;             for (int n = 0; n < 2; ++n) {
;                 const int co = bj * 128 + n * 16;
;                 const f32x4 mvv = *(const f32x4*)(mvp + co) * fac;
;                 f32x4 gn = (f32x4){0.f, 0.f, 0.f, 0.f};
;                 if (hb) gn = *(const f32x4*)(nwn + col0 + co) * (*(const f32x4*)(scn + (size_t)(u.pm >> 3) * 9216 + col0 + co) + 1.f);
	ds_read_b128 v[148:151], v249 offset:49152
	ds_read_b128 v[152:155], v249 offset:50176
	ds_read_b128 v[156:159], v249 offset:51200
	ds_read_b128 v[168:171], v249 offset:52224
	ds_read_b128 v[172:175], v249 offset:53248
	ds_read_b128 v[190:193], v249 offset:54272
	ds_read_b128 v[194:197], v249 offset:55296
	ds_read_b128 v[198:201], v249 offset:56320
	global_load_lds_dwordx4 v[10:11], off
	v_lshl_add_u64 v[10:11], v[220:221], 0, s[86:87]
	s_mov_b32 m0, s56
	s_nop 0
	global_load_lds_dwordx4 v[10:11], off
	s_barrier
	s_waitcnt lgkmcnt(0)
	v_mfma_f32_16x16x32_bf16 v[92:95], v[132:135], v[148:151], v[92:95]
	v_mfma_f32_16x16x32_bf16 v[84:87], v[140:143], v[148:151], v[84:87]
	v_mfma_f32_16x16x32_bf16 v[116:119], v[132:135], v[156:159], v[116:119]
	v_mfma_f32_16x16x32_bf16 v[76:79], v[140:143], v[156:159], v[76:79]
	v_mfma_f32_16x16x32_bf16 v[112:115], v[132:135], v[172:175], v[112:115]
	v_mfma_f32_16x16x32_bf16 v[72:75], v[140:143], v[172:175], v[72:75]
	v_mfma_f32_16x16x32_bf16 v[108:111], v[132:135], v[194:197], v[108:111]
	v_mfma_f32_16x16x32_bf16 v[68:71], v[140:143], v[194:197], v[68:71]
	v_mfma_f32_16x16x32_bf16 v[92:95], v[136:139], v[152:155], v[92:95]
	v_mfma_f32_16x16x32_bf16 v[84:87], v[144:147], v[152:155], v[84:87]
	v_mfma_f32_16x16x32_bf16 v[116:119], v[136:139], v[168:171], v[116:119]
	v_mfma_f32_16x16x32_bf16 v[76:79], v[144:147], v[168:171], v[76:79]
	v_mfma_f32_16x16x32_bf16 v[112:115], v[136:139], v[190:193], v[112:115]
	v_mfma_f32_16x16x32_bf16 v[72:75], v[144:147], v[190:193], v[72:75]
	v_mfma_f32_16x16x32_bf16 v[108:111], v[136:139], v[198:201], v[108:111]
	v_mfma_f32_16x16x32_bf16 v[68:71], v[144:147], v[198:201], v[68:71]
	s_barrier
	s_add_i32 s0, s0, s34
	v_lshl_add_u64 v[10:11], v[222:223], 0, s[86:87]
	s_mov_b32 m0, s0
	s_nop 0
	global_load_lds_dwordx4 v[10:11], off
	v_lshl_add_u64 v[10:11], v[224:225], 0, s[86:87]
	s_add_i32 m0, s0, 0x2000
	s_nop 0
	global_load_lds_dwordx4 v[10:11], off
	s_waitcnt vmcnt(6)
	s_barrier
	v_mfma_f32_16x16x32_bf16 v[48:51], v[202:205], v[148:151], v[48:51]
	v_mfma_f32_16x16x32_bf16 v[16:19], v[210:213], v[148:151], v[16:19]
	v_mfma_f32_16x16x32_bf16 v[44:47], v[202:205], v[156:159], v[44:47]
	v_mfma_f32_16x16x32_bf16 v[10:13], v[210:213], v[156:159], v[12:15]
	v_mfma_f32_16x16x32_bf16 v[40:43], v[202:205], v[172:175], v[40:43]
	v_mfma_f32_16x16x32_bf16 v[6:9], v[210:213], v[172:175], v[6:9]
	v_mfma_f32_16x16x32_bf16 v[36:39], v[202:205], v[194:197], v[36:39]
	v_mfma_f32_16x16x32_bf16 v[0:3], v[210:213], v[194:197], v[0:3]
	v_mfma_f32_16x16x32_bf16 v[48:51], v[206:209], v[152:155], v[48:51]
	v_mfma_f32_16x16x32_bf16 v[16:19], v[214:217], v[152:155], v[16:19]
	v_mfma_f32_16x16x32_bf16 v[44:47], v[206:209], v[168:171], v[44:47]
	v_mfma_f32_16x16x32_bf16 v[12:15], v[214:217], v[168:171], v[10:13]
	v_mfma_f32_16x16x32_bf16 v[40:43], v[206:209], v[190:193], v[40:43]
	v_mfma_f32_16x16x32_bf16 v[8:11], v[214:217], v[190:193], v[6:9]
	v_mfma_f32_16x16x32_bf16 v[36:39], v[206:209], v[198:201], v[36:39]
	v_mfma_f32_16x16x32_bf16 v[0:3], v[214:217], v[198:201], v[0:3]
	s_add_u32 s8, s8, 0x100
	s_addc_u32 s9, s9, 0
	s_add_u32 s62, s62, 0x100
	s_addc_u32 s63, s63, 0
	s_cmp_ge_u32 s64, s49
	s_mov_b32 s26, s64
	s_barrier
	s_cbranch_scc0 .LBB0_2974
	s_ashr_i32 s0, s60, 3
	s_mul_i32 s29, s0, 0x9000
	v_lshl_or_b32 v170, s61, 8, v248
	s_mul_hi_i32 s28, s0, 0x9000
	s_add_u32 s0, s50, s29
	s_addc_u32 s1, s51, s28
	v_ashrrev_i32_e32 v171, 31, v170
	v_lshl_add_u64 v[176:177], v[170:171], 2, s[0:1]
	global_load_dwordx4 v[132:135], v[176:177], off
	v_readfirstlane_b32 s0, v243
	s_cmp_lg_u32 s0, 0
	v_lshlrev_b64 v[168:169], 2, v[170:171]
	v_readfirstlane_b32 s8, v242
	s_cselect_b64 s[26:27], -1, 0
	s_cmp_eq_u32 s0, 0
	v_lshl_add_u64 v[190:191], s[18:19], 0, v[168:169]
	s_cbranch_scc1 .LBB0_2977
	s_add_u32 s0, s43, s29
	s_addc_u32 s1, s48, s28
	v_lshl_add_u64 v[6:7], s[0:1], 0, v[168:169]
	global_load_dwordx4 v[136:139], v[6:7], off
	global_load_dwordx4 v[140:143], v[190:191], off
	s_waitcnt vmcnt(0)
	v_pk_add_f32 v[6:7], v[138:139], 1.0 op_sel_hi:[1,0]
	v_pk_add_f32 v[136:137], v[136:137], 1.0 op_sel_hi:[1,0]
	v_pk_mul_f32 v[218:219], v[142:143], v[6:7]
	v_pk_mul_f32 v[216:217], v[140:141], v[136:137]
	s_branch .LBB0_2978
